# v9 plus GEMM main loops without the no-op mid-MMA setprio pairs and the duplicate post-barrier lgkmcnt wait
# speedup vs baseline: 1.0020x; 1.0009x over previous
; #define PG8_STAGE(bufoff, gbase, voff) do { _Pragma("unroll") for (int _i = 0; _i < 2; ++_i) \
;         __builtin_amdgcn_global_load_lds((const unsigned*)((const char*)(gbase) + (voff)[_i]), (LAS unsigned*)(lds + (bufoff) + ldsw + _i * 8192), 16, 0, 0); } while (0)
; #define PG8_LDA(dst, b, h) do { _Pragma("unroll") for (int m = 0; m < 4; ++m) _Pragma("unroll") for (int k = 0; k < 2; ++k) dst[m][k] = *(const LAS bf16x8*)(lds + PG8_SA(b, h) + aoff + m * 2048 + k * 1024); } while (0)
; #define PG8_LDB(dst, b, h) do { _Pragma("unroll") for (int n = 0; n < 2; ++n) _Pragma("unroll") for (int k = 0; k < 2; ++k) dst[n][k] = *(const LAS bf16x8*)(lds + PG8_SB(b, h) + boff + n * 2048 + k * 1024); } while (0)
; #define PG8_MMA(ai, bj, At, Bt) do { __builtin_amdgcn_s_setprio(1); _Pragma("unroll") for (int m = 0; m < 4; ++m) _Pragma("unroll") for (int n = 0; n < 2; ++n) _Pragma("unroll") for (int k = 0; k < 2; ++k) \
;         acc[ai][bj][m][n] = __builtin_amdgcn_mfma_f32_16x16x32_bf16(Bt[n][k], At[m][k], acc[ai][bj][m][n], 0, 0, 0); __builtin_amdgcn_s_setprio(0); } while (0)
; template <class Epi, class Sched>
; __device__ __forceinline__ void gemm_phase(LAS unsigned char* lds, const Gemm g, const Sched& S, const Epi& E, const int tid) {
;     ...
;         const bool has_next = S.next(ui + 1, nxt);
;         const char* nA = has_next ? (const char*)g.A + (size_t)nxt.pm * tstepA + (size_t)nxt.aoff * 2 : cA; const char* nB = has_next ? (const char*)g.Bt + (size_t)nxt.pn * tstepB : cB;
;         for (int t = 0; t < nt; t += 2) {
;             const bool last = (t == nt - 2);
;             const char* a1 = cA + (size_t)(t + 1) * kstep;
;             const char* a2 = last ? nA : cA + (size_t)(t + 2) * kstep; const char* b2 = last ? nB : cB + (size_t)(t + 2) * kstep;
;             const char* a3 = a2 + kstep; const char* b3 = b2 + kstep;
;             PG8_LDB(B0, 0, 0); PG8_LDB(B1, 0, 1); PG8_SCHED; PG8_LDA(At, 0, 0); PG8_STAGE(PG8_SA(1, 1), a1 + hstepA, voffA);
;             PG8_WAIT_V(8); PG8_WAIT_L(0); PG8_BAR; PG8_MMA(0, 0, At, B0); PG8_MMA(0, 1, At, B1); PG8_BAR; PG8_SCHED;
;             PG8_LDA(At, 0, 1); PG8_STAGE(PG8_SB(0, 0), b2, voffB); PG8_STAGE(PG8_SB(0, 1), b2 + hstepB, voffB); PG8_STAGE(PG8_SA(0, 0), a2, voffA);
;             PG8_WAIT_V(8); PG8_WAIT_L(0); PG8_BAR; PG8_MMA(1, 0, At, B0); PG8_MMA(1, 1, At, B1); PG8_BAR; PG8_SCHED;
.LBB1_36:
	s_add_u32 s42, s56, 0x100
	s_addc_u32 s43, s57, 0
	s_add_i32 s14, 0, 0x10000
	s_cmpk_eq_i32 s71, 0x54
	s_cselect_b32 s61, s49, s43
	s_cselect_b32 s60, s48, s42
	s_cselect_b32 s59, s53, s45
	s_cselect_b32 s58, s52, s44
	s_add_i32 s72, 0, 0x14000
	v_add_u32_e32 v142, s14, v213
	v_add_u32_e32 v158, s72, v213
	ds_read_b128 v[130:133], v142
	ds_read_b128 v[134:137], v142 offset:1024
	ds_read_b128 v[138:141], v142 offset:2048
	ds_read_b128 v[142:145], v142 offset:3072
	ds_read_b128 v[146:149], v158
	ds_read_b128 v[150:153], v158 offset:1024
	ds_read_b128 v[154:157], v158 offset:2048
	ds_read_b128 v[158:161], v158 offset:3072
	v_lshl_add_u64 v[200:201], s[56:57], 0, v[186:187]
	s_add_i32 m0, s47, 0xc000
	ds_read_b128 v[162:165], v218
	ds_read_b128 v[166:169], v218 offset:1024
	ds_read_b128 v[170:173], v218 offset:2048
	ds_read_b128 v[174:177], v218 offset:3072
	ds_read_b128 v[188:191], v218 offset:4096
	ds_read_b128 v[192:195], v218 offset:5120
	ds_read_b128 v[196:199], v218 offset:6144
	ds_read_b128 v[204:207], v218 offset:7168
	global_load_lds_dwordx4 v[200:201], off
	v_lshl_add_u64 v[200:201], s[56:57], 0, v[184:185]
	s_add_i32 m0, s47, 0xe000
	s_nop 0
	global_load_lds_dwordx4 v[200:201], off
	s_waitcnt vmcnt(8)
	s_waitcnt lgkmcnt(0)
	s_barrier
	s_setprio 1
	v_mfma_f32_16x16x32_bf16 v[126:129], v[130:133], v[162:165], v[126:129]
	v_mfma_f32_16x16x32_bf16 v[122:125], v[138:141], v[162:165], v[122:125]
	v_mfma_f32_16x16x32_bf16 v[110:113], v[130:133], v[170:173], v[110:113]
	v_mfma_f32_16x16x32_bf16 v[106:109], v[138:141], v[170:173], v[106:109]
	v_mfma_f32_16x16x32_bf16 v[94:97], v[130:133], v[188:191], v[94:97]
	v_mfma_f32_16x16x32_bf16 v[90:93], v[138:141], v[188:191], v[90:93]
	v_mfma_f32_16x16x32_bf16 v[78:81], v[130:133], v[196:199], v[78:81]
	v_mfma_f32_16x16x32_bf16 v[74:77], v[138:141], v[196:199], v[74:77]
	v_mfma_f32_16x16x32_bf16 v[126:129], v[134:137], v[166:169], v[126:129]
	v_mfma_f32_16x16x32_bf16 v[122:125], v[142:145], v[166:169], v[122:125]
	v_mfma_f32_16x16x32_bf16 v[110:113], v[134:137], v[174:177], v[110:113]
	v_mfma_f32_16x16x32_bf16 v[106:109], v[142:145], v[174:177], v[106:109]
	v_mfma_f32_16x16x32_bf16 v[94:97], v[134:137], v[192:195], v[94:97]
	v_mfma_f32_16x16x32_bf16 v[90:93], v[142:145], v[192:195], v[90:93]
	v_mfma_f32_16x16x32_bf16 v[78:81], v[134:137], v[204:207], v[78:81]
	v_mfma_f32_16x16x32_bf16 v[74:77], v[142:145], v[204:207], v[74:77]
	v_mfma_f32_16x16x32_bf16 v[118:121], v[146:149], v[162:165], v[118:121]
	v_mfma_f32_16x16x32_bf16 v[114:117], v[154:157], v[162:165], v[114:117]
	v_mfma_f32_16x16x32_bf16 v[102:105], v[146:149], v[170:173], v[102:105]
	v_mfma_f32_16x16x32_bf16 v[98:101], v[154:157], v[170:173], v[98:101]
	v_mfma_f32_16x16x32_bf16 v[86:89], v[146:149], v[188:191], v[86:89]
	v_mfma_f32_16x16x32_bf16 v[82:85], v[154:157], v[188:191], v[82:85]
	v_mfma_f32_16x16x32_bf16 v[70:73], v[146:149], v[196:199], v[70:73]
	v_mfma_f32_16x16x32_bf16 v[66:69], v[154:157], v[196:199], v[66:69]
	v_mfma_f32_16x16x32_bf16 v[118:121], v[150:153], v[166:169], v[118:121]
	v_mfma_f32_16x16x32_bf16 v[114:117], v[158:161], v[166:169], v[114:117]
	v_mfma_f32_16x16x32_bf16 v[102:105], v[150:153], v[174:177], v[102:105]
	v_mfma_f32_16x16x32_bf16 v[98:101], v[158:161], v[174:177], v[98:101]
	v_mfma_f32_16x16x32_bf16 v[86:89], v[150:153], v[192:195], v[86:89]
	v_mfma_f32_16x16x32_bf16 v[82:85], v[158:161], v[192:195], v[82:85]
	v_mfma_f32_16x16x32_bf16 v[70:73], v[150:153], v[204:207], v[70:73]
	v_mfma_f32_16x16x32_bf16 v[66:69], v[158:161], v[204:207], v[66:69]
	s_setprio 0
	s_barrier
	s_add_i32 s14, s14, s46
	v_lshl_add_u64 v[200:201], s[58:59], 0, v[0:1]
	s_mov_b32 m0, s14
	ds_read_b128 v[162:165], v218 offset:16384
	ds_read_b128 v[166:169], v218 offset:17408
	ds_read_b128 v[170:173], v218 offset:18432
	ds_read_b128 v[174:177], v218 offset:19456
	ds_read_b128 v[188:191], v218 offset:20480
	ds_read_b128 v[192:195], v218 offset:21504
	ds_read_b128 v[196:199], v218 offset:22528
	ds_read_b128 v[204:207], v218 offset:23552
	global_load_lds_dwordx4 v[200:201], off
	s_add_i32 m0, s14, 0x2000
	s_add_u32 s14, s58, 0x160000
	v_lshl_add_u64 v[208:209], s[58:59], 0, v[182:183]
	s_addc_u32 s15, s59, 0
	s_add_i32 s56, s72, s46
	global_load_lds_dwordx4 v[208:209], off
	v_lshl_add_u64 v[210:211], s[14:15], 0, v[0:1]
	s_mov_b32 m0, s56
	v_lshl_add_u64 v[220:221], s[60:61], 0, v[180:181]
	global_load_lds_dwordx4 v[210:211], off
	v_lshl_add_u64 v[210:211], s[14:15], 0, v[182:183]
	s_add_i32 m0, s56, 0x2000
	s_nop 0
	global_load_lds_dwordx4 v[210:211], off
	v_lshl_add_u64 v[210:211], s[60:61], 0, v[178:179]
	s_mov_b32 m0, s47
	s_nop 0
	global_load_lds_dwordx4 v[210:211], off
	s_mov_b32 m0, s62
	s_nop 0
	global_load_lds_dwordx4 v[220:221], off
	s_waitcnt vmcnt(8)
	s_waitcnt lgkmcnt(0)
	s_barrier
; #define PG8_STAGE(bufoff, gbase, voff) do { _Pragma("unroll") for (int _i = 0; _i < 2; ++_i) \
;         __builtin_amdgcn_global_load_lds((const unsigned*)((const char*)(gbase) + (voff)[_i]), (LAS unsigned*)(lds + (bufoff) + ldsw + _i * 8192), 16, 0, 0); } while (0)
; #define PG8_LDA(dst, b, h) do { _Pragma("unroll") for (int m = 0; m < 4; ++m) _Pragma("unroll") for (int k = 0; k < 2; ++k) dst[m][k] = *(const LAS bf16x8*)(lds + PG8_SA(b, h) + aoff + m * 2048 + k * 1024); } while (0)
; #define PG8_LDB(dst, b, h) do { _Pragma("unroll") for (int n = 0; n < 2; ++n) _Pragma("unroll") for (int k = 0; k < 2; ++k) dst[n][k] = *(const LAS bf16x8*)(lds + PG8_SB(b, h) + boff + n * 2048 + k * 1024); } while (0)
; #define PG8_MMA(ai, bj, At, Bt) do { __builtin_amdgcn_s_setprio(1); _Pragma("unroll") for (int m = 0; m < 4; ++m) _Pragma("unroll") for (int n = 0; n < 2; ++n) _Pragma("unroll") for (int k = 0; k < 2; ++k) \
;         acc[ai][bj][m][n] = __builtin_amdgcn_mfma_f32_16x16x32_bf16(Bt[n][k], At[m][k], acc[ai][bj][m][n], 0, 0, 0); __builtin_amdgcn_s_setprio(0); } while (0)
; #define PG8_WAIT_V(n) asm volatile("s_waitcnt vmcnt(" #n ")" ::: "memory")
; #define PG8_WAIT_L(n) asm volatile("s_waitcnt lgkmcnt(" #n ")" ::: "memory")
; #define PG8_BAR __builtin_amdgcn_s_barrier()
; #define PG8_SCHED __builtin_amdgcn_sched_barrier(0)
; template <class Epi, class Sched>
; __device__ __forceinline__ void gemm_phase(LAS unsigned char* lds, const Gemm g, const Sched& S, const Epi& E, const int tid) {
;     ...
;             PG8_WAIT_V(8); PG8_WAIT_L(0); PG8_BAR; PG8_MMA(1, 0, At, B0); PG8_MMA(1, 1, At, B1); PG8_BAR; PG8_SCHED;
;             PG8_LDB(B0, 1, 0); PG8_LDB(B1, 1, 1); PG8_SCHED; PG8_LDA(At, 1, 0); PG8_STAGE(PG8_SA(0, 1), a2 + hstepA, voffA);
;             PG8_WAIT_V(8); PG8_WAIT_L(0); PG8_BAR; PG8_MMA(0, 0, At, B0); PG8_MMA(0, 1, At, B1); PG8_BAR; PG8_SCHED;
	s_setprio 1
	v_mfma_f32_16x16x32_bf16 v[62:65], v[130:133], v[162:165], v[62:65]
	v_mfma_f32_16x16x32_bf16 v[58:61], v[138:141], v[162:165], v[58:61]
	v_mfma_f32_16x16x32_bf16 v[46:49], v[130:133], v[170:173], v[46:49]
	v_mfma_f32_16x16x32_bf16 v[42:45], v[138:141], v[170:173], v[42:45]
	v_mfma_f32_16x16x32_bf16 v[30:33], v[130:133], v[188:191], v[30:33]
	v_mfma_f32_16x16x32_bf16 v[26:29], v[138:141], v[188:191], v[26:29]
	v_mfma_f32_16x16x32_bf16 v[14:17], v[130:133], v[196:199], v[14:17]
	v_mfma_f32_16x16x32_bf16 v[10:13], v[138:141], v[196:199], v[10:13]
	v_mfma_f32_16x16x32_bf16 v[62:65], v[134:137], v[166:169], v[62:65]
	v_mfma_f32_16x16x32_bf16 v[58:61], v[142:145], v[166:169], v[58:61]
	v_mfma_f32_16x16x32_bf16 v[46:49], v[134:137], v[174:177], v[46:49]
	v_mfma_f32_16x16x32_bf16 v[42:45], v[142:145], v[174:177], v[42:45]
	v_mfma_f32_16x16x32_bf16 v[30:33], v[134:137], v[192:195], v[30:33]
	v_mfma_f32_16x16x32_bf16 v[26:29], v[142:145], v[192:195], v[26:29]
	v_mfma_f32_16x16x32_bf16 v[14:17], v[134:137], v[204:207], v[14:17]
	v_mfma_f32_16x16x32_bf16 v[10:13], v[142:145], v[204:207], v[10:13]
	v_mfma_f32_16x16x32_bf16 v[54:57], v[146:149], v[162:165], v[54:57]
	v_mfma_f32_16x16x32_bf16 v[50:53], v[154:157], v[162:165], v[50:53]
	v_mfma_f32_16x16x32_bf16 v[38:41], v[146:149], v[170:173], v[38:41]
	v_mfma_f32_16x16x32_bf16 v[34:37], v[154:157], v[170:173], v[34:37]
	v_mfma_f32_16x16x32_bf16 v[22:25], v[146:149], v[188:191], v[22:25]
	v_mfma_f32_16x16x32_bf16 v[18:21], v[154:157], v[188:191], v[18:21]
	v_mfma_f32_16x16x32_bf16 v[6:9], v[146:149], v[196:199], v[6:9]
	v_mfma_f32_16x16x32_bf16 v[2:5], v[154:157], v[196:199], v[2:5]
	v_mfma_f32_16x16x32_bf16 v[54:57], v[150:153], v[166:169], v[54:57]
	v_mfma_f32_16x16x32_bf16 v[50:53], v[158:161], v[166:169], v[50:53]
	v_mfma_f32_16x16x32_bf16 v[38:41], v[150:153], v[174:177], v[38:41]
	v_mfma_f32_16x16x32_bf16 v[34:37], v[158:161], v[174:177], v[34:37]
	v_mfma_f32_16x16x32_bf16 v[22:25], v[150:153], v[192:195], v[22:25]
	v_mfma_f32_16x16x32_bf16 v[18:21], v[158:161], v[192:195], v[18:21]
	v_mfma_f32_16x16x32_bf16 v[6:9], v[150:153], v[204:207], v[6:9]
	v_mfma_f32_16x16x32_bf16 v[2:5], v[158:161], v[204:207], v[2:5]
	s_setprio 0
	s_barrier
	s_add_i32 s56, 0, 0x18000
	s_add_i32 s57, 0, 0x1c000
	v_add_u32_e32 v142, s56, v213
	v_add_u32_e32 v158, s57, v213
	ds_read_b128 v[130:133], v142
	ds_read_b128 v[134:137], v142 offset:1024
	ds_read_b128 v[138:141], v142 offset:2048
	ds_read_b128 v[142:145], v142 offset:3072
	ds_read_b128 v[146:149], v158
	ds_read_b128 v[150:153], v158 offset:1024
	ds_read_b128 v[154:157], v158 offset:2048
	ds_read_b128 v[158:161], v158 offset:3072
	s_add_u32 s14, s60, 0x160000
	s_addc_u32 s15, s61, 0
	s_mov_b32 m0, s63
	v_lshl_add_u64 v[222:223], s[14:15], 0, v[178:179]
	ds_read_b128 v[162:165], v218 offset:32768
	ds_read_b128 v[166:169], v218 offset:33792
	ds_read_b128 v[170:173], v218 offset:34816
	ds_read_b128 v[174:177], v218 offset:35840
	ds_read_b128 v[188:191], v218 offset:36864
	ds_read_b128 v[192:195], v218 offset:37888
	ds_read_b128 v[196:199], v218 offset:38912
	ds_read_b128 v[204:207], v218 offset:39936
	global_load_lds_dwordx4 v[222:223], off
	v_lshl_add_u64 v[222:223], s[14:15], 0, v[180:181]
	s_mov_b32 m0, s64
	s_nop 0
	global_load_lds_dwordx4 v[222:223], off
	s_waitcnt vmcnt(8)
	s_waitcnt lgkmcnt(0)
	s_barrier
	s_setprio 1
	v_mfma_f32_16x16x32_bf16 v[126:129], v[130:133], v[162:165], v[126:129]
	v_mfma_f32_16x16x32_bf16 v[122:125], v[138:141], v[162:165], v[122:125]
	v_mfma_f32_16x16x32_bf16 v[110:113], v[130:133], v[170:173], v[110:113]
	v_mfma_f32_16x16x32_bf16 v[106:109], v[138:141], v[170:173], v[106:109]
	v_mfma_f32_16x16x32_bf16 v[94:97], v[130:133], v[188:191], v[94:97]
	v_mfma_f32_16x16x32_bf16 v[90:93], v[138:141], v[188:191], v[90:93]
	v_mfma_f32_16x16x32_bf16 v[78:81], v[130:133], v[196:199], v[78:81]
	v_mfma_f32_16x16x32_bf16 v[74:77], v[138:141], v[196:199], v[74:77]
	v_mfma_f32_16x16x32_bf16 v[126:129], v[134:137], v[166:169], v[126:129]
	v_mfma_f32_16x16x32_bf16 v[122:125], v[142:145], v[166:169], v[122:125]
	v_mfma_f32_16x16x32_bf16 v[110:113], v[134:137], v[174:177], v[110:113]
	v_mfma_f32_16x16x32_bf16 v[106:109], v[142:145], v[174:177], v[106:109]
	v_mfma_f32_16x16x32_bf16 v[94:97], v[134:137], v[192:195], v[94:97]
	v_mfma_f32_16x16x32_bf16 v[90:93], v[142:145], v[192:195], v[90:93]
	v_mfma_f32_16x16x32_bf16 v[78:81], v[134:137], v[204:207], v[78:81]
	v_mfma_f32_16x16x32_bf16 v[74:77], v[142:145], v[204:207], v[74:77]
	v_mfma_f32_16x16x32_bf16 v[118:121], v[146:149], v[162:165], v[118:121]
	v_mfma_f32_16x16x32_bf16 v[114:117], v[154:157], v[162:165], v[114:117]
	v_mfma_f32_16x16x32_bf16 v[102:105], v[146:149], v[170:173], v[102:105]
	v_mfma_f32_16x16x32_bf16 v[98:101], v[154:157], v[170:173], v[98:101]
	v_mfma_f32_16x16x32_bf16 v[86:89], v[146:149], v[188:191], v[86:89]
	v_mfma_f32_16x16x32_bf16 v[82:85], v[154:157], v[188:191], v[82:85]
	v_mfma_f32_16x16x32_bf16 v[70:73], v[146:149], v[196:199], v[70:73]
	v_mfma_f32_16x16x32_bf16 v[66:69], v[154:157], v[196:199], v[66:69]
	v_mfma_f32_16x16x32_bf16 v[118:121], v[150:153], v[166:169], v[118:121]
	v_mfma_f32_16x16x32_bf16 v[114:117], v[158:161], v[166:169], v[114:117]
	v_mfma_f32_16x16x32_bf16 v[102:105], v[150:153], v[174:177], v[102:105]
	v_mfma_f32_16x16x32_bf16 v[98:101], v[158:161], v[174:177], v[98:101]
	v_mfma_f32_16x16x32_bf16 v[86:89], v[150:153], v[192:195], v[86:89]
	v_mfma_f32_16x16x32_bf16 v[82:85], v[158:161], v[192:195], v[82:85]
	v_mfma_f32_16x16x32_bf16 v[70:73], v[150:153], v[204:207], v[70:73]
	v_mfma_f32_16x16x32_bf16 v[66:69], v[158:161], v[204:207], v[66:69]
	s_setprio 0
	s_barrier
; #define PG8_STAGE(bufoff, gbase, voff) do { _Pragma("unroll") for (int _i = 0; _i < 2; ++_i) \
;         __builtin_amdgcn_global_load_lds((const unsigned*)((const char*)(gbase) + (voff)[_i]), (LAS unsigned*)(lds + (bufoff) + ldsw + _i * 8192), 16, 0, 0); } while (0)
; #define PG8_LDA(dst, b, h) do { _Pragma("unroll") for (int m = 0; m < 4; ++m) _Pragma("unroll") for (int k = 0; k < 2; ++k) dst[m][k] = *(const LAS bf16x8*)(lds + PG8_SA(b, h) + aoff + m * 2048 + k * 1024); } while (0)
; #define PG8_MMA(ai, bj, At, Bt) do { __builtin_amdgcn_s_setprio(1); _Pragma("unroll") for (int m = 0; m < 4; ++m) _Pragma("unroll") for (int n = 0; n < 2; ++n) _Pragma("unroll") for (int k = 0; k < 2; ++k) \
;         acc[ai][bj][m][n] = __builtin_amdgcn_mfma_f32_16x16x32_bf16(Bt[n][k], At[m][k], acc[ai][bj][m][n], 0, 0, 0); __builtin_amdgcn_s_setprio(0); } while (0)
; #define PG8_WAIT_V(n) asm volatile("s_waitcnt vmcnt(" #n ")" ::: "memory")
; #define PG8_WAIT_L(n) asm volatile("s_waitcnt lgkmcnt(" #n ")" ::: "memory")
; #define PG8_BAR __builtin_amdgcn_s_barrier()
; #define PG8_SCHED __builtin_amdgcn_sched_barrier(0)
; template <class Epi, class Sched>
; __device__ __forceinline__ void gemm_phase(LAS unsigned char* lds, const Gemm g, const Sched& S, const Epi& E, const int tid) {
;     ...
;             PG8_LDA(At, 1, 1); PG8_STAGE(PG8_SB(1, 0), b3, voffB); PG8_STAGE(PG8_SB(1, 1), b3 + hstepB, voffB); PG8_STAGE(PG8_SA(1, 0), a3, voffA);
;             PG8_WAIT_V(8); PG8_WAIT_L(0); PG8_BAR; PG8_MMA(1, 0, At, B0); PG8_MMA(1, 1, At, B1); PG8_BAR; PG8_SCHED;
;         }
;         if (wr == 0) PG8_BAR;
	s_add_i32 s14, s56, s46
	v_lshl_add_u64 v[200:201], v[200:201], 0, s[90:91]
	s_mov_b32 m0, s14
	ds_read_b128 v[162:165], v218 offset:49152
	ds_read_b128 v[166:169], v218 offset:50176
	ds_read_b128 v[170:173], v218 offset:51200
	ds_read_b128 v[174:177], v218 offset:52224
	ds_read_b128 v[188:191], v218 offset:53248
	ds_read_b128 v[192:195], v218 offset:54272
	ds_read_b128 v[196:199], v218 offset:55296
	ds_read_b128 v[204:207], v218 offset:56320
	global_load_lds_dwordx4 v[200:201], off
	s_add_i32 m0, s14, 0x2000
	s_add_u32 s14, s58, 0x160080
	v_lshl_add_u64 v[200:201], v[208:209], 0, s[90:91]
	s_addc_u32 s15, s59, 0
	s_add_i32 s56, s57, s46
	global_load_lds_dwordx4 v[200:201], off
	v_lshl_add_u64 v[200:201], s[14:15], 0, v[0:1]
	s_mov_b32 m0, s56
	s_nop 0
	global_load_lds_dwordx4 v[200:201], off
	v_lshl_add_u64 v[200:201], s[14:15], 0, v[182:183]
	s_add_i32 m0, s56, 0x2000
	s_nop 0
	global_load_lds_dwordx4 v[200:201], off
	v_lshl_add_u64 v[200:201], v[210:211], 0, s[90:91]
	s_mov_b32 m0, s65
	s_nop 0
	global_load_lds_dwordx4 v[200:201], off
	v_lshl_add_u64 v[200:201], v[220:221], 0, s[90:91]
	s_mov_b32 m0, s66
	s_nop 0
	global_load_lds_dwordx4 v[200:201], off
	s_waitcnt vmcnt(8)
	s_waitcnt lgkmcnt(0)
	s_barrier
	s_setprio 1
	v_mfma_f32_16x16x32_bf16 v[62:65], v[130:133], v[162:165], v[62:65]
	v_mfma_f32_16x16x32_bf16 v[58:61], v[138:141], v[162:165], v[58:61]
	v_mfma_f32_16x16x32_bf16 v[46:49], v[130:133], v[170:173], v[46:49]
	v_mfma_f32_16x16x32_bf16 v[42:45], v[138:141], v[170:173], v[42:45]
	v_mfma_f32_16x16x32_bf16 v[30:33], v[130:133], v[188:191], v[30:33]
	v_mfma_f32_16x16x32_bf16 v[26:29], v[138:141], v[188:191], v[26:29]
	v_mfma_f32_16x16x32_bf16 v[14:17], v[130:133], v[196:199], v[14:17]
	v_mfma_f32_16x16x32_bf16 v[10:13], v[138:141], v[196:199], v[10:13]
	v_mfma_f32_16x16x32_bf16 v[62:65], v[134:137], v[166:169], v[62:65]
	v_mfma_f32_16x16x32_bf16 v[58:61], v[142:145], v[166:169], v[58:61]
	v_mfma_f32_16x16x32_bf16 v[46:49], v[134:137], v[174:177], v[46:49]
	v_mfma_f32_16x16x32_bf16 v[42:45], v[142:145], v[174:177], v[42:45]
	v_mfma_f32_16x16x32_bf16 v[30:33], v[134:137], v[192:195], v[30:33]
	v_mfma_f32_16x16x32_bf16 v[26:29], v[142:145], v[192:195], v[26:29]
	v_mfma_f32_16x16x32_bf16 v[14:17], v[134:137], v[204:207], v[14:17]
	v_mfma_f32_16x16x32_bf16 v[10:13], v[142:145], v[204:207], v[10:13]
	v_mfma_f32_16x16x32_bf16 v[54:57], v[146:149], v[162:165], v[54:57]
	v_mfma_f32_16x16x32_bf16 v[50:53], v[154:157], v[162:165], v[50:53]
	v_mfma_f32_16x16x32_bf16 v[38:41], v[146:149], v[170:173], v[38:41]
	v_mfma_f32_16x16x32_bf16 v[34:37], v[154:157], v[170:173], v[34:37]
	v_mfma_f32_16x16x32_bf16 v[22:25], v[146:149], v[188:191], v[22:25]
	v_mfma_f32_16x16x32_bf16 v[18:21], v[154:157], v[188:191], v[18:21]
	v_mfma_f32_16x16x32_bf16 v[6:9], v[146:149], v[196:199], v[6:9]
	v_mfma_f32_16x16x32_bf16 v[2:5], v[154:157], v[196:199], v[2:5]
	v_mfma_f32_16x16x32_bf16 v[54:57], v[150:153], v[166:169], v[54:57]
	v_mfma_f32_16x16x32_bf16 v[50:53], v[158:161], v[166:169], v[50:53]
	v_mfma_f32_16x16x32_bf16 v[38:41], v[150:153], v[174:177], v[38:41]
	v_mfma_f32_16x16x32_bf16 v[34:37], v[158:161], v[174:177], v[34:37]
	v_mfma_f32_16x16x32_bf16 v[22:25], v[150:153], v[192:195], v[22:25]
	v_mfma_f32_16x16x32_bf16 v[18:21], v[158:161], v[192:195], v[18:21]
	v_mfma_f32_16x16x32_bf16 v[6:9], v[150:153], v[204:207], v[6:9]
	v_mfma_f32_16x16x32_bf16 v[2:5], v[158:161], v[204:207], v[2:5]
	s_setprio 0
	s_barrier
	s_add_i32 s71, s71, 2
	s_add_u32 s44, s44, 0x100
	s_addc_u32 s45, s45, 0
	s_cmpk_gt_u32 s71, 0x55
	s_mov_b64 s[56:57], s[42:43]
	s_cbranch_scc0 .LBB1_36
	s_and_b64 vcc, exec, s[36:37]
	s_cbranch_vccz .LBB1_39
	s_barrier

; #define PG8_STAGE(bufoff, gbase, voff) do { _Pragma("unroll") for (int _i = 0; _i < 2; ++_i) \
;         __builtin_amdgcn_global_load_lds((const unsigned*)((const char*)(gbase) + (voff)[_i]), (LAS unsigned*)(lds + (bufoff) + ldsw + _i * 8192), 16, 0, 0); } while (0)
; #define PG8_LDA(dst, b, h) do { _Pragma("unroll") for (int m = 0; m < 4; ++m) _Pragma("unroll") for (int k = 0; k < 2; ++k) dst[m][k] = *(const LAS bf16x8*)(lds + PG8_SA(b, h) + aoff + m * 2048 + k * 1024); } while (0)
; #define PG8_LDB(dst, b, h) do { _Pragma("unroll") for (int n = 0; n < 2; ++n) _Pragma("unroll") for (int k = 0; k < 2; ++k) dst[n][k] = *(const LAS bf16x8*)(lds + PG8_SB(b, h) + boff + n * 2048 + k * 1024); } while (0)
; #define PG8_MMA(ai, bj, At, Bt) do { __builtin_amdgcn_s_setprio(1); _Pragma("unroll") for (int m = 0; m < 4; ++m) _Pragma("unroll") for (int n = 0; n < 2; ++n) _Pragma("unroll") for (int k = 0; k < 2; ++k) \
;         acc[ai][bj][m][n] = __builtin_amdgcn_mfma_f32_16x16x32_bf16(Bt[n][k], At[m][k], acc[ai][bj][m][n], 0, 0, 0); __builtin_amdgcn_s_setprio(0); } while (0)
; template <class Epi, class Sched>
; __device__ __forceinline__ void gemm_phase(LAS unsigned char* lds, const Gemm g, const Sched& S, const Epi& E, const int tid) {
;     ...
;         const bool has_next = S.next(ui + 1, nxt);
;         const char* nA = has_next ? (const char*)g.A + (size_t)nxt.pm * tstepA + (size_t)nxt.aoff * 2 : cA; const char* nB = has_next ? (const char*)g.Bt + (size_t)nxt.pn * tstepB : cB;
;         for (int t = 0; t < nt; t += 2) {
;             const bool last = (t == nt - 2);
;             const char* a1 = cA + (size_t)(t + 1) * kstep;
;             const char* a2 = last ? nA : cA + (size_t)(t + 2) * kstep; const char* b2 = last ? nB : cB + (size_t)(t + 2) * kstep;
;             const char* a3 = a2 + kstep; const char* b3 = b2 + kstep;
;             PG8_LDB(B0, 0, 0); PG8_LDB(B1, 0, 1); PG8_SCHED; PG8_LDA(At, 0, 0); PG8_STAGE(PG8_SA(1, 1), a1 + hstepA, voffA);
;             PG8_WAIT_V(8); PG8_WAIT_L(0); PG8_BAR; PG8_MMA(0, 0, At, B0); PG8_MMA(0, 1, At, B1); PG8_BAR; PG8_SCHED;
;             PG8_LDA(At, 0, 1); PG8_STAGE(PG8_SB(0, 0), b2, voffB); PG8_STAGE(PG8_SB(0, 1), b2 + hstepB, voffB); PG8_STAGE(PG8_SA(0, 0), a2, voffA);
;             PG8_WAIT_V(8); PG8_WAIT_L(0); PG8_BAR; PG8_MMA(1, 0, At, B0); PG8_MMA(1, 1, At, B1); PG8_BAR; PG8_SCHED;
.LBB1_87:
	s_add_u32 s14, s58, 0xfff80080
	s_addc_u32 s15, s59, -1
	s_add_i32 s70, 0, 0x10000
	s_cmp_eq_u32 s45, 28
	s_cselect_b32 s63, s37, s15
	s_cselect_b32 s62, s53, s14
	v_add_u32_e32 v144, s70, v147
	s_cselect_b32 s61, s41, s44
	s_cselect_b32 s60, s68, s69
	s_add_i32 s71, 0, 0x14000
	ds_read_b128 v[140:143], v144
	ds_read_b128 v[158:161], v144 offset:1024
	ds_read_b128 v[162:165], v144 offset:2048
	ds_read_b128 v[166:169], v144 offset:3072
	v_add_u32_e32 v144, s71, v147
	ds_read_b128 v[170:173], v144
	ds_read_b128 v[174:177], v144 offset:1024
	ds_read_b128 v[178:181], v144 offset:2048
	ds_read_b128 v[182:185], v144 offset:3072
	v_lshl_add_u64 v[220:221], s[58:59], 0, v[138:139]
	s_add_i32 m0, s47, 0xc000
	ds_read_b128 v[186:189], v157
	ds_read_b128 v[190:193], v157 offset:1024
	ds_read_b128 v[194:197], v157 offset:2048
	ds_read_b128 v[198:201], v157 offset:3072
	ds_read_b128 v[204:207], v157 offset:4096
	ds_read_b128 v[208:211], v157 offset:5120
	ds_read_b128 v[212:215], v157 offset:6144
	ds_read_b128 v[216:219], v157 offset:7168
	global_load_lds_dwordx4 v[220:221], off
	v_lshl_add_u64 v[220:221], s[58:59], 0, v[136:137]
	s_add_i32 m0, s47, 0xe000
	s_nop 0
	global_load_lds_dwordx4 v[220:221], off
	s_waitcnt vmcnt(8)
	s_waitcnt lgkmcnt(0)
	s_barrier
	s_setprio 1
	v_mfma_f32_16x16x32_bf16 v[126:129], v[140:143], v[186:189], v[126:129]
	v_mfma_f32_16x16x32_bf16 v[118:121], v[162:165], v[186:189], v[118:121]
	v_mfma_f32_16x16x32_bf16 v[110:113], v[140:143], v[194:197], v[110:113]
	v_mfma_f32_16x16x32_bf16 v[106:109], v[162:165], v[194:197], v[106:109]
	v_mfma_f32_16x16x32_bf16 v[94:97], v[140:143], v[204:207], v[94:97]
	v_mfma_f32_16x16x32_bf16 v[90:93], v[162:165], v[204:207], v[90:93]
	v_mfma_f32_16x16x32_bf16 v[78:81], v[140:143], v[212:215], v[78:81]
	v_mfma_f32_16x16x32_bf16 v[74:77], v[162:165], v[212:215], v[74:77]
	v_mfma_f32_16x16x32_bf16 v[126:129], v[158:161], v[190:193], v[126:129]
	v_mfma_f32_16x16x32_bf16 v[118:121], v[166:169], v[190:193], v[118:121]
	v_mfma_f32_16x16x32_bf16 v[110:113], v[158:161], v[198:201], v[110:113]
	v_mfma_f32_16x16x32_bf16 v[106:109], v[166:169], v[198:201], v[106:109]
	v_mfma_f32_16x16x32_bf16 v[94:97], v[158:161], v[208:211], v[94:97]
	v_mfma_f32_16x16x32_bf16 v[90:93], v[166:169], v[208:211], v[90:93]
	v_mfma_f32_16x16x32_bf16 v[78:81], v[158:161], v[216:219], v[78:81]
	v_mfma_f32_16x16x32_bf16 v[74:77], v[166:169], v[216:219], v[74:77]
	v_mfma_f32_16x16x32_bf16 v[122:125], v[170:173], v[186:189], v[122:125]
	v_mfma_f32_16x16x32_bf16 v[114:117], v[178:181], v[186:189], v[114:117]
	v_mfma_f32_16x16x32_bf16 v[102:105], v[170:173], v[194:197], v[102:105]
	v_mfma_f32_16x16x32_bf16 v[98:101], v[178:181], v[194:197], v[98:101]
	v_mfma_f32_16x16x32_bf16 v[86:89], v[170:173], v[204:207], v[86:89]
	v_mfma_f32_16x16x32_bf16 v[82:85], v[178:181], v[204:207], v[82:85]
	v_mfma_f32_16x16x32_bf16 v[70:73], v[170:173], v[212:215], v[70:73]
	v_mfma_f32_16x16x32_bf16 v[66:69], v[178:181], v[212:215], v[66:69]
	v_mfma_f32_16x16x32_bf16 v[122:125], v[174:177], v[190:193], v[122:125]
	v_mfma_f32_16x16x32_bf16 v[114:117], v[182:185], v[190:193], v[114:117]
	v_mfma_f32_16x16x32_bf16 v[102:105], v[174:177], v[198:201], v[102:105]
	v_mfma_f32_16x16x32_bf16 v[98:101], v[182:185], v[198:201], v[98:101]
	v_mfma_f32_16x16x32_bf16 v[86:89], v[174:177], v[208:211], v[86:89]
	v_mfma_f32_16x16x32_bf16 v[82:85], v[182:185], v[208:211], v[82:85]
	v_mfma_f32_16x16x32_bf16 v[70:73], v[174:177], v[216:219], v[70:73]
	v_mfma_f32_16x16x32_bf16 v[66:69], v[182:185], v[216:219], v[66:69]
	s_setprio 0
	s_barrier
	s_add_i32 s14, s70, s46
	v_lshl_add_u64 v[220:221], s[60:61], 0, v[0:1]
	s_mov_b32 m0, s14
	ds_read_b128 v[186:189], v157 offset:16384
	ds_read_b128 v[190:193], v157 offset:17408
	ds_read_b128 v[194:197], v157 offset:18432
	ds_read_b128 v[198:201], v157 offset:19456
	ds_read_b128 v[204:207], v157 offset:20480
	ds_read_b128 v[208:211], v157 offset:21504
	ds_read_b128 v[212:215], v157 offset:22528
	ds_read_b128 v[216:219], v157 offset:23552
	global_load_lds_dwordx4 v[220:221], off
	s_add_i32 m0, s14, 0x2000
	s_add_u32 s14, s60, 0x80000
	v_lshl_add_u64 v[222:223], s[60:61], 0, v[130:131]
	s_addc_u32 s15, s61, 0
	s_add_i32 s70, s71, s46
	global_load_lds_dwordx4 v[222:223], off
	v_lshl_add_u64 v[224:225], s[14:15], 0, v[0:1]
	s_mov_b32 m0, s70
	v_lshl_add_u64 v[226:227], s[62:63], 0, v[132:133]
	global_load_lds_dwordx4 v[224:225], off
	v_lshl_add_u64 v[224:225], s[14:15], 0, v[130:131]
	s_add_i32 m0, s70, 0x2000
	s_nop 0
	global_load_lds_dwordx4 v[224:225], off
	v_lshl_add_u64 v[224:225], s[62:63], 0, v[134:135]
	s_mov_b32 m0, s47
	s_nop 0
	global_load_lds_dwordx4 v[224:225], off
	s_mov_b32 m0, s57
	s_nop 0
	global_load_lds_dwordx4 v[226:227], off
	s_waitcnt vmcnt(8)
	s_waitcnt lgkmcnt(0)
	s_barrier
; #define PG8_STAGE(bufoff, gbase, voff) do { _Pragma("unroll") for (int _i = 0; _i < 2; ++_i) \
;         __builtin_amdgcn_global_load_lds((const unsigned*)((const char*)(gbase) + (voff)[_i]), (LAS unsigned*)(lds + (bufoff) + ldsw + _i * 8192), 16, 0, 0); } while (0)
; #define PG8_LDA(dst, b, h) do { _Pragma("unroll") for (int m = 0; m < 4; ++m) _Pragma("unroll") for (int k = 0; k < 2; ++k) dst[m][k] = *(const LAS bf16x8*)(lds + PG8_SA(b, h) + aoff + m * 2048 + k * 1024); } while (0)
; #define PG8_LDB(dst, b, h) do { _Pragma("unroll") for (int n = 0; n < 2; ++n) _Pragma("unroll") for (int k = 0; k < 2; ++k) dst[n][k] = *(const LAS bf16x8*)(lds + PG8_SB(b, h) + boff + n * 2048 + k * 1024); } while (0)
; #define PG8_MMA(ai, bj, At, Bt) do { __builtin_amdgcn_s_setprio(1); _Pragma("unroll") for (int m = 0; m < 4; ++m) _Pragma("unroll") for (int n = 0; n < 2; ++n) _Pragma("unroll") for (int k = 0; k < 2; ++k) \
;         acc[ai][bj][m][n] = __builtin_amdgcn_mfma_f32_16x16x32_bf16(Bt[n][k], At[m][k], acc[ai][bj][m][n], 0, 0, 0); __builtin_amdgcn_s_setprio(0); } while (0)
; #define PG8_WAIT_V(n) asm volatile("s_waitcnt vmcnt(" #n ")" ::: "memory")
; #define PG8_WAIT_L(n) asm volatile("s_waitcnt lgkmcnt(" #n ")" ::: "memory")
; #define PG8_BAR __builtin_amdgcn_s_barrier()
; #define PG8_SCHED __builtin_amdgcn_sched_barrier(0)
; template <class Epi, class Sched>
; __device__ __forceinline__ void gemm_phase(LAS unsigned char* lds, const Gemm g, const Sched& S, const Epi& E, const int tid) {
;     ...
;             PG8_WAIT_V(8); PG8_WAIT_L(0); PG8_BAR; PG8_MMA(1, 0, At, B0); PG8_MMA(1, 1, At, B1); PG8_BAR; PG8_SCHED;
;             PG8_LDB(B0, 1, 0); PG8_LDB(B1, 1, 1); PG8_SCHED; PG8_LDA(At, 1, 0); PG8_STAGE(PG8_SA(0, 1), a2 + hstepA, voffA);
;             PG8_WAIT_V(8); PG8_WAIT_L(0); PG8_BAR; PG8_MMA(0, 0, At, B0); PG8_MMA(0, 1, At, B1); PG8_BAR; PG8_SCHED;
	s_setprio 1
	v_mfma_f32_16x16x32_bf16 v[62:65], v[140:143], v[186:189], v[62:65]
	v_mfma_f32_16x16x32_bf16 v[58:61], v[162:165], v[186:189], v[58:61]
	v_mfma_f32_16x16x32_bf16 v[46:49], v[140:143], v[194:197], v[46:49]
	v_mfma_f32_16x16x32_bf16 v[42:45], v[162:165], v[194:197], v[42:45]
	v_mfma_f32_16x16x32_bf16 v[30:33], v[140:143], v[204:207], v[30:33]
	v_mfma_f32_16x16x32_bf16 v[26:29], v[162:165], v[204:207], v[26:29]
	v_mfma_f32_16x16x32_bf16 v[14:17], v[140:143], v[212:215], v[14:17]
	v_mfma_f32_16x16x32_bf16 v[10:13], v[162:165], v[212:215], v[10:13]
	v_mfma_f32_16x16x32_bf16 v[62:65], v[158:161], v[190:193], v[62:65]
	v_mfma_f32_16x16x32_bf16 v[58:61], v[166:169], v[190:193], v[58:61]
	v_mfma_f32_16x16x32_bf16 v[46:49], v[158:161], v[198:201], v[46:49]
	v_mfma_f32_16x16x32_bf16 v[42:45], v[166:169], v[198:201], v[42:45]
	v_mfma_f32_16x16x32_bf16 v[30:33], v[158:161], v[208:211], v[30:33]
	v_mfma_f32_16x16x32_bf16 v[26:29], v[166:169], v[208:211], v[26:29]
	v_mfma_f32_16x16x32_bf16 v[14:17], v[158:161], v[216:219], v[14:17]
	v_mfma_f32_16x16x32_bf16 v[10:13], v[166:169], v[216:219], v[10:13]
	v_mfma_f32_16x16x32_bf16 v[54:57], v[170:173], v[186:189], v[54:57]
	v_mfma_f32_16x16x32_bf16 v[50:53], v[178:181], v[186:189], v[50:53]
	v_mfma_f32_16x16x32_bf16 v[38:41], v[170:173], v[194:197], v[38:41]
	v_mfma_f32_16x16x32_bf16 v[34:37], v[178:181], v[194:197], v[34:37]
	v_mfma_f32_16x16x32_bf16 v[22:25], v[170:173], v[204:207], v[22:25]
	v_mfma_f32_16x16x32_bf16 v[18:21], v[178:181], v[204:207], v[18:21]
	v_mfma_f32_16x16x32_bf16 v[6:9], v[170:173], v[212:215], v[6:9]
	v_mfma_f32_16x16x32_bf16 v[2:5], v[178:181], v[212:215], v[2:5]
	v_mfma_f32_16x16x32_bf16 v[54:57], v[174:177], v[190:193], v[54:57]
	v_mfma_f32_16x16x32_bf16 v[50:53], v[182:185], v[190:193], v[50:53]
	v_mfma_f32_16x16x32_bf16 v[38:41], v[174:177], v[198:201], v[38:41]
	v_mfma_f32_16x16x32_bf16 v[34:37], v[182:185], v[198:201], v[34:37]
	v_mfma_f32_16x16x32_bf16 v[22:25], v[174:177], v[208:211], v[22:25]
	v_mfma_f32_16x16x32_bf16 v[18:21], v[182:185], v[208:211], v[18:21]
	v_mfma_f32_16x16x32_bf16 v[6:9], v[174:177], v[216:219], v[6:9]
	v_mfma_f32_16x16x32_bf16 v[2:5], v[182:185], v[216:219], v[2:5]
	s_setprio 0
	s_barrier
	s_add_i32 s70, 0, 0x18000
	v_add_u32_e32 v144, s70, v147
	s_add_i32 s71, 0, 0x1c000
	ds_read_b128 v[140:143], v144
	ds_read_b128 v[158:161], v144 offset:1024
	ds_read_b128 v[162:165], v144 offset:2048
	ds_read_b128 v[166:169], v144 offset:3072
	v_add_u32_e32 v144, s71, v147
	ds_read_b128 v[170:173], v144
	ds_read_b128 v[174:177], v144 offset:1024
	ds_read_b128 v[178:181], v144 offset:2048
	ds_read_b128 v[182:185], v144 offset:3072
	s_add_u32 s14, s62, 0x80000
	s_addc_u32 s15, s63, 0
	s_mov_b32 m0, s64
	v_lshl_add_u64 v[228:229], s[14:15], 0, v[134:135]
	ds_read_b128 v[186:189], v157 offset:32768
	ds_read_b128 v[190:193], v157 offset:33792
	ds_read_b128 v[194:197], v157 offset:34816
	ds_read_b128 v[198:201], v157 offset:35840
	ds_read_b128 v[204:207], v157 offset:36864
	ds_read_b128 v[208:211], v157 offset:37888
	ds_read_b128 v[212:215], v157 offset:38912
	ds_read_b128 v[216:219], v157 offset:39936
	global_load_lds_dwordx4 v[228:229], off
	v_lshl_add_u64 v[228:229], s[14:15], 0, v[132:133]
	s_mov_b32 m0, s65
	s_nop 0
	global_load_lds_dwordx4 v[228:229], off
	s_waitcnt vmcnt(8)
	s_waitcnt lgkmcnt(0)
	s_barrier
	s_setprio 1
	v_mfma_f32_16x16x32_bf16 v[126:129], v[140:143], v[186:189], v[126:129]
	v_mfma_f32_16x16x32_bf16 v[118:121], v[162:165], v[186:189], v[118:121]
	v_mfma_f32_16x16x32_bf16 v[110:113], v[140:143], v[194:197], v[110:113]
	v_mfma_f32_16x16x32_bf16 v[106:109], v[162:165], v[194:197], v[106:109]
	v_mfma_f32_16x16x32_bf16 v[94:97], v[140:143], v[204:207], v[94:97]
	v_mfma_f32_16x16x32_bf16 v[90:93], v[162:165], v[204:207], v[90:93]
	v_mfma_f32_16x16x32_bf16 v[78:81], v[140:143], v[212:215], v[78:81]
	v_mfma_f32_16x16x32_bf16 v[74:77], v[162:165], v[212:215], v[74:77]
	v_mfma_f32_16x16x32_bf16 v[126:129], v[158:161], v[190:193], v[126:129]
	v_mfma_f32_16x16x32_bf16 v[118:121], v[166:169], v[190:193], v[118:121]
	v_mfma_f32_16x16x32_bf16 v[110:113], v[158:161], v[198:201], v[110:113]
	v_mfma_f32_16x16x32_bf16 v[106:109], v[166:169], v[198:201], v[106:109]
	v_mfma_f32_16x16x32_bf16 v[94:97], v[158:161], v[208:211], v[94:97]
	v_mfma_f32_16x16x32_bf16 v[90:93], v[166:169], v[208:211], v[90:93]
	v_mfma_f32_16x16x32_bf16 v[78:81], v[158:161], v[216:219], v[78:81]
	v_mfma_f32_16x16x32_bf16 v[74:77], v[166:169], v[216:219], v[74:77]
	v_mfma_f32_16x16x32_bf16 v[122:125], v[170:173], v[186:189], v[122:125]
	v_mfma_f32_16x16x32_bf16 v[114:117], v[178:181], v[186:189], v[114:117]
	v_mfma_f32_16x16x32_bf16 v[102:105], v[170:173], v[194:197], v[102:105]
	v_mfma_f32_16x16x32_bf16 v[98:101], v[178:181], v[194:197], v[98:101]
	v_mfma_f32_16x16x32_bf16 v[86:89], v[170:173], v[204:207], v[86:89]
	v_mfma_f32_16x16x32_bf16 v[82:85], v[178:181], v[204:207], v[82:85]
	v_mfma_f32_16x16x32_bf16 v[70:73], v[170:173], v[212:215], v[70:73]
	v_mfma_f32_16x16x32_bf16 v[66:69], v[178:181], v[212:215], v[66:69]
	v_mfma_f32_16x16x32_bf16 v[122:125], v[174:177], v[190:193], v[122:125]
	v_mfma_f32_16x16x32_bf16 v[114:117], v[182:185], v[190:193], v[114:117]
	v_mfma_f32_16x16x32_bf16 v[102:105], v[174:177], v[198:201], v[102:105]
	v_mfma_f32_16x16x32_bf16 v[98:101], v[182:185], v[198:201], v[98:101]
	v_mfma_f32_16x16x32_bf16 v[86:89], v[174:177], v[208:211], v[86:89]
	v_mfma_f32_16x16x32_bf16 v[82:85], v[182:185], v[208:211], v[82:85]
	v_mfma_f32_16x16x32_bf16 v[70:73], v[174:177], v[216:219], v[70:73]
	v_mfma_f32_16x16x32_bf16 v[66:69], v[182:185], v[216:219], v[66:69]
	s_setprio 0
	s_barrier
; #define PG8_STAGE(bufoff, gbase, voff) do { _Pragma("unroll") for (int _i = 0; _i < 2; ++_i) \
;         __builtin_amdgcn_global_load_lds((const unsigned*)((const char*)(gbase) + (voff)[_i]), (LAS unsigned*)(lds + (bufoff) + ldsw + _i * 8192), 16, 0, 0); } while (0)
; #define PG8_LDA(dst, b, h) do { _Pragma("unroll") for (int m = 0; m < 4; ++m) _Pragma("unroll") for (int k = 0; k < 2; ++k) dst[m][k] = *(const LAS bf16x8*)(lds + PG8_SA(b, h) + aoff + m * 2048 + k * 1024); } while (0)
; #define PG8_MMA(ai, bj, At, Bt) do { __builtin_amdgcn_s_setprio(1); _Pragma("unroll") for (int m = 0; m < 4; ++m) _Pragma("unroll") for (int n = 0; n < 2; ++n) _Pragma("unroll") for (int k = 0; k < 2; ++k) \
;         acc[ai][bj][m][n] = __builtin_amdgcn_mfma_f32_16x16x32_bf16(Bt[n][k], At[m][k], acc[ai][bj][m][n], 0, 0, 0); __builtin_amdgcn_s_setprio(0); } while (0)
; #define PG8_WAIT_V(n) asm volatile("s_waitcnt vmcnt(" #n ")" ::: "memory")
; #define PG8_WAIT_L(n) asm volatile("s_waitcnt lgkmcnt(" #n ")" ::: "memory")
; #define PG8_BAR __builtin_amdgcn_s_barrier()
; #define PG8_SCHED __builtin_amdgcn_sched_barrier(0)
; template <class Epi, class Sched>
; __device__ __forceinline__ void gemm_phase(LAS unsigned char* lds, const Gemm g, const Sched& S, const Epi& E, const int tid) {
;     ...
;             PG8_LDA(At, 1, 1); PG8_STAGE(PG8_SB(1, 0), b3, voffB); PG8_STAGE(PG8_SB(1, 1), b3 + hstepB, voffB); PG8_STAGE(PG8_SA(1, 0), a3, voffA);
;             PG8_WAIT_V(8); PG8_WAIT_L(0); PG8_BAR; PG8_MMA(1, 0, At, B0); PG8_MMA(1, 1, At, B1); PG8_BAR; PG8_SCHED;
;         }
;         if (wr == 0) PG8_BAR;
	s_add_i32 s14, s70, s46
	v_lshl_add_u64 v[220:221], v[220:221], 0, s[90:91]
	s_mov_b32 m0, s14
	ds_read_b128 v[186:189], v157 offset:49152
	ds_read_b128 v[190:193], v157 offset:50176
	ds_read_b128 v[194:197], v157 offset:51200
	ds_read_b128 v[198:201], v157 offset:52224
	ds_read_b128 v[204:207], v157 offset:53248
	ds_read_b128 v[208:211], v157 offset:54272
	ds_read_b128 v[212:215], v157 offset:55296
	ds_read_b128 v[216:219], v157 offset:56320
	global_load_lds_dwordx4 v[220:221], off
	s_add_i32 m0, s14, 0x2000
	s_add_u32 s14, s60, 0x80080
	v_lshl_add_u64 v[220:221], v[222:223], 0, s[90:91]
	s_addc_u32 s15, s61, 0
	s_add_i32 s60, s71, s46
	global_load_lds_dwordx4 v[220:221], off
	v_lshl_add_u64 v[220:221], s[14:15], 0, v[0:1]
	s_mov_b32 m0, s60
	s_nop 0
	global_load_lds_dwordx4 v[220:221], off
	v_lshl_add_u64 v[220:221], s[14:15], 0, v[130:131]
	s_add_i32 m0, s60, 0x2000
	s_nop 0
	global_load_lds_dwordx4 v[220:221], off
	v_lshl_add_u64 v[220:221], v[224:225], 0, s[90:91]
	s_mov_b32 m0, s66
	s_nop 0
	global_load_lds_dwordx4 v[220:221], off
	v_lshl_add_u64 v[220:221], v[226:227], 0, s[90:91]
	s_mov_b32 m0, s67
	s_nop 0
	global_load_lds_dwordx4 v[220:221], off
	s_waitcnt vmcnt(8)
	s_waitcnt lgkmcnt(0)
	s_barrier
	s_setprio 1
	v_mfma_f32_16x16x32_bf16 v[62:65], v[140:143], v[186:189], v[62:65]
	v_mfma_f32_16x16x32_bf16 v[58:61], v[162:165], v[186:189], v[58:61]
	v_mfma_f32_16x16x32_bf16 v[46:49], v[140:143], v[194:197], v[46:49]
	v_mfma_f32_16x16x32_bf16 v[42:45], v[162:165], v[194:197], v[42:45]
	v_mfma_f32_16x16x32_bf16 v[30:33], v[140:143], v[204:207], v[30:33]
	v_mfma_f32_16x16x32_bf16 v[26:29], v[162:165], v[204:207], v[26:29]
	v_mfma_f32_16x16x32_bf16 v[14:17], v[140:143], v[212:215], v[14:17]
	v_mfma_f32_16x16x32_bf16 v[10:13], v[162:165], v[212:215], v[10:13]
	v_mfma_f32_16x16x32_bf16 v[62:65], v[158:161], v[190:193], v[62:65]
	v_mfma_f32_16x16x32_bf16 v[58:61], v[166:169], v[190:193], v[58:61]
	v_mfma_f32_16x16x32_bf16 v[46:49], v[158:161], v[198:201], v[46:49]
	v_mfma_f32_16x16x32_bf16 v[42:45], v[166:169], v[198:201], v[42:45]
	v_mfma_f32_16x16x32_bf16 v[30:33], v[158:161], v[208:211], v[30:33]
	v_mfma_f32_16x16x32_bf16 v[26:29], v[166:169], v[208:211], v[26:29]
	v_mfma_f32_16x16x32_bf16 v[14:17], v[158:161], v[216:219], v[14:17]
	v_mfma_f32_16x16x32_bf16 v[10:13], v[166:169], v[216:219], v[10:13]
	v_mfma_f32_16x16x32_bf16 v[54:57], v[170:173], v[186:189], v[54:57]
	v_mfma_f32_16x16x32_bf16 v[50:53], v[178:181], v[186:189], v[50:53]
	v_mfma_f32_16x16x32_bf16 v[38:41], v[170:173], v[194:197], v[38:41]
	v_mfma_f32_16x16x32_bf16 v[34:37], v[178:181], v[194:197], v[34:37]
	v_mfma_f32_16x16x32_bf16 v[22:25], v[170:173], v[204:207], v[22:25]
	v_mfma_f32_16x16x32_bf16 v[18:21], v[178:181], v[204:207], v[18:21]
	v_mfma_f32_16x16x32_bf16 v[6:9], v[170:173], v[212:215], v[6:9]
	v_mfma_f32_16x16x32_bf16 v[2:5], v[178:181], v[212:215], v[2:5]
	v_mfma_f32_16x16x32_bf16 v[54:57], v[174:177], v[190:193], v[54:57]
	v_mfma_f32_16x16x32_bf16 v[50:53], v[182:185], v[190:193], v[50:53]
	v_mfma_f32_16x16x32_bf16 v[38:41], v[174:177], v[198:201], v[38:41]
	v_mfma_f32_16x16x32_bf16 v[34:37], v[182:185], v[198:201], v[34:37]
	v_mfma_f32_16x16x32_bf16 v[22:25], v[174:177], v[208:211], v[22:25]
	v_mfma_f32_16x16x32_bf16 v[18:21], v[182:185], v[208:211], v[18:21]
	v_mfma_f32_16x16x32_bf16 v[6:9], v[174:177], v[216:219], v[6:9]
	v_mfma_f32_16x16x32_bf16 v[2:5], v[182:185], v[216:219], v[2:5]
	s_setprio 0
	s_barrier
	s_add_i32 s45, s45, 2
	s_add_u32 s69, s69, 0x100
	s_addc_u32 s44, s44, 0
	s_add_u32 s58, s58, 0x100
	s_addc_u32 s59, s59, 0
	s_cmp_gt_u32 s45, 29
	s_cbranch_scc0 .LBB1_87
	s_and_b64 vcc, exec, s[26:27]
	s_cbranch_vccz .LBB1_90
	s_barrier

; #define PG8_STAGE(bufoff, gbase, voff) do { _Pragma("unroll") for (int _i = 0; _i < 2; ++_i) \
;         __builtin_amdgcn_global_load_lds((const unsigned*)((const char*)(gbase) + (voff)[_i]), (LAS unsigned*)(lds + (bufoff) + ldsw + _i * 8192), 16, 0, 0); } while (0)
; #define PG8_LDA(dst, b, h) do { _Pragma("unroll") for (int m = 0; m < 4; ++m) _Pragma("unroll") for (int k = 0; k < 2; ++k) dst[m][k] = *(const LAS bf16x8*)(lds + PG8_SA(b, h) + aoff + m * 2048 + k * 1024); } while (0)
; #define PG8_LDB(dst, b, h) do { _Pragma("unroll") for (int n = 0; n < 2; ++n) _Pragma("unroll") for (int k = 0; k < 2; ++k) dst[n][k] = *(const LAS bf16x8*)(lds + PG8_SB(b, h) + boff + n * 2048 + k * 1024); } while (0)
; #define PG8_MMA(ai, bj, At, Bt) do { __builtin_amdgcn_s_setprio(1); _Pragma("unroll") for (int m = 0; m < 4; ++m) _Pragma("unroll") for (int n = 0; n < 2; ++n) _Pragma("unroll") for (int k = 0; k < 2; ++k) \
;         acc[ai][bj][m][n] = __builtin_amdgcn_mfma_f32_16x16x32_bf16(Bt[n][k], At[m][k], acc[ai][bj][m][n], 0, 0, 0); __builtin_amdgcn_s_setprio(0); } while (0)
; template <class Epi, class Sched>
; __device__ __forceinline__ void gemm_phase(LAS unsigned char* lds, const Gemm g, const Sched& S, const Epi& E, const int tid) {
;     ...
;         const bool has_next = S.next(ui + 1, nxt);
;         const char* nA = has_next ? (const char*)g.A + (size_t)nxt.pm * tstepA + (size_t)nxt.aoff * 2 : cA; const char* nB = has_next ? (const char*)g.Bt + (size_t)nxt.pn * tstepB : cB;
;         for (int t = 0; t < nt; t += 2) {
;             const bool last = (t == nt - 2);
;             const char* a1 = cA + (size_t)(t + 1) * kstep;
;             const char* a2 = last ? nA : cA + (size_t)(t + 2) * kstep; const char* b2 = last ? nB : cB + (size_t)(t + 2) * kstep;
;             const char* a3 = a2 + kstep; const char* b3 = b2 + kstep;
;             PG8_LDB(B0, 0, 0); PG8_LDB(B1, 0, 1); PG8_SCHED; PG8_LDA(At, 0, 0); PG8_STAGE(PG8_SA(1, 1), a1 + hstepA, voffA);
;             PG8_WAIT_V(8); PG8_WAIT_L(0); PG8_BAR; PG8_MMA(0, 0, At, B0); PG8_MMA(0, 1, At, B1); PG8_BAR; PG8_SCHED;
;             PG8_LDA(At, 0, 1); PG8_STAGE(PG8_SB(0, 0), b2, voffB); PG8_STAGE(PG8_SB(0, 1), b2 + hstepB, voffB); PG8_STAGE(PG8_SA(0, 0), a2, voffA);
;             PG8_WAIT_V(8); PG8_WAIT_L(0); PG8_BAR; PG8_MMA(1, 0, At, B0); PG8_MMA(1, 1, At, B1); PG8_BAR; PG8_SCHED;
.LBB1_113:
	s_add_u32 s14, s64, 0xfff80080
	s_addc_u32 s15, s65, -1
	s_add_i32 s76, 0, 0x10000
	s_cmp_eq_u32 s45, 28
	s_cselect_b32 s69, s49, s15
	s_cselect_b32 s68, s61, s14
	s_cselect_b32 s67, s53, s44
	s_cselect_b32 s66, s74, s75
	s_add_i32 s77, 0, 0x14000
	v_add_u32_e32 v142, s76, v207
	v_add_u32_e32 v158, s77, v207
	ds_read_b128 v[130:133], v142
	ds_read_b128 v[134:137], v142 offset:1024
	ds_read_b128 v[138:141], v142 offset:2048
	ds_read_b128 v[142:145], v142 offset:3072
	ds_read_b128 v[146:149], v158
	ds_read_b128 v[150:153], v158 offset:1024
	ds_read_b128 v[154:157], v158 offset:2048
	ds_read_b128 v[158:161], v158 offset:3072
	v_lshl_add_u64 v[200:201], s[64:65], 0, v[186:187]
	s_add_i32 m0, s47, 0xc000
	ds_read_b128 v[162:165], v212
	ds_read_b128 v[166:169], v212 offset:1024
	ds_read_b128 v[170:173], v212 offset:2048
	ds_read_b128 v[174:177], v212 offset:3072
	ds_read_b128 v[188:191], v212 offset:4096
	ds_read_b128 v[192:195], v212 offset:5120
	ds_read_b128 v[196:199], v212 offset:6144
	ds_read_b128 v[214:217], v212 offset:7168
	global_load_lds_dwordx4 v[200:201], off
	v_lshl_add_u64 v[200:201], s[64:65], 0, v[184:185]
	s_add_i32 m0, s47, 0xe000
	s_nop 0
	global_load_lds_dwordx4 v[200:201], off
	s_waitcnt vmcnt(8)
	s_waitcnt lgkmcnt(0)
	s_barrier
	s_setprio 1
	v_mfma_f32_16x16x32_bf16 v[126:129], v[130:133], v[162:165], v[126:129]
	v_mfma_f32_16x16x32_bf16 v[122:125], v[138:141], v[162:165], v[122:125]
	v_mfma_f32_16x16x32_bf16 v[110:113], v[130:133], v[170:173], v[110:113]
	v_mfma_f32_16x16x32_bf16 v[106:109], v[138:141], v[170:173], v[106:109]
	v_mfma_f32_16x16x32_bf16 v[94:97], v[130:133], v[188:191], v[94:97]
	v_mfma_f32_16x16x32_bf16 v[90:93], v[138:141], v[188:191], v[90:93]
	v_mfma_f32_16x16x32_bf16 v[78:81], v[130:133], v[196:199], v[78:81]
	v_mfma_f32_16x16x32_bf16 v[74:77], v[138:141], v[196:199], v[74:77]
	v_mfma_f32_16x16x32_bf16 v[126:129], v[134:137], v[166:169], v[126:129]
	v_mfma_f32_16x16x32_bf16 v[122:125], v[142:145], v[166:169], v[122:125]
	v_mfma_f32_16x16x32_bf16 v[110:113], v[134:137], v[174:177], v[110:113]
	v_mfma_f32_16x16x32_bf16 v[106:109], v[142:145], v[174:177], v[106:109]
	v_mfma_f32_16x16x32_bf16 v[94:97], v[134:137], v[192:195], v[94:97]
	v_mfma_f32_16x16x32_bf16 v[90:93], v[142:145], v[192:195], v[90:93]
	v_mfma_f32_16x16x32_bf16 v[78:81], v[134:137], v[214:217], v[78:81]
	v_mfma_f32_16x16x32_bf16 v[74:77], v[142:145], v[214:217], v[74:77]
	v_mfma_f32_16x16x32_bf16 v[118:121], v[146:149], v[162:165], v[118:121]
	v_mfma_f32_16x16x32_bf16 v[114:117], v[154:157], v[162:165], v[114:117]
	v_mfma_f32_16x16x32_bf16 v[102:105], v[146:149], v[170:173], v[102:105]
	v_mfma_f32_16x16x32_bf16 v[98:101], v[154:157], v[170:173], v[98:101]
	v_mfma_f32_16x16x32_bf16 v[86:89], v[146:149], v[188:191], v[86:89]
	v_mfma_f32_16x16x32_bf16 v[82:85], v[154:157], v[188:191], v[82:85]
	v_mfma_f32_16x16x32_bf16 v[70:73], v[146:149], v[196:199], v[70:73]
	v_mfma_f32_16x16x32_bf16 v[66:69], v[154:157], v[196:199], v[66:69]
	v_mfma_f32_16x16x32_bf16 v[118:121], v[150:153], v[166:169], v[118:121]
	v_mfma_f32_16x16x32_bf16 v[114:117], v[158:161], v[166:169], v[114:117]
	v_mfma_f32_16x16x32_bf16 v[102:105], v[150:153], v[174:177], v[102:105]
	v_mfma_f32_16x16x32_bf16 v[98:101], v[158:161], v[174:177], v[98:101]
	v_mfma_f32_16x16x32_bf16 v[86:89], v[150:153], v[192:195], v[86:89]
	v_mfma_f32_16x16x32_bf16 v[82:85], v[158:161], v[192:195], v[82:85]
	v_mfma_f32_16x16x32_bf16 v[70:73], v[150:153], v[214:217], v[70:73]
	v_mfma_f32_16x16x32_bf16 v[66:69], v[158:161], v[214:217], v[66:69]
	s_setprio 0
	s_barrier
	s_add_i32 s14, s76, s46
	v_lshl_add_u64 v[200:201], s[66:67], 0, v[0:1]
	s_mov_b32 m0, s14
	ds_read_b128 v[162:165], v212 offset:16384
	ds_read_b128 v[166:169], v212 offset:17408
	ds_read_b128 v[170:173], v212 offset:18432
	ds_read_b128 v[174:177], v212 offset:19456
	ds_read_b128 v[188:191], v212 offset:20480
	ds_read_b128 v[192:195], v212 offset:21504
	ds_read_b128 v[196:199], v212 offset:22528
	ds_read_b128 v[214:217], v212 offset:23552
	global_load_lds_dwordx4 v[200:201], off
	s_add_i32 m0, s14, 0x2000
	s_add_u32 s14, s66, 0x80000
	v_lshl_add_u64 v[204:205], s[66:67], 0, v[182:183]
	s_addc_u32 s15, s67, 0
	s_add_i32 s76, s77, s46
	global_load_lds_dwordx4 v[204:205], off
	v_lshl_add_u64 v[218:219], s[14:15], 0, v[0:1]
	s_mov_b32 m0, s76
	v_lshl_add_u64 v[220:221], s[68:69], 0, v[180:181]
	global_load_lds_dwordx4 v[218:219], off
	v_lshl_add_u64 v[218:219], s[14:15], 0, v[182:183]
	s_add_i32 m0, s76, 0x2000
	s_nop 0
	global_load_lds_dwordx4 v[218:219], off
	v_lshl_add_u64 v[218:219], s[68:69], 0, v[178:179]
	s_mov_b32 m0, s47
	s_nop 0
	global_load_lds_dwordx4 v[218:219], off
	s_mov_b32 m0, s63
	s_nop 0
	global_load_lds_dwordx4 v[220:221], off
	s_waitcnt vmcnt(8)
	s_waitcnt lgkmcnt(0)
	s_barrier
; #define PG8_STAGE(bufoff, gbase, voff) do { _Pragma("unroll") for (int _i = 0; _i < 2; ++_i) \
;         __builtin_amdgcn_global_load_lds((const unsigned*)((const char*)(gbase) + (voff)[_i]), (LAS unsigned*)(lds + (bufoff) + ldsw + _i * 8192), 16, 0, 0); } while (0)
; #define PG8_LDA(dst, b, h) do { _Pragma("unroll") for (int m = 0; m < 4; ++m) _Pragma("unroll") for (int k = 0; k < 2; ++k) dst[m][k] = *(const LAS bf16x8*)(lds + PG8_SA(b, h) + aoff + m * 2048 + k * 1024); } while (0)
; #define PG8_LDB(dst, b, h) do { _Pragma("unroll") for (int n = 0; n < 2; ++n) _Pragma("unroll") for (int k = 0; k < 2; ++k) dst[n][k] = *(const LAS bf16x8*)(lds + PG8_SB(b, h) + boff + n * 2048 + k * 1024); } while (0)
; #define PG8_MMA(ai, bj, At, Bt) do { __builtin_amdgcn_s_setprio(1); _Pragma("unroll") for (int m = 0; m < 4; ++m) _Pragma("unroll") for (int n = 0; n < 2; ++n) _Pragma("unroll") for (int k = 0; k < 2; ++k) \
;         acc[ai][bj][m][n] = __builtin_amdgcn_mfma_f32_16x16x32_bf16(Bt[n][k], At[m][k], acc[ai][bj][m][n], 0, 0, 0); __builtin_amdgcn_s_setprio(0); } while (0)
; #define PG8_WAIT_V(n) asm volatile("s_waitcnt vmcnt(" #n ")" ::: "memory")
; #define PG8_WAIT_L(n) asm volatile("s_waitcnt lgkmcnt(" #n ")" ::: "memory")
; #define PG8_BAR __builtin_amdgcn_s_barrier()
; #define PG8_SCHED __builtin_amdgcn_sched_barrier(0)
; template <class Epi, class Sched>
; __device__ __forceinline__ void gemm_phase(LAS unsigned char* lds, const Gemm g, const Sched& S, const Epi& E, const int tid) {
;     ...
;             PG8_WAIT_V(8); PG8_WAIT_L(0); PG8_BAR; PG8_MMA(1, 0, At, B0); PG8_MMA(1, 1, At, B1); PG8_BAR; PG8_SCHED;
;             PG8_LDB(B0, 1, 0); PG8_LDB(B1, 1, 1); PG8_SCHED; PG8_LDA(At, 1, 0); PG8_STAGE(PG8_SA(0, 1), a2 + hstepA, voffA);
;             PG8_WAIT_V(8); PG8_WAIT_L(0); PG8_BAR; PG8_MMA(0, 0, At, B0); PG8_MMA(0, 1, At, B1); PG8_BAR; PG8_SCHED;
	s_setprio 1
	v_mfma_f32_16x16x32_bf16 v[62:65], v[130:133], v[162:165], v[62:65]
	v_mfma_f32_16x16x32_bf16 v[58:61], v[138:141], v[162:165], v[58:61]
	v_mfma_f32_16x16x32_bf16 v[46:49], v[130:133], v[170:173], v[46:49]
	v_mfma_f32_16x16x32_bf16 v[42:45], v[138:141], v[170:173], v[42:45]
	v_mfma_f32_16x16x32_bf16 v[30:33], v[130:133], v[188:191], v[30:33]
	v_mfma_f32_16x16x32_bf16 v[26:29], v[138:141], v[188:191], v[26:29]
	v_mfma_f32_16x16x32_bf16 v[14:17], v[130:133], v[196:199], v[14:17]
	v_mfma_f32_16x16x32_bf16 v[10:13], v[138:141], v[196:199], v[10:13]
	v_mfma_f32_16x16x32_bf16 v[62:65], v[134:137], v[166:169], v[62:65]
	v_mfma_f32_16x16x32_bf16 v[58:61], v[142:145], v[166:169], v[58:61]
	v_mfma_f32_16x16x32_bf16 v[46:49], v[134:137], v[174:177], v[46:49]
	v_mfma_f32_16x16x32_bf16 v[42:45], v[142:145], v[174:177], v[42:45]
	v_mfma_f32_16x16x32_bf16 v[30:33], v[134:137], v[192:195], v[30:33]
	v_mfma_f32_16x16x32_bf16 v[26:29], v[142:145], v[192:195], v[26:29]
	v_mfma_f32_16x16x32_bf16 v[14:17], v[134:137], v[214:217], v[14:17]
	v_mfma_f32_16x16x32_bf16 v[10:13], v[142:145], v[214:217], v[10:13]
	v_mfma_f32_16x16x32_bf16 v[54:57], v[146:149], v[162:165], v[54:57]
	v_mfma_f32_16x16x32_bf16 v[50:53], v[154:157], v[162:165], v[50:53]
	v_mfma_f32_16x16x32_bf16 v[38:41], v[146:149], v[170:173], v[38:41]
	v_mfma_f32_16x16x32_bf16 v[34:37], v[154:157], v[170:173], v[34:37]
	v_mfma_f32_16x16x32_bf16 v[22:25], v[146:149], v[188:191], v[22:25]
	v_mfma_f32_16x16x32_bf16 v[18:21], v[154:157], v[188:191], v[18:21]
	v_mfma_f32_16x16x32_bf16 v[6:9], v[146:149], v[196:199], v[6:9]
	v_mfma_f32_16x16x32_bf16 v[2:5], v[154:157], v[196:199], v[2:5]
	v_mfma_f32_16x16x32_bf16 v[54:57], v[150:153], v[166:169], v[54:57]
	v_mfma_f32_16x16x32_bf16 v[50:53], v[158:161], v[166:169], v[50:53]
	v_mfma_f32_16x16x32_bf16 v[38:41], v[150:153], v[174:177], v[38:41]
	v_mfma_f32_16x16x32_bf16 v[34:37], v[158:161], v[174:177], v[34:37]
	v_mfma_f32_16x16x32_bf16 v[22:25], v[150:153], v[192:195], v[22:25]
	v_mfma_f32_16x16x32_bf16 v[18:21], v[158:161], v[192:195], v[18:21]
	v_mfma_f32_16x16x32_bf16 v[6:9], v[150:153], v[214:217], v[6:9]
	v_mfma_f32_16x16x32_bf16 v[2:5], v[158:161], v[214:217], v[2:5]
	s_setprio 0
	s_barrier
	s_add_i32 s76, 0, 0x18000
	s_add_i32 s77, 0, 0x1c000
	v_add_u32_e32 v142, s76, v207
	v_add_u32_e32 v158, s77, v207
	ds_read_b128 v[130:133], v142
	ds_read_b128 v[134:137], v142 offset:1024
	ds_read_b128 v[138:141], v142 offset:2048
	ds_read_b128 v[142:145], v142 offset:3072
	ds_read_b128 v[146:149], v158
	ds_read_b128 v[150:153], v158 offset:1024
	ds_read_b128 v[154:157], v158 offset:2048
	ds_read_b128 v[158:161], v158 offset:3072
	s_add_u32 s14, s68, 0x80000
	s_addc_u32 s15, s69, 0
	s_mov_b32 m0, s84
	v_lshl_add_u64 v[222:223], s[14:15], 0, v[178:179]
	ds_read_b128 v[162:165], v212 offset:32768
	ds_read_b128 v[166:169], v212 offset:33792
	ds_read_b128 v[170:173], v212 offset:34816
	ds_read_b128 v[174:177], v212 offset:35840
	ds_read_b128 v[188:191], v212 offset:36864
	ds_read_b128 v[192:195], v212 offset:37888
	ds_read_b128 v[196:199], v212 offset:38912
	ds_read_b128 v[214:217], v212 offset:39936
	global_load_lds_dwordx4 v[222:223], off
	v_lshl_add_u64 v[222:223], s[14:15], 0, v[180:181]
	s_mov_b32 m0, s85
	s_nop 0
	global_load_lds_dwordx4 v[222:223], off
	s_waitcnt vmcnt(8)
	s_waitcnt lgkmcnt(0)
	s_barrier
	s_setprio 1
	v_mfma_f32_16x16x32_bf16 v[126:129], v[130:133], v[162:165], v[126:129]
	v_mfma_f32_16x16x32_bf16 v[122:125], v[138:141], v[162:165], v[122:125]
	v_mfma_f32_16x16x32_bf16 v[110:113], v[130:133], v[170:173], v[110:113]
	v_mfma_f32_16x16x32_bf16 v[106:109], v[138:141], v[170:173], v[106:109]
	v_mfma_f32_16x16x32_bf16 v[94:97], v[130:133], v[188:191], v[94:97]
	v_mfma_f32_16x16x32_bf16 v[90:93], v[138:141], v[188:191], v[90:93]
	v_mfma_f32_16x16x32_bf16 v[78:81], v[130:133], v[196:199], v[78:81]
	v_mfma_f32_16x16x32_bf16 v[74:77], v[138:141], v[196:199], v[74:77]
	v_mfma_f32_16x16x32_bf16 v[126:129], v[134:137], v[166:169], v[126:129]
	v_mfma_f32_16x16x32_bf16 v[122:125], v[142:145], v[166:169], v[122:125]
	v_mfma_f32_16x16x32_bf16 v[110:113], v[134:137], v[174:177], v[110:113]
	v_mfma_f32_16x16x32_bf16 v[106:109], v[142:145], v[174:177], v[106:109]
	v_mfma_f32_16x16x32_bf16 v[94:97], v[134:137], v[192:195], v[94:97]
	v_mfma_f32_16x16x32_bf16 v[90:93], v[142:145], v[192:195], v[90:93]
	v_mfma_f32_16x16x32_bf16 v[78:81], v[134:137], v[214:217], v[78:81]
	v_mfma_f32_16x16x32_bf16 v[74:77], v[142:145], v[214:217], v[74:77]
	v_mfma_f32_16x16x32_bf16 v[118:121], v[146:149], v[162:165], v[118:121]
	v_mfma_f32_16x16x32_bf16 v[114:117], v[154:157], v[162:165], v[114:117]
	v_mfma_f32_16x16x32_bf16 v[102:105], v[146:149], v[170:173], v[102:105]
	v_mfma_f32_16x16x32_bf16 v[98:101], v[154:157], v[170:173], v[98:101]
	v_mfma_f32_16x16x32_bf16 v[86:89], v[146:149], v[188:191], v[86:89]
	v_mfma_f32_16x16x32_bf16 v[82:85], v[154:157], v[188:191], v[82:85]
	v_mfma_f32_16x16x32_bf16 v[70:73], v[146:149], v[196:199], v[70:73]
	v_mfma_f32_16x16x32_bf16 v[66:69], v[154:157], v[196:199], v[66:69]
	v_mfma_f32_16x16x32_bf16 v[118:121], v[150:153], v[166:169], v[118:121]
	v_mfma_f32_16x16x32_bf16 v[114:117], v[158:161], v[166:169], v[114:117]
	v_mfma_f32_16x16x32_bf16 v[102:105], v[150:153], v[174:177], v[102:105]
	v_mfma_f32_16x16x32_bf16 v[98:101], v[158:161], v[174:177], v[98:101]
	v_mfma_f32_16x16x32_bf16 v[86:89], v[150:153], v[192:195], v[86:89]
	v_mfma_f32_16x16x32_bf16 v[82:85], v[158:161], v[192:195], v[82:85]
	v_mfma_f32_16x16x32_bf16 v[70:73], v[150:153], v[214:217], v[70:73]
	v_mfma_f32_16x16x32_bf16 v[66:69], v[158:161], v[214:217], v[66:69]
	s_setprio 0
	s_barrier
; #define PG8_STAGE(bufoff, gbase, voff) do { _Pragma("unroll") for (int _i = 0; _i < 2; ++_i) \
;         __builtin_amdgcn_global_load_lds((const unsigned*)((const char*)(gbase) + (voff)[_i]), (LAS unsigned*)(lds + (bufoff) + ldsw + _i * 8192), 16, 0, 0); } while (0)
; #define PG8_LDA(dst, b, h) do { _Pragma("unroll") for (int m = 0; m < 4; ++m) _Pragma("unroll") for (int k = 0; k < 2; ++k) dst[m][k] = *(const LAS bf16x8*)(lds + PG8_SA(b, h) + aoff + m * 2048 + k * 1024); } while (0)
; #define PG8_MMA(ai, bj, At, Bt) do { __builtin_amdgcn_s_setprio(1); _Pragma("unroll") for (int m = 0; m < 4; ++m) _Pragma("unroll") for (int n = 0; n < 2; ++n) _Pragma("unroll") for (int k = 0; k < 2; ++k) \
;         acc[ai][bj][m][n] = __builtin_amdgcn_mfma_f32_16x16x32_bf16(Bt[n][k], At[m][k], acc[ai][bj][m][n], 0, 0, 0); __builtin_amdgcn_s_setprio(0); } while (0)
; #define PG8_WAIT_V(n) asm volatile("s_waitcnt vmcnt(" #n ")" ::: "memory")
; #define PG8_WAIT_L(n) asm volatile("s_waitcnt lgkmcnt(" #n ")" ::: "memory")
; #define PG8_BAR __builtin_amdgcn_s_barrier()
; #define PG8_SCHED __builtin_amdgcn_sched_barrier(0)
; template <class Epi, class Sched>
; __device__ __forceinline__ void gemm_phase(LAS unsigned char* lds, const Gemm g, const Sched& S, const Epi& E, const int tid) {
;     ...
;             PG8_LDA(At, 1, 1); PG8_STAGE(PG8_SB(1, 0), b3, voffB); PG8_STAGE(PG8_SB(1, 1), b3 + hstepB, voffB); PG8_STAGE(PG8_SA(1, 0), a3, voffA);
;             PG8_WAIT_V(8); PG8_WAIT_L(0); PG8_BAR; PG8_MMA(1, 0, At, B0); PG8_MMA(1, 1, At, B1); PG8_BAR; PG8_SCHED;
;         }
;         if (wr == 0) PG8_BAR;
	s_add_i32 s14, s76, s46
	v_lshl_add_u64 v[200:201], v[200:201], 0, s[90:91]
	s_mov_b32 m0, s14
	ds_read_b128 v[162:165], v212 offset:49152
	ds_read_b128 v[166:169], v212 offset:50176
	ds_read_b128 v[170:173], v212 offset:51200
	ds_read_b128 v[174:177], v212 offset:52224
	ds_read_b128 v[188:191], v212 offset:53248
	ds_read_b128 v[192:195], v212 offset:54272
	ds_read_b128 v[196:199], v212 offset:55296
	ds_read_b128 v[214:217], v212 offset:56320
	global_load_lds_dwordx4 v[200:201], off
	s_add_i32 m0, s14, 0x2000
	s_add_u32 s14, s66, 0x80080
	v_lshl_add_u64 v[200:201], v[204:205], 0, s[90:91]
	s_addc_u32 s15, s67, 0
	s_add_i32 s66, s77, s46
	global_load_lds_dwordx4 v[200:201], off
	v_lshl_add_u64 v[200:201], s[14:15], 0, v[0:1]
	s_mov_b32 m0, s66
	s_nop 0
	global_load_lds_dwordx4 v[200:201], off
	v_lshl_add_u64 v[200:201], s[14:15], 0, v[182:183]
	s_add_i32 m0, s66, 0x2000
	s_nop 0
	global_load_lds_dwordx4 v[200:201], off
	v_lshl_add_u64 v[200:201], v[218:219], 0, s[90:91]
	s_mov_b32 m0, s72
	s_nop 0
	global_load_lds_dwordx4 v[200:201], off
	v_lshl_add_u64 v[200:201], v[220:221], 0, s[90:91]
	s_mov_b32 m0, s73
	s_nop 0
	global_load_lds_dwordx4 v[200:201], off
	s_waitcnt vmcnt(8)
	s_waitcnt lgkmcnt(0)
	s_barrier
	s_setprio 1
	v_mfma_f32_16x16x32_bf16 v[62:65], v[130:133], v[162:165], v[62:65]
	v_mfma_f32_16x16x32_bf16 v[58:61], v[138:141], v[162:165], v[58:61]
	v_mfma_f32_16x16x32_bf16 v[46:49], v[130:133], v[170:173], v[46:49]
	v_mfma_f32_16x16x32_bf16 v[42:45], v[138:141], v[170:173], v[42:45]
	v_mfma_f32_16x16x32_bf16 v[30:33], v[130:133], v[188:191], v[30:33]
	v_mfma_f32_16x16x32_bf16 v[26:29], v[138:141], v[188:191], v[26:29]
	v_mfma_f32_16x16x32_bf16 v[14:17], v[130:133], v[196:199], v[14:17]
	v_mfma_f32_16x16x32_bf16 v[10:13], v[138:141], v[196:199], v[10:13]
	v_mfma_f32_16x16x32_bf16 v[62:65], v[134:137], v[166:169], v[62:65]
	v_mfma_f32_16x16x32_bf16 v[58:61], v[142:145], v[166:169], v[58:61]
	v_mfma_f32_16x16x32_bf16 v[46:49], v[134:137], v[174:177], v[46:49]
	v_mfma_f32_16x16x32_bf16 v[42:45], v[142:145], v[174:177], v[42:45]
	v_mfma_f32_16x16x32_bf16 v[30:33], v[134:137], v[192:195], v[30:33]
	v_mfma_f32_16x16x32_bf16 v[26:29], v[142:145], v[192:195], v[26:29]
	v_mfma_f32_16x16x32_bf16 v[14:17], v[134:137], v[214:217], v[14:17]
	v_mfma_f32_16x16x32_bf16 v[10:13], v[142:145], v[214:217], v[10:13]
	v_mfma_f32_16x16x32_bf16 v[54:57], v[146:149], v[162:165], v[54:57]
	v_mfma_f32_16x16x32_bf16 v[50:53], v[154:157], v[162:165], v[50:53]
	v_mfma_f32_16x16x32_bf16 v[38:41], v[146:149], v[170:173], v[38:41]
	v_mfma_f32_16x16x32_bf16 v[34:37], v[154:157], v[170:173], v[34:37]
	v_mfma_f32_16x16x32_bf16 v[22:25], v[146:149], v[188:191], v[22:25]
	v_mfma_f32_16x16x32_bf16 v[18:21], v[154:157], v[188:191], v[18:21]
	v_mfma_f32_16x16x32_bf16 v[6:9], v[146:149], v[196:199], v[6:9]
	v_mfma_f32_16x16x32_bf16 v[2:5], v[154:157], v[196:199], v[2:5]
	v_mfma_f32_16x16x32_bf16 v[54:57], v[150:153], v[166:169], v[54:57]
	v_mfma_f32_16x16x32_bf16 v[50:53], v[158:161], v[166:169], v[50:53]
	v_mfma_f32_16x16x32_bf16 v[38:41], v[150:153], v[174:177], v[38:41]
	v_mfma_f32_16x16x32_bf16 v[34:37], v[158:161], v[174:177], v[34:37]
	v_mfma_f32_16x16x32_bf16 v[22:25], v[150:153], v[192:195], v[22:25]
	v_mfma_f32_16x16x32_bf16 v[18:21], v[158:161], v[192:195], v[18:21]
	v_mfma_f32_16x16x32_bf16 v[6:9], v[150:153], v[214:217], v[6:9]
	v_mfma_f32_16x16x32_bf16 v[2:5], v[158:161], v[214:217], v[2:5]
	s_setprio 0
	s_barrier
	s_add_i32 s45, s45, 2
	s_add_u32 s75, s75, 0x100
	s_addc_u32 s44, s44, 0
	s_add_u32 s64, s64, 0x100
	s_addc_u32 s65, s65, 0
	s_cmp_gt_u32 s45, 29
	s_cbranch_scc0 .LBB1_113
	s_and_b64 vcc, exec, s[42:43]
	s_cbranch_vccz .LBB1_116
	s_barrier

; #define PG8_STAGE(bufoff, gbase, voff) do { _Pragma("unroll") for (int _i = 0; _i < 2; ++_i) \
;         __builtin_amdgcn_global_load_lds((const unsigned*)((const char*)(gbase) + (voff)[_i]), (LAS unsigned*)(lds + (bufoff) + ldsw + _i * 8192), 16, 0, 0); } while (0)
; #define PG8_LDA(dst, b, h) do { _Pragma("unroll") for (int m = 0; m < 4; ++m) _Pragma("unroll") for (int k = 0; k < 2; ++k) dst[m][k] = *(const LAS bf16x8*)(lds + PG8_SA(b, h) + aoff + m * 2048 + k * 1024); } while (0)
; #define PG8_LDB(dst, b, h) do { _Pragma("unroll") for (int n = 0; n < 2; ++n) _Pragma("unroll") for (int k = 0; k < 2; ++k) dst[n][k] = *(const LAS bf16x8*)(lds + PG8_SB(b, h) + boff + n * 2048 + k * 1024); } while (0)
; #define PG8_MMA(ai, bj, At, Bt) do { __builtin_amdgcn_s_setprio(1); _Pragma("unroll") for (int m = 0; m < 4; ++m) _Pragma("unroll") for (int n = 0; n < 2; ++n) _Pragma("unroll") for (int k = 0; k < 2; ++k) \
;         acc[ai][bj][m][n] = __builtin_amdgcn_mfma_f32_16x16x32_bf16(Bt[n][k], At[m][k], acc[ai][bj][m][n], 0, 0, 0); __builtin_amdgcn_s_setprio(0); } while (0)
; template <class Epi, class Sched>
; __device__ __forceinline__ void gemm_phase(LAS unsigned char* lds, const Gemm g, const Sched& S, const Epi& E, const int tid) {
;     ...
;         const bool has_next = S.next(ui + 1, nxt);
;         const char* nA = has_next ? (const char*)g.A + (size_t)nxt.pm * tstepA + (size_t)nxt.aoff * 2 : cA; const char* nB = has_next ? (const char*)g.Bt + (size_t)nxt.pn * tstepB : cB;
;         for (int t = 0; t < nt; t += 2) {
;             const bool last = (t == nt - 2);
;             const char* a1 = cA + (size_t)(t + 1) * kstep;
;             const char* a2 = last ? nA : cA + (size_t)(t + 2) * kstep; const char* b2 = last ? nB : cB + (size_t)(t + 2) * kstep;
;             const char* a3 = a2 + kstep; const char* b3 = b2 + kstep;
;             PG8_LDB(B0, 0, 0); PG8_LDB(B1, 0, 1); PG8_SCHED; PG8_LDA(At, 0, 0); PG8_STAGE(PG8_SA(1, 1), a1 + hstepA, voffA);
;             PG8_WAIT_V(8); PG8_WAIT_L(0); PG8_BAR; PG8_MMA(0, 0, At, B0); PG8_MMA(0, 1, At, B1); PG8_BAR; PG8_SCHED;
;             PG8_LDA(At, 0, 1); PG8_STAGE(PG8_SB(0, 0), b2, voffB); PG8_STAGE(PG8_SB(0, 1), b2 + hstepB, voffB); PG8_STAGE(PG8_SA(0, 0), a2, voffA);
;             PG8_WAIT_V(8); PG8_WAIT_L(0); PG8_BAR; PG8_MMA(1, 0, At, B0); PG8_MMA(1, 1, At, B1); PG8_BAR; PG8_SCHED;
.LBB1_156:
	s_add_u32 s40, s60, 0x100
	s_addc_u32 s41, s61, 0
	s_add_i32 s49, 0, 0x10000
	s_cmp_eq_u32 s45, 12
	s_cselect_b32 s65, s57, s41
	s_cselect_b32 s64, s56, s40
	s_cselect_b32 s63, s14, s44
	s_cselect_b32 s62, s15, s43
	s_add_i32 s53, 0, 0x14000
	v_add_u32_e32 v142, s49, v231
	v_add_u32_e32 v158, s53, v231
	ds_read_b128 v[130:133], v142
	ds_read_b128 v[134:137], v142 offset:1024
	ds_read_b128 v[138:141], v142 offset:2048
	ds_read_b128 v[142:145], v142 offset:3072
	ds_read_b128 v[146:149], v158
	ds_read_b128 v[150:153], v158 offset:1024
	ds_read_b128 v[154:157], v158 offset:2048
	ds_read_b128 v[158:161], v158 offset:3072
	v_lshl_add_u64 v[194:195], s[60:61], 0, v[214:215]
	s_add_i32 m0, s47, 0xc000
	ds_read_b128 v[162:165], v236
	ds_read_b128 v[166:169], v236 offset:1024
	ds_read_b128 v[170:173], v236 offset:2048
	ds_read_b128 v[174:177], v236 offset:3072
	ds_read_b128 v[178:181], v236 offset:4096
	ds_read_b128 v[182:185], v236 offset:5120
	ds_read_b128 v[186:189], v236 offset:6144
	ds_read_b128 v[190:193], v236 offset:7168
	global_load_lds_dwordx4 v[194:195], off
	v_lshl_add_u64 v[194:195], s[60:61], 0, v[212:213]
	s_add_i32 m0, s47, 0xe000
	s_nop 0
	global_load_lds_dwordx4 v[194:195], off
	s_waitcnt vmcnt(8)
	s_waitcnt lgkmcnt(0)
	s_barrier
	s_setprio 1
	v_mfma_f32_16x16x32_bf16 v[126:129], v[130:133], v[162:165], v[126:129]
	v_mfma_f32_16x16x32_bf16 v[122:125], v[138:141], v[162:165], v[122:125]
	v_mfma_f32_16x16x32_bf16 v[118:121], v[130:133], v[170:173], v[118:121]
	v_mfma_f32_16x16x32_bf16 v[114:117], v[138:141], v[170:173], v[114:117]
	v_mfma_f32_16x16x32_bf16 v[110:113], v[130:133], v[178:181], v[110:113]
	v_mfma_f32_16x16x32_bf16 v[106:109], v[138:141], v[178:181], v[106:109]
	v_mfma_f32_16x16x32_bf16 v[102:105], v[130:133], v[186:189], v[102:105]
	v_mfma_f32_16x16x32_bf16 v[98:101], v[138:141], v[186:189], v[98:101]
	v_mfma_f32_16x16x32_bf16 v[126:129], v[134:137], v[166:169], v[126:129]
	v_mfma_f32_16x16x32_bf16 v[122:125], v[142:145], v[166:169], v[122:125]
	v_mfma_f32_16x16x32_bf16 v[118:121], v[134:137], v[174:177], v[118:121]
	v_mfma_f32_16x16x32_bf16 v[114:117], v[142:145], v[174:177], v[114:117]
	v_mfma_f32_16x16x32_bf16 v[110:113], v[134:137], v[182:185], v[110:113]
	v_mfma_f32_16x16x32_bf16 v[106:109], v[142:145], v[182:185], v[106:109]
	v_mfma_f32_16x16x32_bf16 v[102:105], v[134:137], v[190:193], v[102:105]
	v_mfma_f32_16x16x32_bf16 v[98:101], v[142:145], v[190:193], v[98:101]
	v_mfma_f32_16x16x32_bf16 v[94:97], v[146:149], v[162:165], v[94:97]
	v_mfma_f32_16x16x32_bf16 v[90:93], v[154:157], v[162:165], v[90:93]
	v_mfma_f32_16x16x32_bf16 v[86:89], v[146:149], v[170:173], v[86:89]
	v_mfma_f32_16x16x32_bf16 v[82:85], v[154:157], v[170:173], v[82:85]
	v_mfma_f32_16x16x32_bf16 v[78:81], v[146:149], v[178:181], v[78:81]
	v_mfma_f32_16x16x32_bf16 v[74:77], v[154:157], v[178:181], v[74:77]
	v_mfma_f32_16x16x32_bf16 v[70:73], v[146:149], v[186:189], v[70:73]
	v_mfma_f32_16x16x32_bf16 v[66:69], v[154:157], v[186:189], v[66:69]
	v_mfma_f32_16x16x32_bf16 v[94:97], v[150:153], v[166:169], v[94:97]
	v_mfma_f32_16x16x32_bf16 v[90:93], v[158:161], v[166:169], v[90:93]
	v_mfma_f32_16x16x32_bf16 v[86:89], v[150:153], v[174:177], v[86:89]
	v_mfma_f32_16x16x32_bf16 v[82:85], v[158:161], v[174:177], v[82:85]
	v_mfma_f32_16x16x32_bf16 v[78:81], v[150:153], v[182:185], v[78:81]
	v_mfma_f32_16x16x32_bf16 v[74:77], v[158:161], v[182:185], v[74:77]
	v_mfma_f32_16x16x32_bf16 v[70:73], v[150:153], v[190:193], v[70:73]
	v_mfma_f32_16x16x32_bf16 v[66:69], v[158:161], v[190:193], v[66:69]
	s_setprio 0
	s_barrier
	s_add_i32 s49, s49, s46
	v_lshl_add_u64 v[194:195], s[62:63], 0, v[206:207]
	s_mov_b32 m0, s49
	ds_read_b128 v[162:165], v236 offset:16384
	ds_read_b128 v[166:169], v236 offset:17408
	ds_read_b128 v[170:173], v236 offset:18432
	ds_read_b128 v[174:177], v236 offset:19456
	ds_read_b128 v[178:181], v236 offset:20480
	ds_read_b128 v[182:185], v236 offset:21504
	ds_read_b128 v[186:189], v236 offset:22528
	ds_read_b128 v[190:193], v236 offset:23552
	global_load_lds_dwordx4 v[194:195], off
	s_add_i32 m0, s49, 0x2000
	s_add_u32 s60, s62, 0x40000
	v_lshl_add_u64 v[196:197], s[62:63], 0, v[210:211]
	s_addc_u32 s61, s63, 0
	s_add_i32 s49, s53, s46
	global_load_lds_dwordx4 v[196:197], off
	v_lshl_add_u64 v[198:199], s[60:61], 0, v[206:207]
	s_mov_b32 m0, s49
	v_lshl_add_u64 v[200:201], s[64:65], 0, v[208:209]
	global_load_lds_dwordx4 v[198:199], off
	v_lshl_add_u64 v[198:199], s[60:61], 0, v[210:211]
	s_add_i32 m0, s49, 0x2000
	s_nop 0
	global_load_lds_dwordx4 v[198:199], off
	v_lshl_add_u64 v[198:199], s[64:65], 0, v[204:205]
	s_mov_b32 m0, s47
	s_nop 0
	global_load_lds_dwordx4 v[198:199], off
	s_mov_b32 m0, s66
	s_nop 0
	global_load_lds_dwordx4 v[200:201], off
	s_waitcnt vmcnt(8)
	s_waitcnt lgkmcnt(0)
	s_barrier
; #define PG8_STAGE(bufoff, gbase, voff) do { _Pragma("unroll") for (int _i = 0; _i < 2; ++_i) \
;         __builtin_amdgcn_global_load_lds((const unsigned*)((const char*)(gbase) + (voff)[_i]), (LAS unsigned*)(lds + (bufoff) + ldsw + _i * 8192), 16, 0, 0); } while (0)
; #define PG8_LDA(dst, b, h) do { _Pragma("unroll") for (int m = 0; m < 4; ++m) _Pragma("unroll") for (int k = 0; k < 2; ++k) dst[m][k] = *(const LAS bf16x8*)(lds + PG8_SA(b, h) + aoff + m * 2048 + k * 1024); } while (0)
; #define PG8_LDB(dst, b, h) do { _Pragma("unroll") for (int n = 0; n < 2; ++n) _Pragma("unroll") for (int k = 0; k < 2; ++k) dst[n][k] = *(const LAS bf16x8*)(lds + PG8_SB(b, h) + boff + n * 2048 + k * 1024); } while (0)
; #define PG8_MMA(ai, bj, At, Bt) do { __builtin_amdgcn_s_setprio(1); _Pragma("unroll") for (int m = 0; m < 4; ++m) _Pragma("unroll") for (int n = 0; n < 2; ++n) _Pragma("unroll") for (int k = 0; k < 2; ++k) \
;         acc[ai][bj][m][n] = __builtin_amdgcn_mfma_f32_16x16x32_bf16(Bt[n][k], At[m][k], acc[ai][bj][m][n], 0, 0, 0); __builtin_amdgcn_s_setprio(0); } while (0)
; #define PG8_WAIT_V(n) asm volatile("s_waitcnt vmcnt(" #n ")" ::: "memory")
; #define PG8_WAIT_L(n) asm volatile("s_waitcnt lgkmcnt(" #n ")" ::: "memory")
; #define PG8_BAR __builtin_amdgcn_s_barrier()
; #define PG8_SCHED __builtin_amdgcn_sched_barrier(0)
; template <class Epi, class Sched>
; __device__ __forceinline__ void gemm_phase(LAS unsigned char* lds, const Gemm g, const Sched& S, const Epi& E, const int tid) {
;     ...
;             PG8_WAIT_V(8); PG8_WAIT_L(0); PG8_BAR; PG8_MMA(1, 0, At, B0); PG8_MMA(1, 1, At, B1); PG8_BAR; PG8_SCHED;
;             PG8_LDB(B0, 1, 0); PG8_LDB(B1, 1, 1); PG8_SCHED; PG8_LDA(At, 1, 0); PG8_STAGE(PG8_SA(0, 1), a2 + hstepA, voffA);
;             PG8_WAIT_V(8); PG8_WAIT_L(0); PG8_BAR; PG8_MMA(0, 0, At, B0); PG8_MMA(0, 1, At, B1); PG8_BAR; PG8_SCHED;
	s_setprio 1
	v_mfma_f32_16x16x32_bf16 v[62:65], v[130:133], v[162:165], v[62:65]
	v_mfma_f32_16x16x32_bf16 v[58:61], v[138:141], v[162:165], v[58:61]
	v_mfma_f32_16x16x32_bf16 v[54:57], v[130:133], v[170:173], v[54:57]
	v_mfma_f32_16x16x32_bf16 v[50:53], v[138:141], v[170:173], v[50:53]
	v_mfma_f32_16x16x32_bf16 v[46:49], v[130:133], v[178:181], v[46:49]
	v_mfma_f32_16x16x32_bf16 v[42:45], v[138:141], v[178:181], v[42:45]
	v_mfma_f32_16x16x32_bf16 v[38:41], v[130:133], v[186:189], v[38:41]
	v_mfma_f32_16x16x32_bf16 v[34:37], v[138:141], v[186:189], v[34:37]
	v_mfma_f32_16x16x32_bf16 v[62:65], v[134:137], v[166:169], v[62:65]
	v_mfma_f32_16x16x32_bf16 v[58:61], v[142:145], v[166:169], v[58:61]
	v_mfma_f32_16x16x32_bf16 v[54:57], v[134:137], v[174:177], v[54:57]
	v_mfma_f32_16x16x32_bf16 v[50:53], v[142:145], v[174:177], v[50:53]
	v_mfma_f32_16x16x32_bf16 v[46:49], v[134:137], v[182:185], v[46:49]
	v_mfma_f32_16x16x32_bf16 v[42:45], v[142:145], v[182:185], v[42:45]
	v_mfma_f32_16x16x32_bf16 v[38:41], v[134:137], v[190:193], v[38:41]
	v_mfma_f32_16x16x32_bf16 v[34:37], v[142:145], v[190:193], v[34:37]
	v_mfma_f32_16x16x32_bf16 v[30:33], v[146:149], v[162:165], v[30:33]
	v_mfma_f32_16x16x32_bf16 v[26:29], v[154:157], v[162:165], v[26:29]
	v_mfma_f32_16x16x32_bf16 v[22:25], v[146:149], v[170:173], v[22:25]
	v_mfma_f32_16x16x32_bf16 v[18:21], v[154:157], v[170:173], v[18:21]
	v_mfma_f32_16x16x32_bf16 v[14:17], v[146:149], v[178:181], v[14:17]
	v_mfma_f32_16x16x32_bf16 v[10:13], v[154:157], v[178:181], v[10:13]
	v_mfma_f32_16x16x32_bf16 v[6:9], v[146:149], v[186:189], v[6:9]
	v_mfma_f32_16x16x32_bf16 v[2:5], v[154:157], v[186:189], v[2:5]
	v_mfma_f32_16x16x32_bf16 v[30:33], v[150:153], v[166:169], v[30:33]
	v_mfma_f32_16x16x32_bf16 v[26:29], v[158:161], v[166:169], v[26:29]
	v_mfma_f32_16x16x32_bf16 v[22:25], v[150:153], v[174:177], v[22:25]
	v_mfma_f32_16x16x32_bf16 v[18:21], v[158:161], v[174:177], v[18:21]
	v_mfma_f32_16x16x32_bf16 v[14:17], v[150:153], v[182:185], v[14:17]
	v_mfma_f32_16x16x32_bf16 v[10:13], v[158:161], v[182:185], v[10:13]
	v_mfma_f32_16x16x32_bf16 v[6:9], v[150:153], v[190:193], v[6:9]
	v_mfma_f32_16x16x32_bf16 v[2:5], v[158:161], v[190:193], v[2:5]
	s_setprio 0
	s_barrier
	s_add_i32 s49, 0, 0x18000
	s_add_i32 s53, 0, 0x1c000
	v_add_u32_e32 v142, s49, v231
	v_add_u32_e32 v158, s53, v231
	ds_read_b128 v[130:133], v142
	ds_read_b128 v[134:137], v142 offset:1024
	ds_read_b128 v[138:141], v142 offset:2048
	ds_read_b128 v[142:145], v142 offset:3072
	ds_read_b128 v[146:149], v158
	ds_read_b128 v[150:153], v158 offset:1024
	ds_read_b128 v[154:157], v158 offset:2048
	ds_read_b128 v[158:161], v158 offset:3072
	s_add_u32 s60, s64, 0x300000
	s_addc_u32 s61, s65, 0
	s_mov_b32 m0, s67
	v_lshl_add_u64 v[216:217], s[60:61], 0, v[204:205]
	ds_read_b128 v[162:165], v236 offset:32768
	ds_read_b128 v[166:169], v236 offset:33792
	ds_read_b128 v[170:173], v236 offset:34816
	ds_read_b128 v[174:177], v236 offset:35840
	ds_read_b128 v[178:181], v236 offset:36864
	ds_read_b128 v[182:185], v236 offset:37888
	ds_read_b128 v[186:189], v236 offset:38912
	ds_read_b128 v[190:193], v236 offset:39936
	global_load_lds_dwordx4 v[216:217], off
	v_lshl_add_u64 v[216:217], s[60:61], 0, v[208:209]
	s_mov_b32 m0, s68
	s_nop 0
	global_load_lds_dwordx4 v[216:217], off
	s_waitcnt vmcnt(8)
	s_waitcnt lgkmcnt(0)
	s_barrier
	s_setprio 1
	v_mfma_f32_16x16x32_bf16 v[126:129], v[130:133], v[162:165], v[126:129]
	v_mfma_f32_16x16x32_bf16 v[122:125], v[138:141], v[162:165], v[122:125]
	v_mfma_f32_16x16x32_bf16 v[118:121], v[130:133], v[170:173], v[118:121]
	v_mfma_f32_16x16x32_bf16 v[114:117], v[138:141], v[170:173], v[114:117]
	v_mfma_f32_16x16x32_bf16 v[110:113], v[130:133], v[178:181], v[110:113]
	v_mfma_f32_16x16x32_bf16 v[106:109], v[138:141], v[178:181], v[106:109]
	v_mfma_f32_16x16x32_bf16 v[102:105], v[130:133], v[186:189], v[102:105]
	v_mfma_f32_16x16x32_bf16 v[98:101], v[138:141], v[186:189], v[98:101]
	v_mfma_f32_16x16x32_bf16 v[126:129], v[134:137], v[166:169], v[126:129]
	v_mfma_f32_16x16x32_bf16 v[122:125], v[142:145], v[166:169], v[122:125]
	v_mfma_f32_16x16x32_bf16 v[118:121], v[134:137], v[174:177], v[118:121]
	v_mfma_f32_16x16x32_bf16 v[114:117], v[142:145], v[174:177], v[114:117]
	v_mfma_f32_16x16x32_bf16 v[110:113], v[134:137], v[182:185], v[110:113]
	v_mfma_f32_16x16x32_bf16 v[106:109], v[142:145], v[182:185], v[106:109]
	v_mfma_f32_16x16x32_bf16 v[102:105], v[134:137], v[190:193], v[102:105]
	v_mfma_f32_16x16x32_bf16 v[98:101], v[142:145], v[190:193], v[98:101]
	v_mfma_f32_16x16x32_bf16 v[94:97], v[146:149], v[162:165], v[94:97]
	v_mfma_f32_16x16x32_bf16 v[90:93], v[154:157], v[162:165], v[90:93]
	v_mfma_f32_16x16x32_bf16 v[86:89], v[146:149], v[170:173], v[86:89]
	v_mfma_f32_16x16x32_bf16 v[82:85], v[154:157], v[170:173], v[82:85]
	v_mfma_f32_16x16x32_bf16 v[78:81], v[146:149], v[178:181], v[78:81]
	v_mfma_f32_16x16x32_bf16 v[74:77], v[154:157], v[178:181], v[74:77]
	v_mfma_f32_16x16x32_bf16 v[70:73], v[146:149], v[186:189], v[70:73]
	v_mfma_f32_16x16x32_bf16 v[66:69], v[154:157], v[186:189], v[66:69]
	v_mfma_f32_16x16x32_bf16 v[94:97], v[150:153], v[166:169], v[94:97]
	v_mfma_f32_16x16x32_bf16 v[90:93], v[158:161], v[166:169], v[90:93]
	v_mfma_f32_16x16x32_bf16 v[86:89], v[150:153], v[174:177], v[86:89]
	v_mfma_f32_16x16x32_bf16 v[82:85], v[158:161], v[174:177], v[82:85]
	v_mfma_f32_16x16x32_bf16 v[78:81], v[150:153], v[182:185], v[78:81]
	v_mfma_f32_16x16x32_bf16 v[74:77], v[158:161], v[182:185], v[74:77]
	v_mfma_f32_16x16x32_bf16 v[70:73], v[150:153], v[190:193], v[70:73]
	v_mfma_f32_16x16x32_bf16 v[66:69], v[158:161], v[190:193], v[66:69]
	s_setprio 0
	s_barrier
; #define PG8_STAGE(bufoff, gbase, voff) do { _Pragma("unroll") for (int _i = 0; _i < 2; ++_i) \
;         __builtin_amdgcn_global_load_lds((const unsigned*)((const char*)(gbase) + (voff)[_i]), (LAS unsigned*)(lds + (bufoff) + ldsw + _i * 8192), 16, 0, 0); } while (0)
; #define PG8_LDA(dst, b, h) do { _Pragma("unroll") for (int m = 0; m < 4; ++m) _Pragma("unroll") for (int k = 0; k < 2; ++k) dst[m][k] = *(const LAS bf16x8*)(lds + PG8_SA(b, h) + aoff + m * 2048 + k * 1024); } while (0)
; #define PG8_MMA(ai, bj, At, Bt) do { __builtin_amdgcn_s_setprio(1); _Pragma("unroll") for (int m = 0; m < 4; ++m) _Pragma("unroll") for (int n = 0; n < 2; ++n) _Pragma("unroll") for (int k = 0; k < 2; ++k) \
;         acc[ai][bj][m][n] = __builtin_amdgcn_mfma_f32_16x16x32_bf16(Bt[n][k], At[m][k], acc[ai][bj][m][n], 0, 0, 0); __builtin_amdgcn_s_setprio(0); } while (0)
; #define PG8_WAIT_V(n) asm volatile("s_waitcnt vmcnt(" #n ")" ::: "memory")
; #define PG8_WAIT_L(n) asm volatile("s_waitcnt lgkmcnt(" #n ")" ::: "memory")
; #define PG8_BAR __builtin_amdgcn_s_barrier()
; #define PG8_SCHED __builtin_amdgcn_sched_barrier(0)
; template <class Epi, class Sched>
; __device__ __forceinline__ void gemm_phase(LAS unsigned char* lds, const Gemm g, const Sched& S, const Epi& E, const int tid) {
;     ...
;             PG8_LDA(At, 1, 1); PG8_STAGE(PG8_SB(1, 0), b3, voffB); PG8_STAGE(PG8_SB(1, 1), b3 + hstepB, voffB); PG8_STAGE(PG8_SA(1, 0), a3, voffA);
;             PG8_WAIT_V(8); PG8_WAIT_L(0); PG8_BAR; PG8_MMA(1, 0, At, B0); PG8_MMA(1, 1, At, B1); PG8_BAR; PG8_SCHED;
;         }
;         if (wr == 0) PG8_BAR;
	s_add_i32 s49, s49, s46
	v_lshl_add_u64 v[194:195], v[194:195], 0, s[90:91]
	s_mov_b32 m0, s49
	ds_read_b128 v[162:165], v236 offset:49152
	ds_read_b128 v[166:169], v236 offset:50176
	ds_read_b128 v[170:173], v236 offset:51200
	ds_read_b128 v[174:177], v236 offset:52224
	ds_read_b128 v[178:181], v236 offset:53248
	ds_read_b128 v[182:185], v236 offset:54272
	ds_read_b128 v[186:189], v236 offset:55296
	ds_read_b128 v[190:193], v236 offset:56320
	global_load_lds_dwordx4 v[194:195], off
	s_add_i32 m0, s49, 0x2000
	s_add_u32 s60, s62, 0x40080
	v_lshl_add_u64 v[194:195], v[196:197], 0, s[90:91]
	s_addc_u32 s61, s63, 0
	s_add_i32 s49, s53, s46
	global_load_lds_dwordx4 v[194:195], off
	v_lshl_add_u64 v[194:195], s[60:61], 0, v[206:207]
	s_mov_b32 m0, s49
	s_nop 0
	global_load_lds_dwordx4 v[194:195], off
	v_lshl_add_u64 v[194:195], s[60:61], 0, v[210:211]
	s_add_i32 m0, s49, 0x2000
	s_nop 0
	global_load_lds_dwordx4 v[194:195], off
	v_lshl_add_u64 v[194:195], v[198:199], 0, s[90:91]
	s_mov_b32 m0, s69
	s_nop 0
	global_load_lds_dwordx4 v[194:195], off
	v_lshl_add_u64 v[194:195], v[200:201], 0, s[90:91]
	s_mov_b32 m0, s70
	s_nop 0
	global_load_lds_dwordx4 v[194:195], off
	s_waitcnt vmcnt(8)
	s_waitcnt lgkmcnt(0)
	s_barrier
	s_setprio 1
	v_mfma_f32_16x16x32_bf16 v[62:65], v[130:133], v[162:165], v[62:65]
	v_mfma_f32_16x16x32_bf16 v[58:61], v[138:141], v[162:165], v[58:61]
	v_mfma_f32_16x16x32_bf16 v[54:57], v[130:133], v[170:173], v[54:57]
	v_mfma_f32_16x16x32_bf16 v[50:53], v[138:141], v[170:173], v[50:53]
	v_mfma_f32_16x16x32_bf16 v[46:49], v[130:133], v[178:181], v[46:49]
	v_mfma_f32_16x16x32_bf16 v[42:45], v[138:141], v[178:181], v[42:45]
	v_mfma_f32_16x16x32_bf16 v[38:41], v[130:133], v[186:189], v[38:41]
	v_mfma_f32_16x16x32_bf16 v[34:37], v[138:141], v[186:189], v[34:37]
	v_mfma_f32_16x16x32_bf16 v[62:65], v[134:137], v[166:169], v[62:65]
	v_mfma_f32_16x16x32_bf16 v[58:61], v[142:145], v[166:169], v[58:61]
	v_mfma_f32_16x16x32_bf16 v[54:57], v[134:137], v[174:177], v[54:57]
	v_mfma_f32_16x16x32_bf16 v[50:53], v[142:145], v[174:177], v[50:53]
	v_mfma_f32_16x16x32_bf16 v[46:49], v[134:137], v[182:185], v[46:49]
	v_mfma_f32_16x16x32_bf16 v[42:45], v[142:145], v[182:185], v[42:45]
	v_mfma_f32_16x16x32_bf16 v[38:41], v[134:137], v[190:193], v[38:41]
	v_mfma_f32_16x16x32_bf16 v[34:37], v[142:145], v[190:193], v[34:37]
	v_mfma_f32_16x16x32_bf16 v[30:33], v[146:149], v[162:165], v[30:33]
	v_mfma_f32_16x16x32_bf16 v[26:29], v[154:157], v[162:165], v[26:29]
	v_mfma_f32_16x16x32_bf16 v[22:25], v[146:149], v[170:173], v[22:25]
	v_mfma_f32_16x16x32_bf16 v[18:21], v[154:157], v[170:173], v[18:21]
	v_mfma_f32_16x16x32_bf16 v[14:17], v[146:149], v[178:181], v[14:17]
	v_mfma_f32_16x16x32_bf16 v[10:13], v[154:157], v[178:181], v[10:13]
	v_mfma_f32_16x16x32_bf16 v[6:9], v[146:149], v[186:189], v[6:9]
	v_mfma_f32_16x16x32_bf16 v[2:5], v[154:157], v[186:189], v[2:5]
	v_mfma_f32_16x16x32_bf16 v[30:33], v[150:153], v[166:169], v[30:33]
	v_mfma_f32_16x16x32_bf16 v[26:29], v[158:161], v[166:169], v[26:29]
	v_mfma_f32_16x16x32_bf16 v[22:25], v[150:153], v[174:177], v[22:25]
	v_mfma_f32_16x16x32_bf16 v[18:21], v[158:161], v[174:177], v[18:21]
	v_mfma_f32_16x16x32_bf16 v[14:17], v[150:153], v[182:185], v[14:17]
	v_mfma_f32_16x16x32_bf16 v[10:13], v[158:161], v[182:185], v[10:13]
	v_mfma_f32_16x16x32_bf16 v[6:9], v[150:153], v[190:193], v[6:9]
	v_mfma_f32_16x16x32_bf16 v[2:5], v[158:161], v[190:193], v[2:5]
	s_setprio 0
	s_barrier
	s_add_i32 s45, s45, 2
	s_add_u32 s43, s43, 0x100
	s_addc_u32 s44, s44, 0
	s_cmp_gt_u32 s45, 13
	s_mov_b64 s[60:61], s[40:41]
	s_cbranch_scc0 .LBB1_156
	s_and_b64 vcc, exec, s[26:27]
	s_cbranch_vccz .LBB1_159
	s_barrier

; #define PG8_STAGE(bufoff, gbase, voff) do { _Pragma("unroll") for (int _i = 0; _i < 2; ++_i) \
;         __builtin_amdgcn_global_load_lds((const unsigned*)((const char*)(gbase) + (voff)[_i]), (LAS unsigned*)(lds + (bufoff) + ldsw + _i * 8192), 16, 0, 0); } while (0)
; #define PG8_LDA(dst, b, h) do { _Pragma("unroll") for (int m = 0; m < 4; ++m) _Pragma("unroll") for (int k = 0; k < 2; ++k) dst[m][k] = *(const LAS bf16x8*)(lds + PG8_SA(b, h) + aoff + m * 2048 + k * 1024); } while (0)
; #define PG8_BAR __builtin_amdgcn_s_barrier()
; template <class Epi, class Sched>
; __device__ __forceinline__ void gemm_phase(LAS unsigned char* lds, const Gemm g, const Sched& S, const Epi& E, const int tid) {
;     ...
;     const char* cA = (const char*)g.A + (size_t)cur.pm * tstepA + (size_t)cur.aoff * 2; const char* cB = (const char*)g.Bt + (size_t)cur.pn * tstepB;
;     PG8_STAGE(PG8_SB(0, 0), cB, voffB); PG8_STAGE(PG8_SB(0, 1), cB + hstepB, voffB); PG8_STAGE(PG8_SA(0, 0), cA, voffA); PG8_STAGE(PG8_SA(0, 1), cA + hstepA, voffA);
;     if (wr == 1) PG8_BAR;
;     PG8_WAIT_V(2); PG8_BAR;
;     PG8_STAGE(PG8_SB(1, 0), cB + kstep, voffB); PG8_STAGE(PG8_SA(1, 0), cA + kstep, voffA); PG8_STAGE(PG8_SB(1, 1), cB + hstepB + kstep, voffB);
;     PG8_WAIT_V(6); PG8_BAR;
;     for (;;) {
;         const bool has_next = S.next(ui + 1, nxt);
;         const char* nA = has_next ? (const char*)g.A + (size_t)nxt.pm * tstepA + (size_t)nxt.aoff * 2 : cA; const char* nB = has_next ? (const char*)g.Bt + (size_t)nxt.pn * tstepB : cB;
;         for (int t = 0; t < nt; t += 2) {
;             const bool last = (t == nt - 2);
;             const char* a1 = cA + (size_t)(t + 1) * kstep;
;             const char* a2 = last ? nA : cA + (size_t)(t + 2) * kstep; const char* b2 = last ? nB : cB + (size_t)(t + 2) * kstep;
;             const char* a3 = a2 + kstep; const char* b3 = b2 + kstep;
;             PG8_LDB(B0, 0, 0); PG8_LDB(B1, 0, 1); PG8_SCHED; PG8_LDA(At, 0, 0); PG8_STAGE(PG8_SA(1, 1), a1 + hstepA, voffA);
;             PG8_WAIT_V(8); PG8_WAIT_L(0); PG8_BAR; PG8_MMA(0, 0, At, B0); PG8_MMA(0, 1, At, B1); PG8_BAR; PG8_SCHED;
;             PG8_LDA(At, 0, 1); PG8_STAGE(PG8_SB(0, 0), b2, voffB); PG8_STAGE(PG8_SB(0, 1), b2 + hstepB, voffB); PG8_STAGE(PG8_SA(0, 0), a2, voffA);
;             PG8_WAIT_V(8); PG8_WAIT_L(0); PG8_BAR; PG8_MMA(1, 0, At, B0); PG8_MMA(1, 1, At, B1); PG8_BAR; PG8_SCHED;
.LBB1_354:
	v_and_b32_e32 v2, 15, v24
	v_bfe_u32 v137, v24, 4, 2
	v_readlane_b32 s4, v255, 7
	v_lshlrev_b32_e32 v3, 4, v137
	v_lshlrev_b32_e32 v131, 2, v2
	s_lshl_b32 s14, s14, 5
	v_readlane_b32 s5, v255, 8
	v_lshl_or_b32 v130, s47, 6, v2
	v_lshl_or_b32 v3, v2, 6, v3
	s_lshl_b32 s38, s47, 13
	v_and_b32_e32 v2, 32, v131
	s_and_b32 s14, s14, 0x60
	s_lshl_b64 s[4:5], s[4:5], 16
	v_bitop3_b32 v36, v3, s38, v2 bitop3:0xde
	s_lshl_b32 s38, s14, 7
	s_add_u32 s82, s36, 0x40080
	s_addc_u32 s83, s37, 0
	s_add_u32 s72, s40, 0x300080
	s_addc_u32 s73, s41, 0
	s_add_u32 s70, s36, 0x40100
	s_addc_u32 s71, s37, 0
	s_add_u32 s68, s40, 0x300100
	s_addc_u32 s69, s41, 0
	v_bitop3_b32 v2, s38, v3, v2 bitop3:0xf6
	s_add_u32 s38, s36, 0x40180
	s_addc_u32 s39, s37, 0
	s_add_u32 s36, s40, 0x300180
	s_addc_u32 s37, s41, 0
	s_add_i32 s47, 0, 0x18000
	s_add_i32 s40, s47, s80
	v_lshl_add_u64 v[26:27], v[4:5], 0, s[90:91]
	s_mov_b32 m0, s40
	s_add_i32 s76, s40, 0x2000
	s_waitcnt vmcnt(2)
	s_barrier
	global_load_lds_dwordx4 v[26:27], off
	v_lshl_add_u64 v[28:29], v[8:9], 0, s[90:91]
	s_mov_b32 m0, s76
	s_add_i32 s41, s15, 0x8000
	global_load_lds_dwordx4 v[28:29], off
	v_lshl_add_u64 v[24:25], v[16:17], 0, s[90:91]
	s_mov_b32 m0, s41
	s_add_i32 s77, s15, 0xa000
	s_add_i32 s56, 0, 0x1c000
	global_load_lds_dwordx4 v[24:25], off
	v_lshl_add_u64 v[30:31], v[18:19], 0, s[90:91]
	s_mov_b32 m0, s77
	s_add_i32 s78, s56, s80
	global_load_lds_dwordx4 v[30:31], off
	v_lshl_add_u64 v[32:33], s[82:83], 0, v[0:1]
	s_mov_b32 m0, s78
	s_add_i32 s79, s78, 0x2000
	global_load_lds_dwordx4 v[32:33], off
	v_lshl_add_u64 v[34:35], s[82:83], 0, v[22:23]
	s_mov_b32 m0, s79
	s_add_i32 s60, 0, 0x10000
	global_load_lds_dwordx4 v[34:35], off
	s_add_i32 s57, 0, 0x14000
	v_add_u32_e32 v129, s60, v2
	s_waitcnt vmcnt(6)
	s_barrier
	v_add_u32_e32 v136, 0, v36
	v_add_u32_e32 v128, s57, v2
	ds_read_b128 v[36:39], v129
	ds_read_b128 v[40:43], v129 offset:1024
	ds_read_b128 v[44:47], v129 offset:2048
	ds_read_b128 v[48:51], v129 offset:3072
	ds_read_b128 v[52:55], v128
	ds_read_b128 v[56:59], v128 offset:1024
	ds_read_b128 v[60:63], v128 offset:2048
	ds_read_b128 v[64:67], v128 offset:3072
	s_add_i32 s83, s60, s80
	s_add_i32 s81, s57, s80
	s_add_i32 s85, s15, 0xc000
	s_add_i32 s84, s15, 0xe000
	s_add_i32 s82, s83, 0x2000
	s_add_i32 s80, s81, 0x2000
	s_cmpk_gt_u32 s44, 0xff
	v_add_u32_e32 v224, s56, v2
	v_add_u32_e32 v225, s47, v2
	s_mov_b32 m0, s85
	v_lshl_add_u64 v[2:3], s[72:73], 0, v[20:21]
	ds_read_b128 v[68:71], v136
	ds_read_b128 v[72:75], v136 offset:1024
	ds_read_b128 v[76:79], v136 offset:2048
	ds_read_b128 v[80:83], v136 offset:3072
	ds_read_b128 v[84:87], v136 offset:4096
	ds_read_b128 v[88:91], v136 offset:5120
	ds_read_b128 v[92:95], v136 offset:6144
	ds_read_b128 v[96:99], v136 offset:7168
	global_load_lds_dwordx4 v[2:3], off
	v_lshl_add_u64 v[2:3], s[72:73], 0, v[10:11]
	s_mov_b32 m0, s84
	s_nop 0
	global_load_lds_dwordx4 v[2:3], off
	s_waitcnt vmcnt(8)
	s_waitcnt lgkmcnt(0)
	s_barrier
	s_setprio 1
	v_mfma_f32_16x16x32_bf16 v[100:103], v[36:39], v[68:71], 0
	v_mfma_f32_16x16x32_bf16 v[104:107], v[44:47], v[68:71], 0
	v_mfma_f32_16x16x32_bf16 v[108:111], v[36:39], v[76:79], 0
	v_mfma_f32_16x16x32_bf16 v[112:115], v[44:47], v[76:79], 0
	v_mfma_f32_16x16x32_bf16 v[116:119], v[36:39], v[84:87], 0
	v_mfma_f32_16x16x32_bf16 v[120:123], v[44:47], v[84:87], 0
	v_mfma_f32_16x16x32_bf16 v[124:127], v[36:39], v[92:95], 0
	v_mfma_f32_16x16x32_bf16 v[100:103], v[40:43], v[72:75], v[100:103]
	v_mfma_f32_16x16x32_bf16 v[104:107], v[48:51], v[72:75], v[104:107]
	v_mfma_f32_16x16x32_bf16 v[108:111], v[40:43], v[80:83], v[108:111]
	v_mfma_f32_16x16x32_bf16 v[112:115], v[48:51], v[80:83], v[112:115]
	v_mfma_f32_16x16x32_bf16 v[116:119], v[40:43], v[88:91], v[116:119]
	v_mfma_f32_16x16x32_bf16 v[120:123], v[48:51], v[88:91], v[120:123]
	v_mfma_f32_16x16x32_bf16 v[124:127], v[40:43], v[96:99], v[124:127]
	v_mfma_f32_16x16x32_bf16 v[132:135], v[44:47], v[92:95], 0
	v_mfma_f32_16x16x32_bf16 v[132:135], v[48:51], v[96:99], v[132:135]
	v_mfma_f32_16x16x32_bf16 v[138:141], v[52:55], v[68:71], 0
	v_mfma_f32_16x16x32_bf16 v[68:71], v[60:63], v[68:71], 0
	v_mfma_f32_16x16x32_bf16 v[138:141], v[56:59], v[72:75], v[138:141]
	v_mfma_f32_16x16x32_bf16 v[68:71], v[64:67], v[72:75], v[68:71]
	v_mfma_f32_16x16x32_bf16 v[72:75], v[52:55], v[76:79], 0
	v_mfma_f32_16x16x32_bf16 v[76:79], v[60:63], v[76:79], 0
	v_mfma_f32_16x16x32_bf16 v[72:75], v[56:59], v[80:83], v[72:75]
	v_mfma_f32_16x16x32_bf16 v[76:79], v[64:67], v[80:83], v[76:79]
	v_mfma_f32_16x16x32_bf16 v[80:83], v[52:55], v[84:87], 0
	v_mfma_f32_16x16x32_bf16 v[84:87], v[60:63], v[84:87], 0
	v_mfma_f32_16x16x32_bf16 v[80:83], v[56:59], v[88:91], v[80:83]
	v_mfma_f32_16x16x32_bf16 v[84:87], v[64:67], v[88:91], v[84:87]
	v_mfma_f32_16x16x32_bf16 v[88:91], v[52:55], v[92:95], 0
	v_mfma_f32_16x16x32_bf16 v[92:95], v[60:63], v[92:95], 0
	v_mfma_f32_16x16x32_bf16 v[88:91], v[56:59], v[96:99], v[88:91]
	v_mfma_f32_16x16x32_bf16 v[92:95], v[64:67], v[96:99], v[92:95]
	s_setprio 0
	s_barrier
	s_mov_b32 m0, s83
	v_lshl_add_u64 v[2:3], v[4:5], 0, s[0:1]
	ds_read_b128 v[96:99], v136 offset:16384
	ds_read_b128 v[142:145], v136 offset:17408
	ds_read_b128 v[146:149], v136 offset:18432
	ds_read_b128 v[150:153], v136 offset:19456
	ds_read_b128 v[154:157], v136 offset:20480
	ds_read_b128 v[158:161], v136 offset:21504
	ds_read_b128 v[162:165], v136 offset:22528
	ds_read_b128 v[166:169], v136 offset:23552
	global_load_lds_dwordx4 v[2:3], off
	v_lshl_add_u64 v[2:3], v[8:9], 0, s[0:1]
	s_mov_b32 m0, s82
	s_nop 0
	global_load_lds_dwordx4 v[2:3], off
	v_lshl_add_u64 v[2:3], s[70:71], 0, v[0:1]
	s_mov_b32 m0, s81
	s_nop 0
	global_load_lds_dwordx4 v[2:3], off
	v_lshl_add_u64 v[2:3], s[70:71], 0, v[22:23]
	s_mov_b32 m0, s80
	s_nop 0
	global_load_lds_dwordx4 v[2:3], off
	v_lshl_add_u64 v[2:3], v[16:17], 0, s[0:1]
	s_mov_b32 m0, s15
	s_nop 0
	global_load_lds_dwordx4 v[2:3], off
	v_lshl_add_u64 v[2:3], v[18:19], 0, s[0:1]
	s_mov_b32 m0, s59
	s_nop 0
	global_load_lds_dwordx4 v[2:3], off
	s_waitcnt vmcnt(8)
	s_waitcnt lgkmcnt(0)
	s_barrier
; #define PG8_STAGE(bufoff, gbase, voff) do { _Pragma("unroll") for (int _i = 0; _i < 2; ++_i) \
;         __builtin_amdgcn_global_load_lds((const unsigned*)((const char*)(gbase) + (voff)[_i]), (LAS unsigned*)(lds + (bufoff) + ldsw + _i * 8192), 16, 0, 0); } while (0)
; #define PG8_LDA(dst, b, h) do { _Pragma("unroll") for (int m = 0; m < 4; ++m) _Pragma("unroll") for (int k = 0; k < 2; ++k) dst[m][k] = *(const LAS bf16x8*)(lds + PG8_SA(b, h) + aoff + m * 2048 + k * 1024); } while (0)
; #define PG8_LDB(dst, b, h) do { _Pragma("unroll") for (int n = 0; n < 2; ++n) _Pragma("unroll") for (int k = 0; k < 2; ++k) dst[n][k] = *(const LAS bf16x8*)(lds + PG8_SB(b, h) + boff + n * 2048 + k * 1024); } while (0)
; #define PG8_MMA(ai, bj, At, Bt) do { __builtin_amdgcn_s_setprio(1); _Pragma("unroll") for (int m = 0; m < 4; ++m) _Pragma("unroll") for (int n = 0; n < 2; ++n) _Pragma("unroll") for (int k = 0; k < 2; ++k) \
;         acc[ai][bj][m][n] = __builtin_amdgcn_mfma_f32_16x16x32_bf16(Bt[n][k], At[m][k], acc[ai][bj][m][n], 0, 0, 0); __builtin_amdgcn_s_setprio(0); } while (0)
; #define PG8_WAIT_V(n) asm volatile("s_waitcnt vmcnt(" #n ")" ::: "memory")
; #define PG8_WAIT_L(n) asm volatile("s_waitcnt lgkmcnt(" #n ")" ::: "memory")
; #define PG8_BAR __builtin_amdgcn_s_barrier()
; #define PG8_SCHED __builtin_amdgcn_sched_barrier(0)
; template <class Epi, class Sched>
; __device__ __forceinline__ void gemm_phase(LAS unsigned char* lds, const Gemm g, const Sched& S, const Epi& E, const int tid) {
;     ...
;             PG8_WAIT_V(8); PG8_WAIT_L(0); PG8_BAR; PG8_MMA(1, 0, At, B0); PG8_MMA(1, 1, At, B1); PG8_BAR; PG8_SCHED;
;             PG8_LDB(B0, 1, 0); PG8_LDB(B1, 1, 1); PG8_SCHED; PG8_LDA(At, 1, 0); PG8_STAGE(PG8_SA(0, 1), a2 + hstepA, voffA);
;             PG8_WAIT_V(8); PG8_WAIT_L(0); PG8_BAR; PG8_MMA(0, 0, At, B0); PG8_MMA(0, 1, At, B1); PG8_BAR; PG8_SCHED;
	s_setprio 1
	v_mfma_f32_16x16x32_bf16 v[170:173], v[36:39], v[96:99], 0
	v_mfma_f32_16x16x32_bf16 v[178:181], v[36:39], v[146:149], 0
	v_mfma_f32_16x16x32_bf16 v[186:189], v[36:39], v[154:157], 0
	v_mfma_f32_16x16x32_bf16 v[36:39], v[36:39], v[162:165], 0
	v_mfma_f32_16x16x32_bf16 v[170:173], v[40:43], v[142:145], v[170:173]
	v_mfma_f32_16x16x32_bf16 v[178:181], v[40:43], v[150:153], v[178:181]
	v_mfma_f32_16x16x32_bf16 v[186:189], v[40:43], v[158:161], v[186:189]
	v_mfma_f32_16x16x32_bf16 v[36:39], v[40:43], v[166:169], v[36:39]
	v_mfma_f32_16x16x32_bf16 v[40:43], v[44:47], v[162:165], 0
	v_mfma_f32_16x16x32_bf16 v[174:177], v[44:47], v[96:99], 0
	v_mfma_f32_16x16x32_bf16 v[182:185], v[44:47], v[146:149], 0
	v_mfma_f32_16x16x32_bf16 v[190:193], v[44:47], v[154:157], 0
	v_mfma_f32_16x16x32_bf16 v[40:43], v[48:51], v[166:169], v[40:43]
	v_mfma_f32_16x16x32_bf16 v[174:177], v[48:51], v[142:145], v[174:177]
	v_mfma_f32_16x16x32_bf16 v[182:185], v[48:51], v[150:153], v[182:185]
	v_mfma_f32_16x16x32_bf16 v[190:193], v[48:51], v[158:161], v[190:193]
	v_mfma_f32_16x16x32_bf16 v[44:47], v[52:55], v[96:99], 0
	v_mfma_f32_16x16x32_bf16 v[48:51], v[60:63], v[96:99], 0
	v_mfma_f32_16x16x32_bf16 v[44:47], v[56:59], v[142:145], v[44:47]
	v_mfma_f32_16x16x32_bf16 v[48:51], v[64:67], v[142:145], v[48:51]
	v_mfma_f32_16x16x32_bf16 v[96:99], v[52:55], v[146:149], 0
	v_mfma_f32_16x16x32_bf16 v[142:145], v[60:63], v[146:149], 0
	v_mfma_f32_16x16x32_bf16 v[146:149], v[52:55], v[154:157], 0
	v_mfma_f32_16x16x32_bf16 v[52:55], v[52:55], v[162:165], 0
	v_mfma_f32_16x16x32_bf16 v[96:99], v[56:59], v[150:153], v[96:99]
	v_mfma_f32_16x16x32_bf16 v[146:149], v[56:59], v[158:161], v[146:149]
	v_mfma_f32_16x16x32_bf16 v[52:55], v[56:59], v[166:169], v[52:55]
	v_mfma_f32_16x16x32_bf16 v[56:59], v[60:63], v[162:165], 0
	v_mfma_f32_16x16x32_bf16 v[142:145], v[64:67], v[150:153], v[142:145]
	v_mfma_f32_16x16x32_bf16 v[150:153], v[60:63], v[154:157], 0
	v_mfma_f32_16x16x32_bf16 v[56:59], v[64:67], v[166:169], v[56:59]
	v_mfma_f32_16x16x32_bf16 v[150:153], v[64:67], v[158:161], v[150:153]
	s_setprio 0
	s_barrier
	ds_read_b128 v[60:63], v225
	ds_read_b128 v[64:67], v225 offset:1024
	ds_read_b128 v[154:157], v225 offset:2048
	ds_read_b128 v[158:161], v225 offset:3072
	ds_read_b128 v[162:165], v224
	ds_read_b128 v[166:169], v224 offset:1024
	ds_read_b128 v[204:207], v224 offset:2048
	ds_read_b128 v[208:211], v224 offset:3072
	s_mov_b32 m0, s45
	v_lshl_add_u64 v[2:3], s[68:69], 0, v[20:21]
	ds_read_b128 v[212:215], v136 offset:32768
	ds_read_b128 v[216:219], v136 offset:33792
	ds_read_b128 v[220:223], v136 offset:34816
	ds_read_b128 v[230:233], v136 offset:35840
	ds_read_b128 v[234:237], v136 offset:36864
	ds_read_b128 v[238:241], v136 offset:37888
	ds_read_b128 v[242:245], v136 offset:38912
	ds_read_b128 v[246:249], v136 offset:39936
	global_load_lds_dwordx4 v[2:3], off
	v_lshl_add_u64 v[2:3], s[68:69], 0, v[10:11]
	s_mov_b32 m0, s58
	s_nop 0
	global_load_lds_dwordx4 v[2:3], off
	s_waitcnt vmcnt(8)
	s_waitcnt lgkmcnt(0)
	s_barrier
	s_setprio 1
	v_mfma_f32_16x16x32_bf16 v[100:103], v[60:63], v[212:215], v[100:103]
	v_mfma_f32_16x16x32_bf16 v[104:107], v[154:157], v[212:215], v[104:107]
	v_mfma_f32_16x16x32_bf16 v[108:111], v[60:63], v[220:223], v[108:111]
	v_mfma_f32_16x16x32_bf16 v[112:115], v[154:157], v[220:223], v[112:115]
	v_mfma_f32_16x16x32_bf16 v[116:119], v[60:63], v[234:237], v[116:119]
	v_mfma_f32_16x16x32_bf16 v[120:123], v[154:157], v[234:237], v[120:123]
	v_mfma_f32_16x16x32_bf16 v[124:127], v[60:63], v[242:245], v[124:127]
	v_mfma_f32_16x16x32_bf16 v[100:103], v[64:67], v[216:219], v[100:103]
	v_mfma_f32_16x16x32_bf16 v[104:107], v[158:161], v[216:219], v[104:107]
	v_mfma_f32_16x16x32_bf16 v[108:111], v[64:67], v[230:233], v[108:111]
	v_mfma_f32_16x16x32_bf16 v[112:115], v[158:161], v[230:233], v[112:115]
	v_mfma_f32_16x16x32_bf16 v[116:119], v[64:67], v[238:241], v[116:119]
	v_mfma_f32_16x16x32_bf16 v[120:123], v[158:161], v[238:241], v[120:123]
	v_mfma_f32_16x16x32_bf16 v[124:127], v[64:67], v[246:249], v[124:127]
	v_mfma_f32_16x16x32_bf16 v[132:135], v[154:157], v[242:245], v[132:135]
	v_mfma_f32_16x16x32_bf16 v[132:135], v[158:161], v[246:249], v[132:135]
	v_mfma_f32_16x16x32_bf16 v[68:71], v[204:207], v[212:215], v[68:71]
	v_mfma_f32_16x16x32_bf16 v[72:75], v[162:165], v[220:223], v[72:75]
	v_mfma_f32_16x16x32_bf16 v[80:83], v[162:165], v[234:237], v[80:83]
	v_mfma_f32_16x16x32_bf16 v[84:87], v[204:207], v[234:237], v[84:87]
	v_mfma_f32_16x16x32_bf16 v[88:91], v[162:165], v[242:245], v[88:91]
	v_mfma_f32_16x16x32_bf16 v[92:95], v[204:207], v[242:245], v[92:95]
	v_mfma_f32_16x16x32_bf16 v[138:141], v[162:165], v[212:215], v[138:141]
	v_mfma_f32_16x16x32_bf16 v[68:71], v[208:211], v[216:219], v[68:71]
	v_mfma_f32_16x16x32_bf16 v[72:75], v[166:169], v[230:233], v[72:75]
	v_mfma_f32_16x16x32_bf16 v[76:79], v[204:207], v[220:223], v[76:79]
	v_mfma_f32_16x16x32_bf16 v[80:83], v[166:169], v[238:241], v[80:83]
	v_mfma_f32_16x16x32_bf16 v[84:87], v[208:211], v[238:241], v[84:87]
	v_mfma_f32_16x16x32_bf16 v[88:91], v[166:169], v[246:249], v[88:91]
	v_mfma_f32_16x16x32_bf16 v[92:95], v[208:211], v[246:249], v[92:95]
	v_mfma_f32_16x16x32_bf16 v[138:141], v[166:169], v[216:219], v[138:141]
	v_mfma_f32_16x16x32_bf16 v[76:79], v[208:211], v[230:233], v[76:79]
	s_setprio 0
	s_barrier
; #define PG8_STAGE(bufoff, gbase, voff) do { _Pragma("unroll") for (int _i = 0; _i < 2; ++_i) \
;         __builtin_amdgcn_global_load_lds((const unsigned*)((const char*)(gbase) + (voff)[_i]), (LAS unsigned*)(lds + (bufoff) + ldsw + _i * 8192), 16, 0, 0); } while (0)
; #define PG8_LDA(dst, b, h) do { _Pragma("unroll") for (int m = 0; m < 4; ++m) _Pragma("unroll") for (int k = 0; k < 2; ++k) dst[m][k] = *(const LAS bf16x8*)(lds + PG8_SA(b, h) + aoff + m * 2048 + k * 1024); } while (0)
; #define PG8_LDB(dst, b, h) do { _Pragma("unroll") for (int n = 0; n < 2; ++n) _Pragma("unroll") for (int k = 0; k < 2; ++k) dst[n][k] = *(const LAS bf16x8*)(lds + PG8_SB(b, h) + boff + n * 2048 + k * 1024); } while (0)
; #define PG8_MMA(ai, bj, At, Bt) do { __builtin_amdgcn_s_setprio(1); _Pragma("unroll") for (int m = 0; m < 4; ++m) _Pragma("unroll") for (int n = 0; n < 2; ++n) _Pragma("unroll") for (int k = 0; k < 2; ++k) \
;         acc[ai][bj][m][n] = __builtin_amdgcn_mfma_f32_16x16x32_bf16(Bt[n][k], At[m][k], acc[ai][bj][m][n], 0, 0, 0); __builtin_amdgcn_s_setprio(0); } while (0)
; #define PG8_WAIT_V(n) asm volatile("s_waitcnt vmcnt(" #n ")" ::: "memory")
; template <class Epi, class Sched>
; __device__ __forceinline__ void gemm_phase(LAS unsigned char* lds, const Gemm g, const Sched& S, const Epi& E, const int tid) {
;     ...
;             PG8_LDB(B0, 0, 0); PG8_LDB(B1, 0, 1); PG8_SCHED; PG8_LDA(At, 0, 0); PG8_STAGE(PG8_SA(1, 1), a1 + hstepA, voffA);
;             PG8_WAIT_V(8); PG8_WAIT_L(0); PG8_BAR; PG8_MMA(0, 0, At, B0); PG8_MMA(0, 1, At, B1); PG8_BAR; PG8_SCHED;
;             PG8_LDA(At, 0, 1); PG8_STAGE(PG8_SB(0, 0), b2, voffB); PG8_STAGE(PG8_SB(0, 1), b2 + hstepB, voffB); PG8_STAGE(PG8_SA(0, 0), a2, voffA);
;             PG8_WAIT_V(8); PG8_WAIT_L(0); PG8_BAR; PG8_MMA(1, 0, At, B0); PG8_MMA(1, 1, At, B1); PG8_BAR; PG8_SCHED;
;             PG8_LDB(B0, 1, 0); PG8_LDB(B1, 1, 1); PG8_SCHED; PG8_LDA(At, 1, 0); PG8_STAGE(PG8_SA(0, 1), a2 + hstepA, voffA);
;             PG8_WAIT_V(8); PG8_WAIT_L(0); PG8_BAR; PG8_MMA(0, 0, At, B0); PG8_MMA(0, 1, At, B1); PG8_BAR; PG8_SCHED;
;             PG8_LDA(At, 1, 1); PG8_STAGE(PG8_SB(1, 0), b3, voffB); PG8_STAGE(PG8_SB(1, 1), b3 + hstepB, voffB); PG8_STAGE(PG8_SA(1, 0), a3, voffA);
;             PG8_WAIT_V(8); PG8_WAIT_L(0); PG8_BAR; PG8_MMA(1, 0, At, B0); PG8_MMA(1, 1, At, B1); PG8_BAR; PG8_SCHED;
	s_mov_b64 s[16:17], 0x180
	s_mov_b32 m0, s40
	v_lshl_add_u64 v[2:3], v[4:5], 0, s[16:17]
	ds_read_b128 v[212:215], v136 offset:49152
	ds_read_b128 v[216:219], v136 offset:50176
	ds_read_b128 v[220:223], v136 offset:51200
	ds_read_b128 v[230:233], v136 offset:52224
	ds_read_b128 v[234:237], v136 offset:53248
	ds_read_b128 v[238:241], v136 offset:54272
	ds_read_b128 v[242:245], v136 offset:55296
	ds_read_b128 v[246:249], v136 offset:56320
	global_load_lds_dwordx4 v[2:3], off
	v_lshl_add_u64 v[2:3], v[8:9], 0, s[16:17]
	s_mov_b32 m0, s76
	s_nop 0
	global_load_lds_dwordx4 v[2:3], off
	v_lshl_add_u64 v[2:3], s[38:39], 0, v[0:1]
	s_mov_b32 m0, s78
	s_nop 0
	global_load_lds_dwordx4 v[2:3], off
	v_lshl_add_u64 v[2:3], s[38:39], 0, v[22:23]
	s_mov_b32 m0, s79
	s_nop 0
	global_load_lds_dwordx4 v[2:3], off
	v_lshl_add_u64 v[2:3], v[16:17], 0, s[16:17]
	s_mov_b32 m0, s41
	s_nop 0
	global_load_lds_dwordx4 v[2:3], off
	v_lshl_add_u64 v[2:3], v[18:19], 0, s[16:17]
	s_mov_b32 m0, s77
	s_nop 0
	global_load_lds_dwordx4 v[2:3], off
	s_waitcnt vmcnt(8)
	s_waitcnt lgkmcnt(0)
	s_barrier
	s_setprio 1
	v_mfma_f32_16x16x32_bf16 v[36:39], v[60:63], v[242:245], v[36:39]
	v_mfma_f32_16x16x32_bf16 v[40:43], v[154:157], v[242:245], v[40:43]
	v_mfma_f32_16x16x32_bf16 v[170:173], v[60:63], v[212:215], v[170:173]
	v_mfma_f32_16x16x32_bf16 v[174:177], v[154:157], v[212:215], v[174:177]
	v_mfma_f32_16x16x32_bf16 v[178:181], v[60:63], v[220:223], v[178:181]
	v_mfma_f32_16x16x32_bf16 v[182:185], v[154:157], v[220:223], v[182:185]
	v_mfma_f32_16x16x32_bf16 v[186:189], v[60:63], v[234:237], v[186:189]
	v_mfma_f32_16x16x32_bf16 v[190:193], v[154:157], v[234:237], v[190:193]
	v_mfma_f32_16x16x32_bf16 v[36:39], v[64:67], v[246:249], v[36:39]
	v_mfma_f32_16x16x32_bf16 v[40:43], v[158:161], v[246:249], v[40:43]
	v_mfma_f32_16x16x32_bf16 v[170:173], v[64:67], v[216:219], v[170:173]
	v_mfma_f32_16x16x32_bf16 v[174:177], v[158:161], v[216:219], v[174:177]
	v_mfma_f32_16x16x32_bf16 v[178:181], v[64:67], v[230:233], v[178:181]
	v_mfma_f32_16x16x32_bf16 v[182:185], v[158:161], v[230:233], v[182:185]
	v_mfma_f32_16x16x32_bf16 v[186:189], v[64:67], v[238:241], v[186:189]
	v_mfma_f32_16x16x32_bf16 v[190:193], v[158:161], v[238:241], v[190:193]
	v_mfma_f32_16x16x32_bf16 v[44:47], v[162:165], v[212:215], v[44:47]
	v_mfma_f32_16x16x32_bf16 v[48:51], v[204:207], v[212:215], v[48:51]
	v_mfma_f32_16x16x32_bf16 v[60:63], v[162:165], v[220:223], v[96:99]
	v_mfma_f32_16x16x32_bf16 v[64:67], v[204:207], v[220:223], v[142:145]
	v_mfma_f32_16x16x32_bf16 v[96:99], v[162:165], v[234:237], v[146:149]
	v_mfma_f32_16x16x32_bf16 v[52:55], v[162:165], v[242:245], v[52:55]
	v_mfma_f32_16x16x32_bf16 v[56:59], v[204:207], v[242:245], v[56:59]
	v_mfma_f32_16x16x32_bf16 v[44:47], v[166:169], v[216:219], v[44:47]
	v_mfma_f32_16x16x32_bf16 v[48:51], v[208:211], v[216:219], v[48:51]
	v_mfma_f32_16x16x32_bf16 v[60:63], v[166:169], v[230:233], v[60:63]
	v_mfma_f32_16x16x32_bf16 v[64:67], v[208:211], v[230:233], v[64:67]
	v_mfma_f32_16x16x32_bf16 v[96:99], v[166:169], v[238:241], v[96:99]
	v_mfma_f32_16x16x32_bf16 v[142:145], v[204:207], v[234:237], v[150:153]
	v_mfma_f32_16x16x32_bf16 v[52:55], v[166:169], v[246:249], v[52:55]
	v_mfma_f32_16x16x32_bf16 v[56:59], v[208:211], v[246:249], v[56:59]
	v_mfma_f32_16x16x32_bf16 v[142:145], v[208:211], v[238:241], v[142:145]
	s_setprio 0
	s_barrier
	ds_read_b128 v[146:149], v129
	ds_read_b128 v[150:153], v129 offset:1024
	ds_read_b128 v[154:157], v129 offset:2048
	ds_read_b128 v[158:161], v129 offset:3072
	ds_read_b128 v[162:165], v128
	ds_read_b128 v[166:169], v128 offset:1024
	ds_read_b128 v[204:207], v128 offset:2048
	ds_read_b128 v[208:211], v128 offset:3072
	s_mov_b32 m0, s85
	v_lshl_add_u64 v[2:3], s[36:37], 0, v[20:21]
	ds_read_b128 v[212:215], v136
	ds_read_b128 v[216:219], v136 offset:1024
	ds_read_b128 v[220:223], v136 offset:2048
	ds_read_b128 v[230:233], v136 offset:3072
	ds_read_b128 v[234:237], v136 offset:4096
	ds_read_b128 v[238:241], v136 offset:5120
	ds_read_b128 v[242:245], v136 offset:6144
	ds_read_b128 v[246:249], v136 offset:7168
	global_load_lds_dwordx4 v[2:3], off
	v_lshl_add_u64 v[2:3], s[36:37], 0, v[10:11]
	s_mov_b32 m0, s84
	s_nop 0
	global_load_lds_dwordx4 v[2:3], off
	s_waitcnt vmcnt(8)
	s_waitcnt lgkmcnt(0)
	s_barrier
	s_setprio 1
	v_mfma_f32_16x16x32_bf16 v[20:23], v[146:149], v[212:215], v[100:103]
	v_mfma_f32_16x16x32_bf16 v[100:103], v[154:157], v[212:215], v[104:107]
	v_mfma_f32_16x16x32_bf16 v[104:107], v[146:149], v[220:223], v[108:111]
	v_mfma_f32_16x16x32_bf16 v[108:111], v[154:157], v[220:223], v[112:115]
	v_mfma_f32_16x16x32_bf16 v[198:201], v[158:161], v[230:233], v[108:111]
	v_mfma_f32_16x16x32_bf16 v[108:111], v[146:149], v[234:237], v[116:119]
	v_mfma_f32_16x16x32_bf16 v[114:117], v[150:153], v[238:241], v[108:111]
	v_mfma_f32_16x16x32_bf16 v[108:111], v[154:157], v[234:237], v[120:123]
	v_mfma_f32_16x16x32_bf16 v[118:121], v[158:161], v[238:241], v[108:111]
	v_mfma_f32_16x16x32_bf16 v[108:111], v[146:149], v[242:245], v[124:127]
	v_mfma_f32_16x16x32_bf16 v[20:23], v[150:153], v[216:219], v[20:23]
	v_mfma_f32_16x16x32_bf16 v[100:103], v[158:161], v[216:219], v[100:103]
	v_mfma_f32_16x16x32_bf16 v[104:107], v[150:153], v[230:233], v[104:107]
	v_mfma_f32_16x16x32_bf16 v[194:197], v[150:153], v[246:249], v[108:111]
	v_mfma_f32_16x16x32_bf16 v[108:111], v[154:157], v[242:245], v[132:135]
	v_mfma_f32_16x16x32_bf16 v[132:135], v[158:161], v[246:249], v[108:111]
	v_mfma_f32_16x16x32_bf16 v[72:75], v[162:165], v[220:223], v[72:75]
	v_mfma_f32_16x16x32_bf16 v[108:111], v[162:165], v[212:215], v[138:141]
	v_mfma_f32_16x16x32_bf16 v[68:71], v[204:207], v[212:215], v[68:71]
	v_mfma_f32_16x16x32_bf16 v[212:215], v[166:169], v[230:233], v[72:75]
	v_mfma_f32_16x16x32_bf16 v[72:75], v[204:207], v[220:223], v[76:79]
	v_mfma_f32_16x16x32_bf16 v[138:141], v[166:169], v[216:219], v[108:111]
	v_mfma_f32_16x16x32_bf16 v[68:71], v[208:211], v[216:219], v[68:71]
	v_mfma_f32_16x16x32_bf16 v[216:219], v[208:211], v[230:233], v[72:75]
	v_mfma_f32_16x16x32_bf16 v[72:75], v[162:165], v[234:237], v[80:83]
	v_mfma_f32_16x16x32_bf16 v[220:223], v[166:169], v[238:241], v[72:75]
	v_mfma_f32_16x16x32_bf16 v[72:75], v[204:207], v[234:237], v[84:87]
	v_mfma_f32_16x16x32_bf16 v[82:85], v[208:211], v[238:241], v[72:75]
	v_mfma_f32_16x16x32_bf16 v[72:75], v[162:165], v[242:245], v[88:91]
	v_mfma_f32_16x16x32_bf16 v[230:233], v[166:169], v[246:249], v[72:75]
	v_mfma_f32_16x16x32_bf16 v[72:75], v[204:207], v[242:245], v[92:95]
	v_mfma_f32_16x16x32_bf16 v[234:237], v[208:211], v[246:249], v[72:75]
	s_setprio 0
	s_barrier
; #define PG8_STAGE(bufoff, gbase, voff) do { _Pragma("unroll") for (int _i = 0; _i < 2; ++_i) \
;         __builtin_amdgcn_global_load_lds((const unsigned*)((const char*)(gbase) + (voff)[_i]), (LAS unsigned*)(lds + (bufoff) + ldsw + _i * 8192), 16, 0, 0); } while (0)
; #define PG8_LDA(dst, b, h) do { _Pragma("unroll") for (int m = 0; m < 4; ++m) _Pragma("unroll") for (int k = 0; k < 2; ++k) dst[m][k] = *(const LAS bf16x8*)(lds + PG8_SA(b, h) + aoff + m * 2048 + k * 1024); } while (0)
; #define PG8_LDB(dst, b, h) do { _Pragma("unroll") for (int n = 0; n < 2; ++n) _Pragma("unroll") for (int k = 0; k < 2; ++k) dst[n][k] = *(const LAS bf16x8*)(lds + PG8_SB(b, h) + boff + n * 2048 + k * 1024); } while (0)
; #define PG8_MMA(ai, bj, At, Bt) do { __builtin_amdgcn_s_setprio(1); _Pragma("unroll") for (int m = 0; m < 4; ++m) _Pragma("unroll") for (int n = 0; n < 2; ++n) _Pragma("unroll") for (int k = 0; k < 2; ++k) \
;         acc[ai][bj][m][n] = __builtin_amdgcn_mfma_f32_16x16x32_bf16(Bt[n][k], At[m][k], acc[ai][bj][m][n], 0, 0, 0); __builtin_amdgcn_s_setprio(0); } while (0)
; #define PG8_WAIT_V(n) asm volatile("s_waitcnt vmcnt(" #n ")" ::: "memory")
; #define PG8_WAIT_L(n) asm volatile("s_waitcnt lgkmcnt(" #n ")" ::: "memory")
; #define PG8_BAR __builtin_amdgcn_s_barrier()
; #define PG8_SCHED __builtin_amdgcn_sched_barrier(0)
; template <class Epi, class Sched>
; __device__ __forceinline__ void gemm_phase(LAS unsigned char* lds, const Gemm g, const Sched& S, const Epi& E, const int tid) {
;     ...
;             PG8_LDA(At, 0, 1); PG8_STAGE(PG8_SB(0, 0), b2, voffB); PG8_STAGE(PG8_SB(0, 1), b2 + hstepB, voffB); PG8_STAGE(PG8_SA(0, 0), a2, voffA);
;             PG8_WAIT_V(8); PG8_WAIT_L(0); PG8_BAR; PG8_MMA(1, 0, At, B0); PG8_MMA(1, 1, At, B1); PG8_BAR; PG8_SCHED;
;             PG8_LDB(B0, 1, 0); PG8_LDB(B1, 1, 1); PG8_SCHED; PG8_LDA(At, 1, 0); PG8_STAGE(PG8_SA(0, 1), a2 + hstepA, voffA);
;             PG8_WAIT_V(8); PG8_WAIT_L(0); PG8_BAR; PG8_MMA(0, 0, At, B0); PG8_MMA(0, 1, At, B1); PG8_BAR; PG8_SCHED;
	s_mov_b32 m0, s83
	s_nop 3
	ds_read_b128 v[72:75], v136 offset:16384
	ds_read_b128 v[76:79], v136 offset:17408
	ds_read_b128 v[86:89], v136 offset:18432
	ds_read_b128 v[90:93], v136 offset:19456
	ds_read_b128 v[108:111], v136 offset:20480
	ds_read_b128 v[122:125], v136 offset:21504
	ds_read_b128 v[126:129], v136 offset:22528
	ds_read_b128 v[238:241], v136 offset:23552
	global_load_lds_dwordx4 v[4:5], off
	s_mov_b32 m0, s82
	s_nop 0
	global_load_lds_dwordx4 v[8:9], off
	s_mov_b32 m0, s81
	s_nop 0
	global_load_lds_dwordx4 v[12:13], off
	s_mov_b32 m0, s80
	s_nop 0
	global_load_lds_dwordx4 v[14:15], off
	s_mov_b32 m0, s15
	s_nop 0
	global_load_lds_dwordx4 v[16:17], off
	s_mov_b32 m0, s59
	s_nop 0
	global_load_lds_dwordx4 v[18:19], off
	s_waitcnt vmcnt(8)
	s_waitcnt lgkmcnt(0)
	s_barrier
	s_setprio 1
	v_mfma_f32_16x16x32_bf16 v[8:11], v[146:149], v[72:75], v[170:173]
	v_mfma_f32_16x16x32_bf16 v[12:15], v[154:157], v[72:75], v[174:177]
	v_mfma_f32_16x16x32_bf16 v[16:19], v[146:149], v[86:89], v[178:181]
	v_mfma_f32_16x16x32_bf16 v[36:39], v[146:149], v[126:129], v[36:39]
	v_mfma_f32_16x16x32_bf16 v[8:11], v[150:153], v[76:79], v[8:11]
	v_mfma_f32_16x16x32_bf16 v[12:15], v[158:161], v[76:79], v[12:15]
	v_mfma_f32_16x16x32_bf16 v[16:19], v[150:153], v[90:93], v[16:19]
	v_mfma_f32_16x16x32_bf16 v[170:173], v[154:157], v[86:89], v[182:185]
	v_mfma_f32_16x16x32_bf16 v[174:177], v[146:149], v[108:111], v[186:189]
	v_mfma_f32_16x16x32_bf16 v[178:181], v[154:157], v[108:111], v[190:193]
	v_mfma_f32_16x16x32_bf16 v[36:39], v[150:153], v[238:241], v[36:39]
	v_mfma_f32_16x16x32_bf16 v[40:43], v[154:157], v[126:129], v[40:43]
	v_mfma_f32_16x16x32_bf16 v[170:173], v[158:161], v[90:93], v[170:173]
	v_mfma_f32_16x16x32_bf16 v[174:177], v[150:153], v[122:125], v[174:177]
	v_mfma_f32_16x16x32_bf16 v[178:181], v[158:161], v[122:125], v[178:181]
	v_mfma_f32_16x16x32_bf16 v[146:149], v[158:161], v[238:241], v[40:43]
	v_mfma_f32_16x16x32_bf16 v[40:43], v[162:165], v[72:75], v[44:47]
	v_mfma_f32_16x16x32_bf16 v[150:153], v[166:169], v[76:79], v[40:43]
	v_mfma_f32_16x16x32_bf16 v[40:43], v[204:207], v[72:75], v[48:51]
	v_mfma_f32_16x16x32_bf16 v[154:157], v[208:211], v[76:79], v[40:43]
	v_mfma_f32_16x16x32_bf16 v[40:43], v[162:165], v[86:89], v[60:63]
	v_mfma_f32_16x16x32_bf16 v[158:161], v[166:169], v[90:93], v[40:43]
	v_mfma_f32_16x16x32_bf16 v[40:43], v[204:207], v[86:89], v[64:67]
	v_mfma_f32_16x16x32_bf16 v[182:185], v[208:211], v[90:93], v[40:43]
	v_mfma_f32_16x16x32_bf16 v[40:43], v[162:165], v[108:111], v[96:99]
	v_mfma_f32_16x16x32_bf16 v[186:189], v[166:169], v[122:125], v[40:43]
	v_mfma_f32_16x16x32_bf16 v[40:43], v[204:207], v[108:111], v[142:145]
	v_mfma_f32_16x16x32_bf16 v[142:145], v[208:211], v[122:125], v[40:43]
	v_mfma_f32_16x16x32_bf16 v[40:43], v[162:165], v[126:129], v[52:55]
	v_mfma_f32_16x16x32_bf16 v[162:165], v[166:169], v[238:241], v[40:43]
	v_mfma_f32_16x16x32_bf16 v[40:43], v[204:207], v[126:129], v[56:59]
	v_mfma_f32_16x16x32_bf16 v[166:169], v[208:211], v[238:241], v[40:43]
	s_setprio 0
	s_barrier
	ds_read_b128 v[50:53], v225
	ds_read_b128 v[54:57], v225 offset:1024
	ds_read_b128 v[190:193], v225 offset:2048
	ds_read_b128 v[204:207], v225 offset:3072
	ds_read_b128 v[208:211], v224
	ds_read_b128 v[238:241], v224 offset:1024
	ds_read_b128 v[242:245], v224 offset:2048
	ds_read_b128 v[246:249], v224 offset:3072
	s_mov_b32 m0, s45
	ds_read_b128 v[40:43], v136 offset:32768
	ds_read_b128 v[44:47], v136 offset:33792
	ds_read_b128 v[58:61], v136 offset:34816
	ds_read_b128 v[62:65], v136 offset:35840
	ds_read_b128 v[2:5], v136 offset:36864
	ds_read_b128 v[72:75], v136 offset:37888
	ds_read_b128 v[76:79], v136 offset:38912
	ds_read_b128 v[224:227], v136 offset:39936
	global_load_lds_dwordx4 v[228:229], off
	s_mov_b32 m0, s58
	s_nop 0
	global_load_lds_dwordx4 v[6:7], off
	s_waitcnt vmcnt(8)
	s_waitcnt lgkmcnt(0)
	s_barrier
; #define PG8_STAGE(bufoff, gbase, voff) do { _Pragma("unroll") for (int _i = 0; _i < 2; ++_i) \
;         __builtin_amdgcn_global_load_lds((const unsigned*)((const char*)(gbase) + (voff)[_i]), (LAS unsigned*)(lds + (bufoff) + ldsw + _i * 8192), 16, 0, 0); } while (0)
; #define PG8_LDA(dst, b, h) do { _Pragma("unroll") for (int m = 0; m < 4; ++m) _Pragma("unroll") for (int k = 0; k < 2; ++k) dst[m][k] = *(const LAS bf16x8*)(lds + PG8_SA(b, h) + aoff + m * 2048 + k * 1024); } while (0)
; #define PG8_MMA(ai, bj, At, Bt) do { __builtin_amdgcn_s_setprio(1); _Pragma("unroll") for (int m = 0; m < 4; ++m) _Pragma("unroll") for (int n = 0; n < 2; ++n) _Pragma("unroll") for (int k = 0; k < 2; ++k) \
;         acc[ai][bj][m][n] = __builtin_amdgcn_mfma_f32_16x16x32_bf16(Bt[n][k], At[m][k], acc[ai][bj][m][n], 0, 0, 0); __builtin_amdgcn_s_setprio(0); } while (0)
; #define PG8_WAIT_V(n) asm volatile("s_waitcnt vmcnt(" #n ")" ::: "memory")
; #define PG8_WAIT_L(n) asm volatile("s_waitcnt lgkmcnt(" #n ")" ::: "memory")
; #define PG8_BAR __builtin_amdgcn_s_barrier()
; #define PG8_SCHED __builtin_amdgcn_sched_barrier(0)
; template <class Epi, class Sched>
; __device__ __forceinline__ void gemm_phase(LAS unsigned char* lds, const Gemm g, const Sched& S, const Epi& E, const int tid) {
;     ...
;             PG8_WAIT_V(8); PG8_WAIT_L(0); PG8_BAR; PG8_MMA(0, 0, At, B0); PG8_MMA(0, 1, At, B1); PG8_BAR; PG8_SCHED;
;             PG8_LDA(At, 1, 1); PG8_STAGE(PG8_SB(1, 0), b3, voffB); PG8_STAGE(PG8_SB(1, 1), b3 + hstepB, voffB); PG8_STAGE(PG8_SA(1, 0), a3, voffA);
;             PG8_WAIT_V(8); PG8_WAIT_L(0); PG8_BAR; PG8_MMA(1, 0, At, B0); PG8_MMA(1, 1, At, B1); PG8_BAR; PG8_SCHED;
;         }
;         if (wr == 0) PG8_BAR;
	s_setprio 1
	v_mfma_f32_16x16x32_bf16 v[20:23], v[50:53], v[40:43], v[20:23]
	v_mfma_f32_16x16x32_bf16 v[122:125], v[54:57], v[44:47], v[20:23]
	v_mfma_f32_16x16x32_bf16 v[20:23], v[190:193], v[40:43], v[100:103]
	v_mfma_f32_16x16x32_bf16 v[126:129], v[204:207], v[44:47], v[20:23]
	v_mfma_f32_16x16x32_bf16 v[20:23], v[50:53], v[58:61], v[104:107]
	v_mfma_f32_16x16x32_bf16 v[110:113], v[54:57], v[62:65], v[20:23]
	v_mfma_f32_16x16x32_bf16 v[20:23], v[190:193], v[58:61], v[198:201]
	v_mfma_f32_16x16x32_bf16 v[106:109], v[204:207], v[62:65], v[20:23]
	v_mfma_f32_16x16x32_bf16 v[20:23], v[50:53], v[2:5], v[114:117]
	v_mfma_f32_16x16x32_bf16 v[94:97], v[54:57], v[72:75], v[20:23]
	v_mfma_f32_16x16x32_bf16 v[20:23], v[190:193], v[2:5], v[118:121]
	v_mfma_f32_16x16x32_bf16 v[90:93], v[204:207], v[72:75], v[20:23]
	v_mfma_f32_16x16x32_bf16 v[20:23], v[50:53], v[76:79], v[194:197]
	v_mfma_f32_16x16x32_bf16 v[198:201], v[54:57], v[224:227], v[20:23]
	v_mfma_f32_16x16x32_bf16 v[20:23], v[190:193], v[76:79], v[132:135]
	v_mfma_f32_16x16x32_bf16 v[194:197], v[204:207], v[224:227], v[20:23]
	v_mfma_f32_16x16x32_bf16 v[20:23], v[208:211], v[40:43], v[138:141]
	v_mfma_f32_16x16x32_bf16 v[118:121], v[238:241], v[44:47], v[20:23]
	v_mfma_f32_16x16x32_bf16 v[20:23], v[242:245], v[40:43], v[68:71]
	v_mfma_f32_16x16x32_bf16 v[114:117], v[246:249], v[44:47], v[20:23]
	v_mfma_f32_16x16x32_bf16 v[20:23], v[208:211], v[58:61], v[212:215]
	v_mfma_f32_16x16x32_bf16 v[102:105], v[238:241], v[62:65], v[20:23]
	v_mfma_f32_16x16x32_bf16 v[20:23], v[242:245], v[58:61], v[216:219]
	v_mfma_f32_16x16x32_bf16 v[98:101], v[246:249], v[62:65], v[20:23]
	v_mfma_f32_16x16x32_bf16 v[20:23], v[208:211], v[2:5], v[220:223]
	v_mfma_f32_16x16x32_bf16 v[2:5], v[242:245], v[2:5], v[82:85]
	v_mfma_f32_16x16x32_bf16 v[82:85], v[246:249], v[72:75], v[2:5]
	v_mfma_f32_16x16x32_bf16 v[2:5], v[208:211], v[76:79], v[230:233]
	v_mfma_f32_16x16x32_bf16 v[86:89], v[238:241], v[72:75], v[20:23]
	v_mfma_f32_16x16x32_bf16 v[70:73], v[238:241], v[224:227], v[2:5]
	v_mfma_f32_16x16x32_bf16 v[2:5], v[242:245], v[76:79], v[234:237]
	v_mfma_f32_16x16x32_bf16 v[66:69], v[246:249], v[224:227], v[2:5]
	s_setprio 0
	s_barrier
	s_mov_b32 m0, s40
	s_nop 3
	ds_read_b128 v[2:5], v136 offset:49152
	ds_read_b128 v[20:23], v136 offset:50176
	ds_read_b128 v[74:77], v136 offset:51200
	ds_read_b128 v[78:81], v136 offset:52224
	ds_read_b128 v[132:135], v136 offset:53248
	ds_read_b128 v[138:141], v136 offset:54272
	ds_read_b128 v[212:215], v136 offset:55296
	ds_read_b128 v[216:219], v136 offset:56320
	global_load_lds_dwordx4 v[26:27], off
	s_mov_b32 m0, s76
	s_nop 0
	global_load_lds_dwordx4 v[28:29], off
	s_mov_b32 m0, s78
	s_nop 0
	global_load_lds_dwordx4 v[32:33], off
	s_mov_b32 m0, s79
	s_nop 0
	global_load_lds_dwordx4 v[34:35], off
	s_mov_b32 m0, s41
	s_nop 0
	global_load_lds_dwordx4 v[24:25], off
	s_mov_b32 m0, s77
	s_nop 0
	global_load_lds_dwordx4 v[30:31], off
	s_waitcnt vmcnt(8)
	s_waitcnt lgkmcnt(0)
	s_barrier
	s_setprio 1
	v_mfma_f32_16x16x32_bf16 v[6:9], v[50:53], v[2:5], v[8:11]
	v_mfma_f32_16x16x32_bf16 v[62:65], v[54:57], v[20:23], v[6:9]
	v_mfma_f32_16x16x32_bf16 v[6:9], v[190:193], v[2:5], v[12:15]
	v_mfma_f32_16x16x32_bf16 v[58:61], v[204:207], v[20:23], v[6:9]
	v_mfma_f32_16x16x32_bf16 v[6:9], v[50:53], v[74:77], v[16:19]
	v_mfma_f32_16x16x32_bf16 v[46:49], v[54:57], v[78:81], v[6:9]
	v_mfma_f32_16x16x32_bf16 v[6:9], v[190:193], v[74:77], v[170:173]
	v_mfma_f32_16x16x32_bf16 v[42:45], v[204:207], v[78:81], v[6:9]
	v_mfma_f32_16x16x32_bf16 v[6:9], v[50:53], v[132:135], v[174:177]
	v_mfma_f32_16x16x32_bf16 v[30:33], v[54:57], v[138:141], v[6:9]
	v_mfma_f32_16x16x32_bf16 v[6:9], v[190:193], v[132:135], v[178:181]
	v_mfma_f32_16x16x32_bf16 v[26:29], v[204:207], v[138:141], v[6:9]
	v_mfma_f32_16x16x32_bf16 v[6:9], v[50:53], v[212:215], v[36:39]
	v_mfma_f32_16x16x32_bf16 v[14:17], v[54:57], v[216:219], v[6:9]
	v_mfma_f32_16x16x32_bf16 v[6:9], v[190:193], v[212:215], v[146:149]
	v_mfma_f32_16x16x32_bf16 v[10:13], v[204:207], v[216:219], v[6:9]
	v_mfma_f32_16x16x32_bf16 v[6:9], v[208:211], v[2:5], v[150:153]
	v_mfma_f32_16x16x32_bf16 v[2:5], v[242:245], v[2:5], v[154:157]
	v_mfma_f32_16x16x32_bf16 v[50:53], v[246:249], v[20:23], v[2:5]
	v_mfma_f32_16x16x32_bf16 v[2:5], v[208:211], v[74:77], v[158:161]
	v_mfma_f32_16x16x32_bf16 v[38:41], v[238:241], v[78:81], v[2:5]
	v_mfma_f32_16x16x32_bf16 v[2:5], v[242:245], v[74:77], v[182:185]
	v_mfma_f32_16x16x32_bf16 v[34:37], v[246:249], v[78:81], v[2:5]
	v_mfma_f32_16x16x32_bf16 v[2:5], v[208:211], v[132:135], v[186:189]
	v_mfma_f32_16x16x32_bf16 v[54:57], v[238:241], v[20:23], v[6:9]
	v_mfma_f32_16x16x32_bf16 v[22:25], v[238:241], v[138:141], v[2:5]
	v_mfma_f32_16x16x32_bf16 v[2:5], v[242:245], v[132:135], v[142:145]
	v_mfma_f32_16x16x32_bf16 v[18:21], v[246:249], v[138:141], v[2:5]
	v_mfma_f32_16x16x32_bf16 v[2:5], v[208:211], v[212:215], v[162:165]
	v_mfma_f32_16x16x32_bf16 v[6:9], v[238:241], v[216:219], v[2:5]
	v_mfma_f32_16x16x32_bf16 v[2:5], v[242:245], v[212:215], v[166:169]
	v_mfma_f32_16x16x32_bf16 v[2:5], v[246:249], v[216:219], v[2:5]
	s_setprio 0
	s_barrier
	s_cbranch_scc1 .LBB1_356
	s_barrier

; #define PG8_STAGE(bufoff, gbase, voff) do { _Pragma("unroll") for (int _i = 0; _i < 2; ++_i) \
;         __builtin_amdgcn_global_load_lds((const unsigned*)((const char*)(gbase) + (voff)[_i]), (LAS unsigned*)(lds + (bufoff) + ldsw + _i * 8192), 16, 0, 0); } while (0)
; #define PG8_LDA(dst, b, h) do { _Pragma("unroll") for (int m = 0; m < 4; ++m) _Pragma("unroll") for (int k = 0; k < 2; ++k) dst[m][k] = *(const LAS bf16x8*)(lds + PG8_SA(b, h) + aoff + m * 2048 + k * 1024); } while (0)
; #define PG8_BAR __builtin_amdgcn_s_barrier()
; template <class Epi, class Sched>
; __device__ __forceinline__ void gemm_phase(LAS unsigned char* lds, const Gemm g, const Sched& S, const Epi& E, const int tid) {
;     ...
;     const char* cA = (const char*)g.A + (size_t)cur.pm * tstepA + (size_t)cur.aoff * 2; const char* cB = (const char*)g.Bt + (size_t)cur.pn * tstepB;
;     PG8_STAGE(PG8_SB(0, 0), cB, voffB); PG8_STAGE(PG8_SB(0, 1), cB + hstepB, voffB); PG8_STAGE(PG8_SA(0, 0), cA, voffA); PG8_STAGE(PG8_SA(0, 1), cA + hstepA, voffA);
;     if (wr == 1) PG8_BAR;
;     PG8_WAIT_V(2); PG8_BAR;
;     PG8_STAGE(PG8_SB(1, 0), cB + kstep, voffB); PG8_STAGE(PG8_SA(1, 0), cA + kstep, voffA); PG8_STAGE(PG8_SB(1, 1), cB + hstepB + kstep, voffB);
;     PG8_WAIT_V(6); PG8_BAR;
;     for (;;) {
;         const bool has_next = S.next(ui + 1, nxt);
;         const char* nA = has_next ? (const char*)g.A + (size_t)nxt.pm * tstepA + (size_t)nxt.aoff * 2 : cA; const char* nB = has_next ? (const char*)g.Bt + (size_t)nxt.pn * tstepB : cB;
;         for (int t = 0; t < nt; t += 2) {
;             const bool last = (t == nt - 2);
;             const char* a1 = cA + (size_t)(t + 1) * kstep;
;             const char* a2 = last ? nA : cA + (size_t)(t + 2) * kstep; const char* b2 = last ? nB : cB + (size_t)(t + 2) * kstep;
;             const char* a3 = a2 + kstep; const char* b3 = b2 + kstep;
;             PG8_LDB(B0, 0, 0); PG8_LDB(B1, 0, 1); PG8_SCHED; PG8_LDA(At, 0, 0); PG8_STAGE(PG8_SA(1, 1), a1 + hstepA, voffA);
;             PG8_WAIT_V(8); PG8_WAIT_L(0); PG8_BAR; PG8_MMA(0, 0, At, B0); PG8_MMA(0, 1, At, B1); PG8_BAR; PG8_SCHED;
;             PG8_LDA(At, 0, 1); PG8_STAGE(PG8_SB(0, 0), b2, voffB); PG8_STAGE(PG8_SB(0, 1), b2 + hstepB, voffB); PG8_STAGE(PG8_SA(0, 0), a2, voffA);
;             PG8_WAIT_V(8); PG8_WAIT_L(0); PG8_BAR; PG8_MMA(1, 0, At, B0); PG8_MMA(1, 1, At, B1); PG8_BAR; PG8_SCHED;
.LBB1_374:
	v_and_b32_e32 v25, 15, v24
	v_lshrrev_b32_e32 v24, 1, v24
	v_and_b32_e32 v133, 24, v24
	v_lshlrev_b32_e32 v24, 1, v133
	v_lshlrev_b32_e32 v130, 2, v25
	v_lshl_or_b32 v131, s61, 6, v25
	v_lshl_or_b32 v24, v25, 6, v24
	s_lshl_b32 s36, s61, 13
	v_and_b32_e32 v25, 32, v130
	v_bitop3_b32 v36, v24, s36, v25 bitop3:0xde
	s_lshl_b32 s36, s58, 5
	s_and_b32 s58, s36, 0x60
	s_lshl_b32 s36, s58, 7
	s_add_u32 s82, s26, 0x20080
	s_addc_u32 s83, s27, 0
	s_add_u32 s70, s38, 0x300080
	s_addc_u32 s71, s39, 0
	s_add_u32 s68, s26, 0x20100
	s_addc_u32 s69, s27, 0
	s_add_u32 s40, s38, 0x300100
	s_addc_u32 s41, s39, 0
	v_bitop3_b32 v37, s36, v24, v25 bitop3:0xf6
	s_add_u32 s36, s26, 0x20180
	s_addc_u32 s37, s27, 0
	s_add_u32 s26, s38, 0x300180
	s_addc_u32 s27, s39, 0
	s_add_i32 s38, s47, s80
	v_lshl_add_u64 v[26:27], v[4:5], 0, s[90:91]
	s_mov_b32 m0, s38
	s_add_i32 s61, s38, 0x2000
	s_waitcnt vmcnt(2)
	s_barrier
	global_load_lds_dwordx4 v[26:27], off
	v_lshl_add_u64 v[28:29], v[8:9], 0, s[90:91]
	s_mov_b32 m0, s61
	s_add_i32 s39, s14, 0x8000
	global_load_lds_dwordx4 v[28:29], off
	v_lshl_add_u64 v[24:25], v[16:17], 0, s[90:91]
	s_mov_b32 m0, s39
	s_add_i32 s74, s14, 0xa000
	global_load_lds_dwordx4 v[24:25], off
	v_lshl_add_u64 v[30:31], v[18:19], 0, s[90:91]
	s_mov_b32 m0, s74
	s_add_i32 s75, s56, s80
	global_load_lds_dwordx4 v[30:31], off
	v_lshl_add_u64 v[32:33], s[82:83], 0, v[0:1]
	s_mov_b32 m0, s75
	s_add_i32 s79, s75, 0x2000
	global_load_lds_dwordx4 v[32:33], off
	v_lshl_add_u64 v[34:35], s[82:83], 0, v[22:23]
	s_mov_b32 m0, s79
	v_add_u32_e32 v237, s60, v37
	global_load_lds_dwordx4 v[34:35], off
	s_waitcnt vmcnt(6)
	s_barrier
	v_add_u32_e32 v132, 0, v36
	v_add_u32_e32 v244, s56, v37
	v_add_u32_e32 v245, s47, v37
	v_add_u32_e32 v236, s57, v37
	ds_read_b128 v[36:39], v237
	ds_read_b128 v[40:43], v237 offset:1024
	ds_read_b128 v[44:47], v237 offset:2048
	ds_read_b128 v[48:51], v237 offset:3072
	ds_read_b128 v[52:55], v236
	ds_read_b128 v[56:59], v236 offset:1024
	ds_read_b128 v[60:63], v236 offset:2048
	ds_read_b128 v[64:67], v236 offset:3072
	s_add_i32 s83, s60, s80
	s_add_i32 s81, s57, s80
	s_add_i32 s85, s14, 0xc000
	s_add_i32 s84, s14, 0xe000
	s_add_i32 s82, s83, 0x2000
	s_add_i32 s80, s81, 0x2000
	s_cmpk_gt_u32 s44, 0xff
	s_mov_b32 m0, s85
	v_lshl_add_u64 v[100:101], s[70:71], 0, v[20:21]
	ds_read_b128 v[68:71], v132
	ds_read_b128 v[72:75], v132 offset:1024
	ds_read_b128 v[76:79], v132 offset:2048
	ds_read_b128 v[80:83], v132 offset:3072
	ds_read_b128 v[84:87], v132 offset:4096
	ds_read_b128 v[88:91], v132 offset:5120
	ds_read_b128 v[92:95], v132 offset:6144
	ds_read_b128 v[96:99], v132 offset:7168
	global_load_lds_dwordx4 v[100:101], off
	v_lshl_add_u64 v[100:101], s[70:71], 0, v[10:11]
	s_mov_b32 m0, s84
	s_nop 0
	global_load_lds_dwordx4 v[100:101], off
	s_waitcnt vmcnt(8)
	s_waitcnt lgkmcnt(0)
	s_barrier
	s_setprio 1
	v_mfma_f32_16x16x32_bf16 v[100:103], v[36:39], v[68:71], 0
	v_mfma_f32_16x16x32_bf16 v[104:107], v[44:47], v[68:71], 0
	v_mfma_f32_16x16x32_bf16 v[108:111], v[36:39], v[76:79], 0
	v_mfma_f32_16x16x32_bf16 v[112:115], v[44:47], v[76:79], 0
	v_mfma_f32_16x16x32_bf16 v[116:119], v[36:39], v[84:87], 0
	v_mfma_f32_16x16x32_bf16 v[120:123], v[44:47], v[84:87], 0
	v_mfma_f32_16x16x32_bf16 v[124:127], v[36:39], v[92:95], 0
	v_mfma_f32_16x16x32_bf16 v[100:103], v[40:43], v[72:75], v[100:103]
	v_mfma_f32_16x16x32_bf16 v[104:107], v[48:51], v[72:75], v[104:107]
	v_mfma_f32_16x16x32_bf16 v[108:111], v[40:43], v[80:83], v[108:111]
	v_mfma_f32_16x16x32_bf16 v[112:115], v[48:51], v[80:83], v[112:115]
	v_mfma_f32_16x16x32_bf16 v[116:119], v[40:43], v[88:91], v[116:119]
	v_mfma_f32_16x16x32_bf16 v[120:123], v[48:51], v[88:91], v[120:123]
	v_mfma_f32_16x16x32_bf16 v[124:127], v[40:43], v[96:99], v[124:127]
	v_mfma_f32_16x16x32_bf16 v[134:137], v[44:47], v[92:95], 0
	v_mfma_f32_16x16x32_bf16 v[134:137], v[48:51], v[96:99], v[134:137]
	v_mfma_f32_16x16x32_bf16 v[138:141], v[52:55], v[68:71], 0
	v_mfma_f32_16x16x32_bf16 v[68:71], v[60:63], v[68:71], 0
	v_mfma_f32_16x16x32_bf16 v[138:141], v[56:59], v[72:75], v[138:141]
	v_mfma_f32_16x16x32_bf16 v[68:71], v[64:67], v[72:75], v[68:71]
	v_mfma_f32_16x16x32_bf16 v[72:75], v[52:55], v[76:79], 0
	v_mfma_f32_16x16x32_bf16 v[76:79], v[60:63], v[76:79], 0
	v_mfma_f32_16x16x32_bf16 v[72:75], v[56:59], v[80:83], v[72:75]
	v_mfma_f32_16x16x32_bf16 v[76:79], v[64:67], v[80:83], v[76:79]
	v_mfma_f32_16x16x32_bf16 v[80:83], v[52:55], v[84:87], 0
	v_mfma_f32_16x16x32_bf16 v[84:87], v[60:63], v[84:87], 0
	v_mfma_f32_16x16x32_bf16 v[80:83], v[56:59], v[88:91], v[80:83]
	v_mfma_f32_16x16x32_bf16 v[84:87], v[64:67], v[88:91], v[84:87]
	v_mfma_f32_16x16x32_bf16 v[88:91], v[52:55], v[92:95], 0
	v_mfma_f32_16x16x32_bf16 v[92:95], v[60:63], v[92:95], 0
	v_mfma_f32_16x16x32_bf16 v[88:91], v[56:59], v[96:99], v[88:91]
	v_mfma_f32_16x16x32_bf16 v[92:95], v[64:67], v[96:99], v[92:95]
	s_setprio 0
	s_barrier
	s_mov_b32 m0, s83
	v_lshl_add_u64 v[128:129], v[4:5], 0, s[0:1]
	ds_read_b128 v[96:99], v132 offset:16384
	ds_read_b128 v[142:145], v132 offset:17408
	ds_read_b128 v[146:149], v132 offset:18432
	ds_read_b128 v[150:153], v132 offset:19456
	ds_read_b128 v[154:157], v132 offset:20480
	ds_read_b128 v[158:161], v132 offset:21504
	ds_read_b128 v[162:165], v132 offset:22528
	ds_read_b128 v[166:169], v132 offset:23552
	global_load_lds_dwordx4 v[128:129], off
	v_lshl_add_u64 v[128:129], v[8:9], 0, s[0:1]
	s_mov_b32 m0, s82
	s_nop 0
	global_load_lds_dwordx4 v[128:129], off
	v_lshl_add_u64 v[128:129], s[68:69], 0, v[0:1]
	s_mov_b32 m0, s81
	s_nop 0
	global_load_lds_dwordx4 v[128:129], off
	v_lshl_add_u64 v[128:129], s[68:69], 0, v[22:23]
	s_mov_b32 m0, s80
	s_nop 0
	global_load_lds_dwordx4 v[128:129], off
	v_lshl_add_u64 v[128:129], v[16:17], 0, s[0:1]
	s_mov_b32 m0, s14
	s_nop 0
	global_load_lds_dwordx4 v[128:129], off
	v_lshl_add_u64 v[128:129], v[18:19], 0, s[0:1]
	s_mov_b32 m0, s59
	s_nop 0
	global_load_lds_dwordx4 v[128:129], off
	s_waitcnt vmcnt(8)
	s_waitcnt lgkmcnt(0)
	s_barrier
; #define PG8_STAGE(bufoff, gbase, voff) do { _Pragma("unroll") for (int _i = 0; _i < 2; ++_i) \
;         __builtin_amdgcn_global_load_lds((const unsigned*)((const char*)(gbase) + (voff)[_i]), (LAS unsigned*)(lds + (bufoff) + ldsw + _i * 8192), 16, 0, 0); } while (0)
; #define PG8_LDA(dst, b, h) do { _Pragma("unroll") for (int m = 0; m < 4; ++m) _Pragma("unroll") for (int k = 0; k < 2; ++k) dst[m][k] = *(const LAS bf16x8*)(lds + PG8_SA(b, h) + aoff + m * 2048 + k * 1024); } while (0)
; #define PG8_LDB(dst, b, h) do { _Pragma("unroll") for (int n = 0; n < 2; ++n) _Pragma("unroll") for (int k = 0; k < 2; ++k) dst[n][k] = *(const LAS bf16x8*)(lds + PG8_SB(b, h) + boff + n * 2048 + k * 1024); } while (0)
; #define PG8_MMA(ai, bj, At, Bt) do { __builtin_amdgcn_s_setprio(1); _Pragma("unroll") for (int m = 0; m < 4; ++m) _Pragma("unroll") for (int n = 0; n < 2; ++n) _Pragma("unroll") for (int k = 0; k < 2; ++k) \
;         acc[ai][bj][m][n] = __builtin_amdgcn_mfma_f32_16x16x32_bf16(Bt[n][k], At[m][k], acc[ai][bj][m][n], 0, 0, 0); __builtin_amdgcn_s_setprio(0); } while (0)
; #define PG8_WAIT_V(n) asm volatile("s_waitcnt vmcnt(" #n ")" ::: "memory")
; #define PG8_WAIT_L(n) asm volatile("s_waitcnt lgkmcnt(" #n ")" ::: "memory")
; #define PG8_BAR __builtin_amdgcn_s_barrier()
; #define PG8_SCHED __builtin_amdgcn_sched_barrier(0)
; template <class Epi, class Sched>
; __device__ __forceinline__ void gemm_phase(LAS unsigned char* lds, const Gemm g, const Sched& S, const Epi& E, const int tid) {
;     ...
;             PG8_WAIT_V(8); PG8_WAIT_L(0); PG8_BAR; PG8_MMA(1, 0, At, B0); PG8_MMA(1, 1, At, B1); PG8_BAR; PG8_SCHED;
;             PG8_LDB(B0, 1, 0); PG8_LDB(B1, 1, 1); PG8_SCHED; PG8_LDA(At, 1, 0); PG8_STAGE(PG8_SA(0, 1), a2 + hstepA, voffA);
;             PG8_WAIT_V(8); PG8_WAIT_L(0); PG8_BAR; PG8_MMA(0, 0, At, B0); PG8_MMA(0, 1, At, B1); PG8_BAR; PG8_SCHED;
	s_setprio 1
	v_mfma_f32_16x16x32_bf16 v[170:173], v[36:39], v[96:99], 0
	v_mfma_f32_16x16x32_bf16 v[178:181], v[36:39], v[146:149], 0
	v_mfma_f32_16x16x32_bf16 v[186:189], v[36:39], v[154:157], 0
	v_mfma_f32_16x16x32_bf16 v[36:39], v[36:39], v[162:165], 0
	v_mfma_f32_16x16x32_bf16 v[170:173], v[40:43], v[142:145], v[170:173]
	v_mfma_f32_16x16x32_bf16 v[178:181], v[40:43], v[150:153], v[178:181]
	v_mfma_f32_16x16x32_bf16 v[186:189], v[40:43], v[158:161], v[186:189]
	v_mfma_f32_16x16x32_bf16 v[36:39], v[40:43], v[166:169], v[36:39]
	v_mfma_f32_16x16x32_bf16 v[40:43], v[44:47], v[162:165], 0
	v_mfma_f32_16x16x32_bf16 v[174:177], v[44:47], v[96:99], 0
	v_mfma_f32_16x16x32_bf16 v[182:185], v[44:47], v[146:149], 0
	v_mfma_f32_16x16x32_bf16 v[190:193], v[44:47], v[154:157], 0
	v_mfma_f32_16x16x32_bf16 v[40:43], v[48:51], v[166:169], v[40:43]
	v_mfma_f32_16x16x32_bf16 v[174:177], v[48:51], v[142:145], v[174:177]
	v_mfma_f32_16x16x32_bf16 v[182:185], v[48:51], v[150:153], v[182:185]
	v_mfma_f32_16x16x32_bf16 v[190:193], v[48:51], v[158:161], v[190:193]
	v_mfma_f32_16x16x32_bf16 v[44:47], v[52:55], v[96:99], 0
	v_mfma_f32_16x16x32_bf16 v[48:51], v[60:63], v[96:99], 0
	v_mfma_f32_16x16x32_bf16 v[44:47], v[56:59], v[142:145], v[44:47]
	v_mfma_f32_16x16x32_bf16 v[48:51], v[64:67], v[142:145], v[48:51]
	v_mfma_f32_16x16x32_bf16 v[96:99], v[52:55], v[146:149], 0
	v_mfma_f32_16x16x32_bf16 v[142:145], v[60:63], v[146:149], 0
	v_mfma_f32_16x16x32_bf16 v[146:149], v[52:55], v[154:157], 0
	v_mfma_f32_16x16x32_bf16 v[52:55], v[52:55], v[162:165], 0
	v_mfma_f32_16x16x32_bf16 v[96:99], v[56:59], v[150:153], v[96:99]
	v_mfma_f32_16x16x32_bf16 v[146:149], v[56:59], v[158:161], v[146:149]
	v_mfma_f32_16x16x32_bf16 v[52:55], v[56:59], v[166:169], v[52:55]
	v_mfma_f32_16x16x32_bf16 v[56:59], v[60:63], v[162:165], 0
	v_mfma_f32_16x16x32_bf16 v[142:145], v[64:67], v[150:153], v[142:145]
	v_mfma_f32_16x16x32_bf16 v[150:153], v[60:63], v[154:157], 0
	v_mfma_f32_16x16x32_bf16 v[56:59], v[64:67], v[166:169], v[56:59]
	v_mfma_f32_16x16x32_bf16 v[150:153], v[64:67], v[158:161], v[150:153]
	s_setprio 0
	s_barrier
	ds_read_b128 v[60:63], v245
	ds_read_b128 v[64:67], v245 offset:1024
	ds_read_b128 v[154:157], v245 offset:2048
	ds_read_b128 v[158:161], v245 offset:3072
	ds_read_b128 v[162:165], v244
	ds_read_b128 v[166:169], v244 offset:1024
	ds_read_b128 v[194:197], v244 offset:2048
	ds_read_b128 v[198:201], v244 offset:3072
	s_mov_b32 m0, s15
	v_lshl_add_u64 v[128:129], s[40:41], 0, v[20:21]
	ds_read_b128 v[204:207], v132 offset:32768
	ds_read_b128 v[208:211], v132 offset:33792
	ds_read_b128 v[212:215], v132 offset:34816
	ds_read_b128 v[216:219], v132 offset:35840
	ds_read_b128 v[220:223], v132 offset:36864
	ds_read_b128 v[224:227], v132 offset:37888
	ds_read_b128 v[228:231], v132 offset:38912
	ds_read_b128 v[232:235], v132 offset:39936
	global_load_lds_dwordx4 v[128:129], off
	v_lshl_add_u64 v[128:129], s[40:41], 0, v[10:11]
	s_mov_b32 m0, s45
	s_nop 0
	global_load_lds_dwordx4 v[128:129], off
	s_waitcnt vmcnt(8)
	s_waitcnt lgkmcnt(0)
	s_barrier
	s_setprio 1
	v_mfma_f32_16x16x32_bf16 v[100:103], v[60:63], v[204:207], v[100:103]
	v_mfma_f32_16x16x32_bf16 v[104:107], v[154:157], v[204:207], v[104:107]
	v_mfma_f32_16x16x32_bf16 v[108:111], v[60:63], v[212:215], v[108:111]
	v_mfma_f32_16x16x32_bf16 v[112:115], v[154:157], v[212:215], v[112:115]
	v_mfma_f32_16x16x32_bf16 v[116:119], v[60:63], v[220:223], v[116:119]
	v_mfma_f32_16x16x32_bf16 v[120:123], v[154:157], v[220:223], v[120:123]
	v_mfma_f32_16x16x32_bf16 v[124:127], v[60:63], v[228:231], v[124:127]
	v_mfma_f32_16x16x32_bf16 v[100:103], v[64:67], v[208:211], v[100:103]
	v_mfma_f32_16x16x32_bf16 v[104:107], v[158:161], v[208:211], v[104:107]
	v_mfma_f32_16x16x32_bf16 v[108:111], v[64:67], v[216:219], v[108:111]
	v_mfma_f32_16x16x32_bf16 v[112:115], v[158:161], v[216:219], v[112:115]
	v_mfma_f32_16x16x32_bf16 v[116:119], v[64:67], v[224:227], v[116:119]
	v_mfma_f32_16x16x32_bf16 v[120:123], v[158:161], v[224:227], v[120:123]
	v_mfma_f32_16x16x32_bf16 v[124:127], v[64:67], v[232:235], v[124:127]
	v_mfma_f32_16x16x32_bf16 v[134:137], v[154:157], v[228:231], v[134:137]
	v_mfma_f32_16x16x32_bf16 v[134:137], v[158:161], v[232:235], v[134:137]
	v_mfma_f32_16x16x32_bf16 v[68:71], v[194:197], v[204:207], v[68:71]
	v_mfma_f32_16x16x32_bf16 v[72:75], v[162:165], v[212:215], v[72:75]
	v_mfma_f32_16x16x32_bf16 v[76:79], v[194:197], v[212:215], v[76:79]
	v_mfma_f32_16x16x32_bf16 v[80:83], v[162:165], v[220:223], v[80:83]
	v_mfma_f32_16x16x32_bf16 v[84:87], v[194:197], v[220:223], v[84:87]
	v_mfma_f32_16x16x32_bf16 v[88:91], v[162:165], v[228:231], v[88:91]
	v_mfma_f32_16x16x32_bf16 v[92:95], v[194:197], v[228:231], v[92:95]
	v_mfma_f32_16x16x32_bf16 v[138:141], v[162:165], v[204:207], v[138:141]
	v_mfma_f32_16x16x32_bf16 v[68:71], v[198:201], v[208:211], v[68:71]
	v_mfma_f32_16x16x32_bf16 v[72:75], v[166:169], v[216:219], v[72:75]
	v_mfma_f32_16x16x32_bf16 v[76:79], v[198:201], v[216:219], v[76:79]
	v_mfma_f32_16x16x32_bf16 v[80:83], v[166:169], v[224:227], v[80:83]
	v_mfma_f32_16x16x32_bf16 v[84:87], v[198:201], v[224:227], v[84:87]
	v_mfma_f32_16x16x32_bf16 v[88:91], v[166:169], v[232:235], v[88:91]
	v_mfma_f32_16x16x32_bf16 v[92:95], v[198:201], v[232:235], v[92:95]
	v_mfma_f32_16x16x32_bf16 v[138:141], v[166:169], v[208:211], v[138:141]
	s_setprio 0
	s_barrier
; #define PG8_STAGE(bufoff, gbase, voff) do { _Pragma("unroll") for (int _i = 0; _i < 2; ++_i) \
;         __builtin_amdgcn_global_load_lds((const unsigned*)((const char*)(gbase) + (voff)[_i]), (LAS unsigned*)(lds + (bufoff) + ldsw + _i * 8192), 16, 0, 0); } while (0)
; #define PG8_LDA(dst, b, h) do { _Pragma("unroll") for (int m = 0; m < 4; ++m) _Pragma("unroll") for (int k = 0; k < 2; ++k) dst[m][k] = *(const LAS bf16x8*)(lds + PG8_SA(b, h) + aoff + m * 2048 + k * 1024); } while (0)
; #define PG8_LDB(dst, b, h) do { _Pragma("unroll") for (int n = 0; n < 2; ++n) _Pragma("unroll") for (int k = 0; k < 2; ++k) dst[n][k] = *(const LAS bf16x8*)(lds + PG8_SB(b, h) + boff + n * 2048 + k * 1024); } while (0)
; #define PG8_WAIT_V(n) asm volatile("s_waitcnt vmcnt(" #n ")" ::: "memory")
; #define PG8_BAR __builtin_amdgcn_s_barrier()
; template <class Epi, class Sched>
; __device__ __forceinline__ void gemm_phase(LAS unsigned char* lds, const Gemm g, const Sched& S, const Epi& E, const int tid) {
;     ...
;         for (int t = 0; t < nt; t += 2) {
;             const bool last = (t == nt - 2);
;             const char* a1 = cA + (size_t)(t + 1) * kstep;
;             const char* a2 = last ? nA : cA + (size_t)(t + 2) * kstep; const char* b2 = last ? nB : cB + (size_t)(t + 2) * kstep;
;             const char* a3 = a2 + kstep; const char* b3 = b2 + kstep;
;             PG8_LDB(B0, 0, 0); PG8_LDB(B1, 0, 1); PG8_SCHED; PG8_LDA(At, 0, 0); PG8_STAGE(PG8_SA(1, 1), a1 + hstepA, voffA);
;             PG8_WAIT_V(8); PG8_WAIT_L(0); PG8_BAR; PG8_MMA(0, 0, At, B0); PG8_MMA(0, 1, At, B1); PG8_BAR; PG8_SCHED;
;             PG8_LDA(At, 0, 1); PG8_STAGE(PG8_SB(0, 0), b2, voffB); PG8_STAGE(PG8_SB(0, 1), b2 + hstepB, voffB); PG8_STAGE(PG8_SA(0, 0), a2, voffA);
;             PG8_WAIT_V(8); PG8_WAIT_L(0); PG8_BAR; PG8_MMA(1, 0, At, B0); PG8_MMA(1, 1, At, B1); PG8_BAR; PG8_SCHED;
;             PG8_LDB(B0, 1, 0); PG8_LDB(B1, 1, 1); PG8_SCHED; PG8_LDA(At, 1, 0); PG8_STAGE(PG8_SA(0, 1), a2 + hstepA, voffA);
;             PG8_WAIT_V(8); PG8_WAIT_L(0); PG8_BAR; PG8_MMA(0, 0, At, B0); PG8_MMA(0, 1, At, B1); PG8_BAR; PG8_SCHED;
;             PG8_LDA(At, 1, 1); PG8_STAGE(PG8_SB(1, 0), b3, voffB); PG8_STAGE(PG8_SB(1, 1), b3 + hstepB, voffB); PG8_STAGE(PG8_SA(1, 0), a3, voffA);
;             PG8_WAIT_V(8); PG8_WAIT_L(0); PG8_BAR; PG8_MMA(1, 0, At, B0); PG8_MMA(1, 1, At, B1); PG8_BAR; PG8_SCHED;
	s_mov_b32 m0, s38
	v_lshl_add_u64 v[128:129], v[4:5], 0, s[16:17]
	ds_read_b128 v[204:207], v132 offset:49152
	ds_read_b128 v[208:211], v132 offset:50176
	ds_read_b128 v[212:215], v132 offset:51200
	ds_read_b128 v[216:219], v132 offset:52224
	ds_read_b128 v[220:223], v132 offset:53248
	ds_read_b128 v[224:227], v132 offset:54272
	ds_read_b128 v[228:231], v132 offset:55296
	ds_read_b128 v[232:235], v132 offset:56320
	global_load_lds_dwordx4 v[128:129], off
	v_lshl_add_u64 v[128:129], v[8:9], 0, s[16:17]
	s_mov_b32 m0, s61
	v_lshl_add_u64 v[22:23], s[36:37], 0, v[22:23]
	global_load_lds_dwordx4 v[128:129], off
	v_lshl_add_u64 v[128:129], s[36:37], 0, v[0:1]
	s_mov_b32 m0, s75
	s_nop 0
	global_load_lds_dwordx4 v[128:129], off
	s_mov_b32 m0, s79
	s_nop 0
	global_load_lds_dwordx4 v[22:23], off
	v_lshl_add_u64 v[22:23], v[16:17], 0, s[16:17]
	s_mov_b32 m0, s39
	s_nop 0
	global_load_lds_dwordx4 v[22:23], off
	v_lshl_add_u64 v[22:23], v[18:19], 0, s[16:17]
	s_mov_b32 m0, s74
	s_nop 0
	global_load_lds_dwordx4 v[22:23], off
	s_waitcnt vmcnt(8)
	s_waitcnt lgkmcnt(0)
	s_barrier
	s_setprio 1
	v_mfma_f32_16x16x32_bf16 v[36:39], v[60:63], v[228:231], v[36:39]
	v_mfma_f32_16x16x32_bf16 v[40:43], v[154:157], v[228:231], v[40:43]
	v_mfma_f32_16x16x32_bf16 v[170:173], v[60:63], v[204:207], v[170:173]
	v_mfma_f32_16x16x32_bf16 v[174:177], v[154:157], v[204:207], v[174:177]
	v_mfma_f32_16x16x32_bf16 v[178:181], v[60:63], v[212:215], v[178:181]
	v_mfma_f32_16x16x32_bf16 v[182:185], v[154:157], v[212:215], v[182:185]
	v_mfma_f32_16x16x32_bf16 v[186:189], v[60:63], v[220:223], v[186:189]
	v_mfma_f32_16x16x32_bf16 v[190:193], v[154:157], v[220:223], v[190:193]
	v_mfma_f32_16x16x32_bf16 v[36:39], v[64:67], v[232:235], v[36:39]
	v_mfma_f32_16x16x32_bf16 v[40:43], v[158:161], v[232:235], v[40:43]
	v_mfma_f32_16x16x32_bf16 v[170:173], v[64:67], v[208:211], v[170:173]
	v_mfma_f32_16x16x32_bf16 v[174:177], v[158:161], v[208:211], v[174:177]
	v_mfma_f32_16x16x32_bf16 v[178:181], v[64:67], v[216:219], v[178:181]
	v_mfma_f32_16x16x32_bf16 v[182:185], v[158:161], v[216:219], v[182:185]
	v_mfma_f32_16x16x32_bf16 v[186:189], v[64:67], v[224:227], v[186:189]
	v_mfma_f32_16x16x32_bf16 v[190:193], v[158:161], v[224:227], v[190:193]
	v_mfma_f32_16x16x32_bf16 v[44:47], v[162:165], v[204:207], v[44:47]
	v_mfma_f32_16x16x32_bf16 v[48:51], v[194:197], v[204:207], v[48:51]
	v_mfma_f32_16x16x32_bf16 v[60:63], v[162:165], v[212:215], v[96:99]
	v_mfma_f32_16x16x32_bf16 v[64:67], v[194:197], v[212:215], v[142:145]
	v_mfma_f32_16x16x32_bf16 v[96:99], v[162:165], v[220:223], v[146:149]
	v_mfma_f32_16x16x32_bf16 v[52:55], v[162:165], v[228:231], v[52:55]
	v_mfma_f32_16x16x32_bf16 v[56:59], v[194:197], v[228:231], v[56:59]
	v_mfma_f32_16x16x32_bf16 v[44:47], v[166:169], v[208:211], v[44:47]
	v_mfma_f32_16x16x32_bf16 v[48:51], v[198:201], v[208:211], v[48:51]
	v_mfma_f32_16x16x32_bf16 v[60:63], v[166:169], v[216:219], v[60:63]
	v_mfma_f32_16x16x32_bf16 v[64:67], v[198:201], v[216:219], v[64:67]
	v_mfma_f32_16x16x32_bf16 v[96:99], v[166:169], v[224:227], v[96:99]
	v_mfma_f32_16x16x32_bf16 v[142:145], v[194:197], v[220:223], v[150:153]
	v_mfma_f32_16x16x32_bf16 v[52:55], v[166:169], v[232:235], v[52:55]
	v_mfma_f32_16x16x32_bf16 v[56:59], v[198:201], v[232:235], v[56:59]
	v_mfma_f32_16x16x32_bf16 v[142:145], v[198:201], v[224:227], v[142:145]
	s_setprio 0
	s_barrier
	ds_read_b128 v[146:149], v237
	ds_read_b128 v[150:153], v237 offset:1024
	ds_read_b128 v[154:157], v237 offset:2048
	ds_read_b128 v[158:161], v237 offset:3072
	ds_read_b128 v[162:165], v236
	ds_read_b128 v[166:169], v236 offset:1024
	ds_read_b128 v[194:197], v236 offset:2048
	ds_read_b128 v[198:201], v236 offset:3072
	s_mov_b32 m0, s85
	v_lshl_add_u64 v[20:21], s[26:27], 0, v[20:21]
	ds_read_b128 v[204:207], v132
	ds_read_b128 v[208:211], v132 offset:1024
	ds_read_b128 v[212:215], v132 offset:2048
	ds_read_b128 v[216:219], v132 offset:3072
	ds_read_b128 v[220:223], v132 offset:4096
	ds_read_b128 v[224:227], v132 offset:5120
	ds_read_b128 v[228:231], v132 offset:6144
	ds_read_b128 v[232:235], v132 offset:7168
	global_load_lds_dwordx4 v[20:21], off
	v_lshl_add_u64 v[10:11], s[26:27], 0, v[10:11]
	s_mov_b32 m0, s84
	s_nop 0
	global_load_lds_dwordx4 v[10:11], off
	s_waitcnt vmcnt(8)
	s_waitcnt lgkmcnt(0)
	s_barrier
	s_setprio 1
	v_mfma_f32_16x16x32_bf16 v[20:23], v[146:149], v[204:207], v[100:103]
	v_mfma_f32_16x16x32_bf16 v[100:103], v[154:157], v[204:207], v[104:107]
	v_mfma_f32_16x16x32_bf16 v[104:107], v[146:149], v[212:215], v[108:111]
	v_mfma_f32_16x16x32_bf16 v[108:111], v[154:157], v[212:215], v[112:115]
	v_mfma_f32_16x16x32_bf16 v[236:239], v[158:161], v[216:219], v[108:111]
	v_mfma_f32_16x16x32_bf16 v[108:111], v[146:149], v[220:223], v[116:119]
	v_mfma_f32_16x16x32_bf16 v[114:117], v[150:153], v[224:227], v[108:111]
	v_mfma_f32_16x16x32_bf16 v[108:111], v[154:157], v[220:223], v[120:123]
	v_mfma_f32_16x16x32_bf16 v[118:121], v[158:161], v[224:227], v[108:111]
	v_mfma_f32_16x16x32_bf16 v[108:111], v[146:149], v[228:231], v[124:127]
	v_mfma_f32_16x16x32_bf16 v[20:23], v[150:153], v[208:211], v[20:23]
	v_mfma_f32_16x16x32_bf16 v[100:103], v[158:161], v[208:211], v[100:103]
	v_mfma_f32_16x16x32_bf16 v[104:107], v[150:153], v[216:219], v[104:107]
	v_mfma_f32_16x16x32_bf16 v[240:243], v[150:153], v[232:235], v[108:111]
	v_mfma_f32_16x16x32_bf16 v[108:111], v[154:157], v[228:231], v[134:137]
	v_mfma_f32_16x16x32_bf16 v[134:137], v[158:161], v[232:235], v[108:111]
	v_mfma_f32_16x16x32_bf16 v[68:71], v[194:197], v[204:207], v[68:71]
	v_mfma_f32_16x16x32_bf16 v[108:111], v[162:165], v[204:207], v[138:141]
	v_mfma_f32_16x16x32_bf16 v[204:207], v[198:201], v[208:211], v[68:71]
	v_mfma_f32_16x16x32_bf16 v[68:71], v[162:165], v[212:215], v[72:75]
	v_mfma_f32_16x16x32_bf16 v[138:141], v[166:169], v[208:211], v[108:111]
	v_mfma_f32_16x16x32_bf16 v[208:211], v[166:169], v[216:219], v[68:71]
	v_mfma_f32_16x16x32_bf16 v[68:71], v[194:197], v[212:215], v[76:79]
	v_mfma_f32_16x16x32_bf16 v[74:77], v[198:201], v[216:219], v[68:71]
	v_mfma_f32_16x16x32_bf16 v[68:71], v[162:165], v[220:223], v[80:83]
	v_mfma_f32_16x16x32_bf16 v[78:81], v[166:169], v[224:227], v[68:71]
	v_mfma_f32_16x16x32_bf16 v[68:71], v[194:197], v[220:223], v[84:87]
	v_mfma_f32_16x16x32_bf16 v[82:85], v[198:201], v[224:227], v[68:71]
	v_mfma_f32_16x16x32_bf16 v[68:71], v[162:165], v[228:231], v[88:91]
	v_mfma_f32_16x16x32_bf16 v[212:215], v[166:169], v[232:235], v[68:71]
	v_mfma_f32_16x16x32_bf16 v[68:71], v[194:197], v[228:231], v[92:95]
	v_mfma_f32_16x16x32_bf16 v[216:219], v[198:201], v[232:235], v[68:71]
	s_setprio 0
	s_barrier
; #define PG8_STAGE(bufoff, gbase, voff) do { _Pragma("unroll") for (int _i = 0; _i < 2; ++_i) \
;         __builtin_amdgcn_global_load_lds((const unsigned*)((const char*)(gbase) + (voff)[_i]), (LAS unsigned*)(lds + (bufoff) + ldsw + _i * 8192), 16, 0, 0); } while (0)
; #define PG8_LDA(dst, b, h) do { _Pragma("unroll") for (int m = 0; m < 4; ++m) _Pragma("unroll") for (int k = 0; k < 2; ++k) dst[m][k] = *(const LAS bf16x8*)(lds + PG8_SA(b, h) + aoff + m * 2048 + k * 1024); } while (0)
; #define PG8_LDB(dst, b, h) do { _Pragma("unroll") for (int n = 0; n < 2; ++n) _Pragma("unroll") for (int k = 0; k < 2; ++k) dst[n][k] = *(const LAS bf16x8*)(lds + PG8_SB(b, h) + boff + n * 2048 + k * 1024); } while (0)
; #define PG8_WAIT_V(n) asm volatile("s_waitcnt vmcnt(" #n ")" ::: "memory")
; #define PG8_BAR __builtin_amdgcn_s_barrier()
; template <class Epi, class Sched>
; __device__ __forceinline__ void gemm_phase(LAS unsigned char* lds, const Gemm g, const Sched& S, const Epi& E, const int tid) {
;     ...
;         for (int t = 0; t < nt; t += 2) {
;             const bool last = (t == nt - 2);
;             const char* a1 = cA + (size_t)(t + 1) * kstep;
;             const char* a2 = last ? nA : cA + (size_t)(t + 2) * kstep; const char* b2 = last ? nB : cB + (size_t)(t + 2) * kstep;
;             const char* a3 = a2 + kstep; const char* b3 = b2 + kstep;
;             PG8_LDB(B0, 0, 0); PG8_LDB(B1, 0, 1); PG8_SCHED; PG8_LDA(At, 0, 0); PG8_STAGE(PG8_SA(1, 1), a1 + hstepA, voffA);
;             PG8_WAIT_V(8); PG8_WAIT_L(0); PG8_BAR; PG8_MMA(0, 0, At, B0); PG8_MMA(0, 1, At, B1); PG8_BAR; PG8_SCHED;
;             PG8_LDA(At, 0, 1); PG8_STAGE(PG8_SB(0, 0), b2, voffB); PG8_STAGE(PG8_SB(0, 1), b2 + hstepB, voffB); PG8_STAGE(PG8_SA(0, 0), a2, voffA);
;             PG8_WAIT_V(8); PG8_WAIT_L(0); PG8_BAR; PG8_MMA(1, 0, At, B0); PG8_MMA(1, 1, At, B1); PG8_BAR; PG8_SCHED;
;             PG8_LDB(B0, 1, 0); PG8_LDB(B1, 1, 1); PG8_SCHED; PG8_LDA(At, 1, 0); PG8_STAGE(PG8_SA(0, 1), a2 + hstepA, voffA);
;             PG8_WAIT_V(8); PG8_WAIT_L(0); PG8_BAR; PG8_MMA(0, 0, At, B0); PG8_MMA(0, 1, At, B1); PG8_BAR; PG8_SCHED;
;             PG8_LDA(At, 1, 1); PG8_STAGE(PG8_SB(1, 0), b3, voffB); PG8_STAGE(PG8_SB(1, 1), b3 + hstepB, voffB); PG8_STAGE(PG8_SA(1, 0), a3, voffA);
;             PG8_WAIT_V(8); PG8_WAIT_L(0); PG8_BAR; PG8_MMA(1, 0, At, B0); PG8_MMA(1, 1, At, B1); PG8_BAR; PG8_SCHED;
	s_mov_b32 m0, s83
	s_nop 3
	ds_read_b128 v[68:71], v132 offset:16384
	ds_read_b128 v[86:89], v132 offset:17408
	ds_read_b128 v[90:93], v132 offset:18432
	ds_read_b128 v[108:111], v132 offset:19456
	ds_read_b128 v[122:125], v132 offset:20480
	ds_read_b128 v[126:129], v132 offset:21504
	ds_read_b128 v[220:223], v132 offset:22528
	ds_read_b128 v[224:227], v132 offset:23552
	global_load_lds_dwordx4 v[4:5], off
	s_mov_b32 m0, s82
	s_nop 0
	global_load_lds_dwordx4 v[8:9], off
	s_mov_b32 m0, s81
	s_nop 0
	global_load_lds_dwordx4 v[12:13], off
	s_mov_b32 m0, s80
	s_nop 0
	global_load_lds_dwordx4 v[14:15], off
	s_mov_b32 m0, s14
	s_nop 0
	global_load_lds_dwordx4 v[16:17], off
	s_mov_b32 m0, s59
	s_nop 0
	global_load_lds_dwordx4 v[18:19], off
	s_waitcnt vmcnt(8)
	s_waitcnt lgkmcnt(0)
	s_barrier
	s_setprio 1
	v_mfma_f32_16x16x32_bf16 v[8:11], v[146:149], v[68:71], v[170:173]
	v_mfma_f32_16x16x32_bf16 v[12:15], v[154:157], v[68:71], v[174:177]
	v_mfma_f32_16x16x32_bf16 v[16:19], v[146:149], v[90:93], v[178:181]
	v_mfma_f32_16x16x32_bf16 v[36:39], v[146:149], v[220:223], v[36:39]
	v_mfma_f32_16x16x32_bf16 v[8:11], v[150:153], v[86:89], v[8:11]
	v_mfma_f32_16x16x32_bf16 v[12:15], v[158:161], v[86:89], v[12:15]
	v_mfma_f32_16x16x32_bf16 v[16:19], v[150:153], v[108:111], v[16:19]
	v_mfma_f32_16x16x32_bf16 v[170:173], v[154:157], v[90:93], v[182:185]
	v_mfma_f32_16x16x32_bf16 v[174:177], v[146:149], v[122:125], v[186:189]
	v_mfma_f32_16x16x32_bf16 v[178:181], v[154:157], v[122:125], v[190:193]
	v_mfma_f32_16x16x32_bf16 v[36:39], v[150:153], v[224:227], v[36:39]
	v_mfma_f32_16x16x32_bf16 v[40:43], v[154:157], v[220:223], v[40:43]
	v_mfma_f32_16x16x32_bf16 v[170:173], v[158:161], v[108:111], v[170:173]
	v_mfma_f32_16x16x32_bf16 v[174:177], v[150:153], v[126:129], v[174:177]
	v_mfma_f32_16x16x32_bf16 v[178:181], v[158:161], v[126:129], v[178:181]
	v_mfma_f32_16x16x32_bf16 v[146:149], v[158:161], v[224:227], v[40:43]
	v_mfma_f32_16x16x32_bf16 v[40:43], v[162:165], v[68:71], v[44:47]
	v_mfma_f32_16x16x32_bf16 v[150:153], v[166:169], v[86:89], v[40:43]
	v_mfma_f32_16x16x32_bf16 v[40:43], v[194:197], v[68:71], v[48:51]
	v_mfma_f32_16x16x32_bf16 v[154:157], v[198:201], v[86:89], v[40:43]
	v_mfma_f32_16x16x32_bf16 v[40:43], v[162:165], v[90:93], v[60:63]
	v_mfma_f32_16x16x32_bf16 v[158:161], v[166:169], v[108:111], v[40:43]
	v_mfma_f32_16x16x32_bf16 v[40:43], v[194:197], v[90:93], v[64:67]
	v_mfma_f32_16x16x32_bf16 v[182:185], v[198:201], v[108:111], v[40:43]
	v_mfma_f32_16x16x32_bf16 v[40:43], v[162:165], v[122:125], v[96:99]
	v_mfma_f32_16x16x32_bf16 v[186:189], v[166:169], v[126:129], v[40:43]
	v_mfma_f32_16x16x32_bf16 v[40:43], v[194:197], v[122:125], v[142:145]
	v_mfma_f32_16x16x32_bf16 v[142:145], v[198:201], v[126:129], v[40:43]
	v_mfma_f32_16x16x32_bf16 v[40:43], v[162:165], v[220:223], v[52:55]
	v_mfma_f32_16x16x32_bf16 v[162:165], v[166:169], v[224:227], v[40:43]
	v_mfma_f32_16x16x32_bf16 v[40:43], v[194:197], v[220:223], v[56:59]
	v_mfma_f32_16x16x32_bf16 v[166:169], v[198:201], v[224:227], v[40:43]
	s_setprio 0
	s_barrier
	ds_read_b128 v[58:61], v245
	ds_read_b128 v[66:69], v245 offset:1024
	ds_read_b128 v[190:193], v245 offset:2048
	ds_read_b128 v[194:197], v245 offset:3072
	ds_read_b128 v[198:201], v244
	ds_read_b128 v[220:223], v244 offset:1024
	ds_read_b128 v[224:227], v244 offset:2048
	ds_read_b128 v[228:231], v244 offset:3072
	s_mov_b32 m0, s15
	ds_read_b128 v[40:43], v132 offset:32768
	ds_read_b128 v[44:47], v132 offset:33792
	ds_read_b128 v[48:51], v132 offset:34816
	ds_read_b128 v[52:55], v132 offset:35840
	ds_read_b128 v[232:235], v132 offset:36864
	ds_read_b128 v[244:247], v132 offset:37888
	ds_read_b128 v[62:65], v132 offset:38912
	ds_read_b128 v[70:73], v132 offset:39936
	global_load_lds_dwordx4 v[2:3], off
	s_mov_b32 m0, s45
	s_nop 0
	global_load_lds_dwordx4 v[6:7], off
	s_waitcnt vmcnt(8)
	s_waitcnt lgkmcnt(0)
	s_barrier
; #define PG8_STAGE(bufoff, gbase, voff) do { _Pragma("unroll") for (int _i = 0; _i < 2; ++_i) \
;         __builtin_amdgcn_global_load_lds((const unsigned*)((const char*)(gbase) + (voff)[_i]), (LAS unsigned*)(lds + (bufoff) + ldsw + _i * 8192), 16, 0, 0); } while (0)
; #define PG8_LDA(dst, b, h) do { _Pragma("unroll") for (int m = 0; m < 4; ++m) _Pragma("unroll") for (int k = 0; k < 2; ++k) dst[m][k] = *(const LAS bf16x8*)(lds + PG8_SA(b, h) + aoff + m * 2048 + k * 1024); } while (0)
; #define PG8_LDB(dst, b, h) do { _Pragma("unroll") for (int n = 0; n < 2; ++n) _Pragma("unroll") for (int k = 0; k < 2; ++k) dst[n][k] = *(const LAS bf16x8*)(lds + PG8_SB(b, h) + boff + n * 2048 + k * 1024); } while (0)
; #define PG8_WAIT_V(n) asm volatile("s_waitcnt vmcnt(" #n ")" ::: "memory")
; template <class Epi, class Sched>
; __device__ __forceinline__ void gemm_phase(LAS unsigned char* lds, const Gemm g, const Sched& S, const Epi& E, const int tid) {
;     ...
;         for (int t = 0; t < nt; t += 2) {
;             const bool last = (t == nt - 2);
;             const char* a1 = cA + (size_t)(t + 1) * kstep;
;             const char* a2 = last ? nA : cA + (size_t)(t + 2) * kstep; const char* b2 = last ? nB : cB + (size_t)(t + 2) * kstep;
;             const char* a3 = a2 + kstep; const char* b3 = b2 + kstep;
;             PG8_LDB(B0, 0, 0); PG8_LDB(B1, 0, 1); PG8_SCHED; PG8_LDA(At, 0, 0); PG8_STAGE(PG8_SA(1, 1), a1 + hstepA, voffA);
;             PG8_WAIT_V(8); PG8_WAIT_L(0); PG8_BAR; PG8_MMA(0, 0, At, B0); PG8_MMA(0, 1, At, B1); PG8_BAR; PG8_SCHED;
;             PG8_LDA(At, 0, 1); PG8_STAGE(PG8_SB(0, 0), b2, voffB); PG8_STAGE(PG8_SB(0, 1), b2 + hstepB, voffB); PG8_STAGE(PG8_SA(0, 0), a2, voffA);
;             PG8_WAIT_V(8); PG8_WAIT_L(0); PG8_BAR; PG8_MMA(1, 0, At, B0); PG8_MMA(1, 1, At, B1); PG8_BAR; PG8_SCHED;
;             PG8_LDB(B0, 1, 0); PG8_LDB(B1, 1, 1); PG8_SCHED; PG8_LDA(At, 1, 0); PG8_STAGE(PG8_SA(0, 1), a2 + hstepA, voffA);
;             PG8_WAIT_V(8); PG8_WAIT_L(0); PG8_BAR; PG8_MMA(0, 0, At, B0); PG8_MMA(0, 1, At, B1); PG8_BAR; PG8_SCHED;
;             PG8_LDA(At, 1, 1); PG8_STAGE(PG8_SB(1, 0), b3, voffB); PG8_STAGE(PG8_SB(1, 1), b3 + hstepB, voffB); PG8_STAGE(PG8_SA(1, 0), a3, voffA);
;             PG8_WAIT_V(8); PG8_WAIT_L(0); PG8_BAR; PG8_MMA(1, 0, At, B0); PG8_MMA(1, 1, At, B1); PG8_BAR; PG8_SCHED;
;         }
;         if (wr == 0) PG8_BAR;
	s_setprio 1
	v_mfma_f32_16x16x32_bf16 v[2:5], v[58:61], v[40:43], v[20:23]
	v_mfma_f32_16x16x32_bf16 v[126:129], v[66:69], v[44:47], v[2:5]
	v_mfma_f32_16x16x32_bf16 v[2:5], v[190:193], v[40:43], v[100:103]
	v_mfma_f32_16x16x32_bf16 v[122:125], v[194:197], v[44:47], v[2:5]
	v_mfma_f32_16x16x32_bf16 v[2:5], v[58:61], v[48:51], v[104:107]
	v_mfma_f32_16x16x32_bf16 v[110:113], v[66:69], v[52:55], v[2:5]
	v_mfma_f32_16x16x32_bf16 v[2:5], v[190:193], v[48:51], v[236:239]
	v_mfma_f32_16x16x32_bf16 v[106:109], v[194:197], v[52:55], v[2:5]
	v_mfma_f32_16x16x32_bf16 v[2:5], v[58:61], v[232:235], v[114:117]
	v_mfma_f32_16x16x32_bf16 v[94:97], v[66:69], v[244:247], v[2:5]
	v_mfma_f32_16x16x32_bf16 v[2:5], v[190:193], v[232:235], v[118:121]
	v_mfma_f32_16x16x32_bf16 v[90:93], v[194:197], v[244:247], v[2:5]
	v_mfma_f32_16x16x32_bf16 v[2:5], v[58:61], v[62:65], v[240:243]
	v_mfma_f32_16x16x32_bf16 v[240:243], v[66:69], v[70:73], v[2:5]
	v_mfma_f32_16x16x32_bf16 v[2:5], v[190:193], v[62:65], v[134:137]
	v_mfma_f32_16x16x32_bf16 v[236:239], v[194:197], v[70:73], v[2:5]
	v_mfma_f32_16x16x32_bf16 v[2:5], v[198:201], v[40:43], v[138:141]
	v_mfma_f32_16x16x32_bf16 v[118:121], v[220:223], v[44:47], v[2:5]
	v_mfma_f32_16x16x32_bf16 v[2:5], v[224:227], v[40:43], v[204:207]
	v_mfma_f32_16x16x32_bf16 v[114:117], v[228:231], v[44:47], v[2:5]
	v_mfma_f32_16x16x32_bf16 v[2:5], v[198:201], v[48:51], v[208:211]
	v_mfma_f32_16x16x32_bf16 v[102:105], v[220:223], v[52:55], v[2:5]
	v_mfma_f32_16x16x32_bf16 v[2:5], v[224:227], v[48:51], v[74:77]
	v_mfma_f32_16x16x32_bf16 v[98:101], v[228:231], v[52:55], v[2:5]
	v_mfma_f32_16x16x32_bf16 v[2:5], v[198:201], v[232:235], v[78:81]
	v_mfma_f32_16x16x32_bf16 v[86:89], v[220:223], v[244:247], v[2:5]
	v_mfma_f32_16x16x32_bf16 v[2:5], v[224:227], v[232:235], v[82:85]
	v_mfma_f32_16x16x32_bf16 v[82:85], v[228:231], v[244:247], v[2:5]
	v_mfma_f32_16x16x32_bf16 v[2:5], v[198:201], v[62:65], v[212:215]
	v_mfma_f32_16x16x32_bf16 v[54:57], v[220:223], v[70:73], v[2:5]
	v_mfma_f32_16x16x32_bf16 v[2:5], v[224:227], v[62:65], v[216:219]
	v_mfma_f32_16x16x32_bf16 v[50:53], v[228:231], v[70:73], v[2:5]
	s_setprio 0
	s_barrier
	s_mov_b32 m0, s38
	s_nop 3
	ds_read_b128 v[2:5], v132 offset:49152
	ds_read_b128 v[20:23], v132 offset:50176
	ds_read_b128 v[62:65], v132 offset:51200
	ds_read_b128 v[70:73], v132 offset:52224
	ds_read_b128 v[134:137], v132 offset:53248
	ds_read_b128 v[138:141], v132 offset:54272
	ds_read_b128 v[204:207], v132 offset:55296
	ds_read_b128 v[208:211], v132 offset:56320
	global_load_lds_dwordx4 v[26:27], off
	s_mov_b32 m0, s61
	s_nop 0
	global_load_lds_dwordx4 v[28:29], off
	s_mov_b32 m0, s75
	s_nop 0
	global_load_lds_dwordx4 v[32:33], off
	s_mov_b32 m0, s79
	s_nop 0
	global_load_lds_dwordx4 v[34:35], off
	s_mov_b32 m0, s39
	s_nop 0
	global_load_lds_dwordx4 v[24:25], off
	s_mov_b32 m0, s74
	s_nop 0
	global_load_lds_dwordx4 v[30:31], off
	s_waitcnt vmcnt(8)
	s_waitcnt lgkmcnt(0)
	s_barrier
	s_setprio 1
	v_mfma_f32_16x16x32_bf16 v[6:9], v[58:61], v[2:5], v[8:11]
	v_mfma_f32_16x16x32_bf16 v[78:81], v[66:69], v[20:23], v[6:9]
	v_mfma_f32_16x16x32_bf16 v[6:9], v[190:193], v[2:5], v[12:15]
	v_mfma_f32_16x16x32_bf16 v[74:77], v[194:197], v[20:23], v[6:9]
	v_mfma_f32_16x16x32_bf16 v[6:9], v[58:61], v[62:65], v[16:19]
	v_mfma_f32_16x16x32_bf16 v[46:49], v[66:69], v[70:73], v[6:9]
	v_mfma_f32_16x16x32_bf16 v[6:9], v[190:193], v[62:65], v[170:173]
	v_mfma_f32_16x16x32_bf16 v[42:45], v[194:197], v[70:73], v[6:9]
	v_mfma_f32_16x16x32_bf16 v[6:9], v[58:61], v[134:137], v[174:177]
	v_mfma_f32_16x16x32_bf16 v[30:33], v[66:69], v[138:141], v[6:9]
	v_mfma_f32_16x16x32_bf16 v[6:9], v[190:193], v[134:137], v[178:181]
	v_mfma_f32_16x16x32_bf16 v[26:29], v[194:197], v[138:141], v[6:9]
	v_mfma_f32_16x16x32_bf16 v[6:9], v[58:61], v[204:207], v[36:39]
	v_mfma_f32_16x16x32_bf16 v[14:17], v[66:69], v[208:211], v[6:9]
	v_mfma_f32_16x16x32_bf16 v[6:9], v[190:193], v[204:207], v[146:149]
	v_mfma_f32_16x16x32_bf16 v[10:13], v[194:197], v[208:211], v[6:9]
	v_mfma_f32_16x16x32_bf16 v[6:9], v[198:201], v[2:5], v[150:153]
	v_mfma_f32_16x16x32_bf16 v[2:5], v[224:227], v[2:5], v[154:157]
	v_mfma_f32_16x16x32_bf16 v[58:61], v[228:231], v[20:23], v[2:5]
	v_mfma_f32_16x16x32_bf16 v[2:5], v[198:201], v[62:65], v[158:161]
	v_mfma_f32_16x16x32_bf16 v[38:41], v[220:223], v[70:73], v[2:5]
	v_mfma_f32_16x16x32_bf16 v[2:5], v[224:227], v[62:65], v[182:185]
	v_mfma_f32_16x16x32_bf16 v[34:37], v[228:231], v[70:73], v[2:5]
	v_mfma_f32_16x16x32_bf16 v[2:5], v[198:201], v[134:137], v[186:189]
	v_mfma_f32_16x16x32_bf16 v[66:69], v[220:223], v[20:23], v[6:9]
	v_mfma_f32_16x16x32_bf16 v[22:25], v[220:223], v[138:141], v[2:5]
	v_mfma_f32_16x16x32_bf16 v[2:5], v[224:227], v[134:137], v[142:145]
	v_mfma_f32_16x16x32_bf16 v[18:21], v[228:231], v[138:141], v[2:5]
	v_mfma_f32_16x16x32_bf16 v[2:5], v[198:201], v[204:207], v[162:165]
	v_mfma_f32_16x16x32_bf16 v[6:9], v[220:223], v[208:211], v[2:5]
	v_mfma_f32_16x16x32_bf16 v[2:5], v[224:227], v[204:207], v[166:169]
	v_mfma_f32_16x16x32_bf16 v[2:5], v[228:231], v[208:211], v[2:5]
	s_setprio 0
	s_barrier
	s_cbranch_scc1 .LBB1_376
	s_barrier

; #define PG8_STAGE(bufoff, gbase, voff) do { _Pragma("unroll") for (int _i = 0; _i < 2; ++_i) \
;         __builtin_amdgcn_global_load_lds((const unsigned*)((const char*)(gbase) + (voff)[_i]), (LAS unsigned*)(lds + (bufoff) + ldsw + _i * 8192), 16, 0, 0); } while (0)
; #define PG8_LDA(dst, b, h) do { _Pragma("unroll") for (int m = 0; m < 4; ++m) _Pragma("unroll") for (int k = 0; k < 2; ++k) dst[m][k] = *(const LAS bf16x8*)(lds + PG8_SA(b, h) + aoff + m * 2048 + k * 1024); } while (0)
; #define PG8_LDB(dst, b, h) do { _Pragma("unroll") for (int n = 0; n < 2; ++n) _Pragma("unroll") for (int k = 0; k < 2; ++k) dst[n][k] = *(const LAS bf16x8*)(lds + PG8_SB(b, h) + boff + n * 2048 + k * 1024); } while (0)
; #define PG8_WAIT_V(n) asm volatile("s_waitcnt vmcnt(" #n ")" ::: "memory")
; #define PG8_BAR __builtin_amdgcn_s_barrier()
; template <class Epi, class Sched>
; __device__ __forceinline__ void gemm_phase(LAS unsigned char* lds, const Gemm g, const Sched& S, const Epi& E, const int tid) {
;     ...
;         for (int t = 0; t < nt; t += 2) {
;             const bool last = (t == nt - 2);
;             const char* a1 = cA + (size_t)(t + 1) * kstep;
;             const char* a2 = last ? nA : cA + (size_t)(t + 2) * kstep; const char* b2 = last ? nB : cB + (size_t)(t + 2) * kstep;
;             const char* a3 = a2 + kstep; const char* b3 = b2 + kstep;
;             PG8_LDB(B0, 0, 0); PG8_LDB(B1, 0, 1); PG8_SCHED; PG8_LDA(At, 0, 0); PG8_STAGE(PG8_SA(1, 1), a1 + hstepA, voffA);
;             PG8_WAIT_V(8); PG8_WAIT_L(0); PG8_BAR; PG8_MMA(0, 0, At, B0); PG8_MMA(0, 1, At, B1); PG8_BAR; PG8_SCHED;
;             PG8_LDA(At, 0, 1); PG8_STAGE(PG8_SB(0, 0), b2, voffB); PG8_STAGE(PG8_SB(0, 1), b2 + hstepB, voffB); PG8_STAGE(PG8_SA(0, 0), a2, voffA);
;             PG8_WAIT_V(8); PG8_WAIT_L(0); PG8_BAR; PG8_MMA(1, 0, At, B0); PG8_MMA(1, 1, At, B1); PG8_BAR; PG8_SCHED;
;             PG8_LDB(B0, 1, 0); PG8_LDB(B1, 1, 1); PG8_SCHED; PG8_LDA(At, 1, 0); PG8_STAGE(PG8_SA(0, 1), a2 + hstepA, voffA);
;             PG8_WAIT_V(8); PG8_WAIT_L(0); PG8_BAR; PG8_MMA(0, 0, At, B0); PG8_MMA(0, 1, At, B1); PG8_BAR; PG8_SCHED;
;             PG8_LDA(At, 1, 1); PG8_STAGE(PG8_SB(1, 0), b3, voffB); PG8_STAGE(PG8_SB(1, 1), b3 + hstepB, voffB); PG8_STAGE(PG8_SA(1, 0), a3, voffA);
;             PG8_WAIT_V(8); PG8_WAIT_L(0); PG8_BAR; PG8_MMA(1, 0, At, B0); PG8_MMA(1, 1, At, B1); PG8_BAR; PG8_SCHED;
.LBB1_432:
	s_add_u32 s14, s38, 0xfff80080
	s_addc_u32 s15, s39, -1
	s_add_i32 s4, 0, 0x10000
	s_cmp_eq_u32 s45, 28
	s_cselect_b32 s79, s69, s15
	s_cselect_b32 s78, s85, s14
	v_add_u32_e32 v144, s4, v147
	s_cselect_b32 s77, s37, s44
	s_cselect_b32 s76, vcc_lo, vcc_hi
	s_add_i32 s80, 0, 0x14000
	ds_read_b128 v[140:143], v144
	ds_read_b128 v[158:161], v144 offset:1024
	ds_read_b128 v[162:165], v144 offset:2048
	ds_read_b128 v[166:169], v144 offset:3072
	v_add_u32_e32 v144, s80, v147
	ds_read_b128 v[170:173], v144
	ds_read_b128 v[174:177], v144 offset:1024
	ds_read_b128 v[178:181], v144 offset:2048
	ds_read_b128 v[182:185], v144 offset:3072
	v_lshl_add_u64 v[144:145], s[38:39], 0, v[138:139]
	s_add_i32 m0, s56, 0xc000
	ds_read_b128 v[186:189], v156
	ds_read_b128 v[190:193], v156 offset:1024
	ds_read_b128 v[204:207], v156 offset:2048
	ds_read_b128 v[208:211], v156 offset:3072
	ds_read_b128 v[212:215], v156 offset:4096
	ds_read_b128 v[216:219], v156 offset:5120
	ds_read_b128 v[220:223], v156 offset:6144
	ds_read_b128 v[230:233], v156 offset:7168
	global_load_lds_dwordx4 v[144:145], off
	v_lshl_add_u64 v[144:145], s[38:39], 0, v[136:137]
	s_add_i32 m0, s56, 0xe000
	s_nop 0
	global_load_lds_dwordx4 v[144:145], off
	s_waitcnt vmcnt(8)
	s_waitcnt lgkmcnt(0)
	s_barrier
	s_setprio 1
	v_mfma_f32_16x16x32_bf16 v[126:129], v[140:143], v[186:189], v[126:129]
	v_mfma_f32_16x16x32_bf16 v[122:125], v[162:165], v[186:189], v[122:125]
	v_mfma_f32_16x16x32_bf16 v[110:113], v[140:143], v[204:207], v[110:113]
	v_mfma_f32_16x16x32_bf16 v[106:109], v[162:165], v[204:207], v[106:109]
	v_mfma_f32_16x16x32_bf16 v[94:97], v[140:143], v[212:215], v[94:97]
	v_mfma_f32_16x16x32_bf16 v[90:93], v[162:165], v[212:215], v[90:93]
	v_mfma_f32_16x16x32_bf16 v[78:81], v[140:143], v[220:223], v[78:81]
	v_mfma_f32_16x16x32_bf16 v[74:77], v[162:165], v[220:223], v[74:77]
	v_mfma_f32_16x16x32_bf16 v[126:129], v[158:161], v[190:193], v[126:129]
	v_mfma_f32_16x16x32_bf16 v[122:125], v[166:169], v[190:193], v[122:125]
	v_mfma_f32_16x16x32_bf16 v[110:113], v[158:161], v[208:211], v[110:113]
	v_mfma_f32_16x16x32_bf16 v[106:109], v[166:169], v[208:211], v[106:109]
	v_mfma_f32_16x16x32_bf16 v[94:97], v[158:161], v[216:219], v[94:97]
	v_mfma_f32_16x16x32_bf16 v[90:93], v[166:169], v[216:219], v[90:93]
	v_mfma_f32_16x16x32_bf16 v[78:81], v[158:161], v[230:233], v[78:81]
	v_mfma_f32_16x16x32_bf16 v[74:77], v[166:169], v[230:233], v[74:77]
	v_mfma_f32_16x16x32_bf16 v[118:121], v[170:173], v[186:189], v[118:121]
	v_mfma_f32_16x16x32_bf16 v[114:117], v[178:181], v[186:189], v[114:117]
	v_mfma_f32_16x16x32_bf16 v[102:105], v[170:173], v[204:207], v[102:105]
	v_mfma_f32_16x16x32_bf16 v[98:101], v[178:181], v[204:207], v[98:101]
	v_mfma_f32_16x16x32_bf16 v[86:89], v[170:173], v[212:215], v[86:89]
	v_mfma_f32_16x16x32_bf16 v[82:85], v[178:181], v[212:215], v[82:85]
	v_mfma_f32_16x16x32_bf16 v[70:73], v[170:173], v[220:223], v[70:73]
	v_mfma_f32_16x16x32_bf16 v[66:69], v[178:181], v[220:223], v[66:69]
	v_mfma_f32_16x16x32_bf16 v[118:121], v[174:177], v[190:193], v[118:121]
	v_mfma_f32_16x16x32_bf16 v[114:117], v[182:185], v[190:193], v[114:117]
	v_mfma_f32_16x16x32_bf16 v[102:105], v[174:177], v[208:211], v[102:105]
	v_mfma_f32_16x16x32_bf16 v[98:101], v[182:185], v[208:211], v[98:101]
	v_mfma_f32_16x16x32_bf16 v[86:89], v[174:177], v[216:219], v[86:89]
	v_mfma_f32_16x16x32_bf16 v[82:85], v[182:185], v[216:219], v[82:85]
	v_mfma_f32_16x16x32_bf16 v[70:73], v[174:177], v[230:233], v[70:73]
	v_mfma_f32_16x16x32_bf16 v[66:69], v[182:185], v[230:233], v[66:69]
	s_setprio 0
	s_barrier
	s_add_i32 s4, s4, s83
	v_lshl_add_u64 v[144:145], s[76:77], 0, v[0:1]
	s_mov_b32 m0, s4
	ds_read_b128 v[186:189], v156 offset:16384
	ds_read_b128 v[190:193], v156 offset:17408
	ds_read_b128 v[204:207], v156 offset:18432
	ds_read_b128 v[208:211], v156 offset:19456
	ds_read_b128 v[212:215], v156 offset:20480
	ds_read_b128 v[216:219], v156 offset:21504
	ds_read_b128 v[220:223], v156 offset:22528
	ds_read_b128 v[230:233], v156 offset:23552
	global_load_lds_dwordx4 v[144:145], off
	s_add_i32 m0, s4, 0x2000
	s_add_u32 s14, s76, 0x80000
	v_lshl_add_u64 v[194:195], s[76:77], 0, v[134:135]
	s_addc_u32 s15, s77, 0
	s_add_i32 s4, s80, s83
	global_load_lds_dwordx4 v[194:195], off
	v_lshl_add_u64 v[196:197], s[14:15], 0, v[0:1]
	s_mov_b32 m0, s4
	v_lshl_add_u64 v[198:199], s[78:79], 0, v[132:133]
	global_load_lds_dwordx4 v[196:197], off
	v_lshl_add_u64 v[196:197], s[14:15], 0, v[134:135]
	s_add_i32 m0, s4, 0x2000
	s_nop 0
	global_load_lds_dwordx4 v[196:197], off
	v_lshl_add_u64 v[196:197], s[78:79], 0, v[130:131]
	s_mov_b32 m0, s56
	s_nop 0
	global_load_lds_dwordx4 v[196:197], off
	s_mov_b32 m0, s57
	s_nop 0
	global_load_lds_dwordx4 v[198:199], off
	s_waitcnt vmcnt(8)
	s_waitcnt lgkmcnt(0)
	s_barrier
; #define PG8_STAGE(bufoff, gbase, voff) do { _Pragma("unroll") for (int _i = 0; _i < 2; ++_i) \
;         __builtin_amdgcn_global_load_lds((const unsigned*)((const char*)(gbase) + (voff)[_i]), (LAS unsigned*)(lds + (bufoff) + ldsw + _i * 8192), 16, 0, 0); } while (0)
; #define PG8_LDA(dst, b, h) do { _Pragma("unroll") for (int m = 0; m < 4; ++m) _Pragma("unroll") for (int k = 0; k < 2; ++k) dst[m][k] = *(const LAS bf16x8*)(lds + PG8_SA(b, h) + aoff + m * 2048 + k * 1024); } while (0)
; #define PG8_LDB(dst, b, h) do { _Pragma("unroll") for (int n = 0; n < 2; ++n) _Pragma("unroll") for (int k = 0; k < 2; ++k) dst[n][k] = *(const LAS bf16x8*)(lds + PG8_SB(b, h) + boff + n * 2048 + k * 1024); } while (0)
; #define PG8_WAIT_V(n) asm volatile("s_waitcnt vmcnt(" #n ")" ::: "memory")
; #define PG8_BAR __builtin_amdgcn_s_barrier()
; template <class Epi, class Sched>
; __device__ __forceinline__ void gemm_phase(LAS unsigned char* lds, const Gemm g, const Sched& S, const Epi& E, const int tid) {
;     ...
;         for (int t = 0; t < nt; t += 2) {
;             const bool last = (t == nt - 2);
;             const char* a1 = cA + (size_t)(t + 1) * kstep;
;             const char* a2 = last ? nA : cA + (size_t)(t + 2) * kstep; const char* b2 = last ? nB : cB + (size_t)(t + 2) * kstep;
;             const char* a3 = a2 + kstep; const char* b3 = b2 + kstep;
;             PG8_LDB(B0, 0, 0); PG8_LDB(B1, 0, 1); PG8_SCHED; PG8_LDA(At, 0, 0); PG8_STAGE(PG8_SA(1, 1), a1 + hstepA, voffA);
;             PG8_WAIT_V(8); PG8_WAIT_L(0); PG8_BAR; PG8_MMA(0, 0, At, B0); PG8_MMA(0, 1, At, B1); PG8_BAR; PG8_SCHED;
;             PG8_LDA(At, 0, 1); PG8_STAGE(PG8_SB(0, 0), b2, voffB); PG8_STAGE(PG8_SB(0, 1), b2 + hstepB, voffB); PG8_STAGE(PG8_SA(0, 0), a2, voffA);
;             PG8_WAIT_V(8); PG8_WAIT_L(0); PG8_BAR; PG8_MMA(1, 0, At, B0); PG8_MMA(1, 1, At, B1); PG8_BAR; PG8_SCHED;
;             PG8_LDB(B0, 1, 0); PG8_LDB(B1, 1, 1); PG8_SCHED; PG8_LDA(At, 1, 0); PG8_STAGE(PG8_SA(0, 1), a2 + hstepA, voffA);
;             PG8_WAIT_V(8); PG8_WAIT_L(0); PG8_BAR; PG8_MMA(0, 0, At, B0); PG8_MMA(0, 1, At, B1); PG8_BAR; PG8_SCHED;
;             PG8_LDA(At, 1, 1); PG8_STAGE(PG8_SB(1, 0), b3, voffB); PG8_STAGE(PG8_SB(1, 1), b3 + hstepB, voffB); PG8_STAGE(PG8_SA(1, 0), a3, voffA);
;             PG8_WAIT_V(8); PG8_WAIT_L(0); PG8_BAR; PG8_MMA(1, 0, At, B0); PG8_MMA(1, 1, At, B1); PG8_BAR; PG8_SCHED;
	s_setprio 1
	v_mfma_f32_16x16x32_bf16 v[62:65], v[140:143], v[186:189], v[62:65]
	v_mfma_f32_16x16x32_bf16 v[58:61], v[162:165], v[186:189], v[58:61]
	v_mfma_f32_16x16x32_bf16 v[46:49], v[140:143], v[204:207], v[46:49]
	v_mfma_f32_16x16x32_bf16 v[42:45], v[162:165], v[204:207], v[42:45]
	v_mfma_f32_16x16x32_bf16 v[30:33], v[140:143], v[212:215], v[30:33]
	v_mfma_f32_16x16x32_bf16 v[26:29], v[162:165], v[212:215], v[26:29]
	v_mfma_f32_16x16x32_bf16 v[14:17], v[140:143], v[220:223], v[14:17]
	v_mfma_f32_16x16x32_bf16 v[10:13], v[162:165], v[220:223], v[10:13]
	v_mfma_f32_16x16x32_bf16 v[62:65], v[158:161], v[190:193], v[62:65]
	v_mfma_f32_16x16x32_bf16 v[58:61], v[166:169], v[190:193], v[58:61]
	v_mfma_f32_16x16x32_bf16 v[46:49], v[158:161], v[208:211], v[46:49]
	v_mfma_f32_16x16x32_bf16 v[42:45], v[166:169], v[208:211], v[42:45]
	v_mfma_f32_16x16x32_bf16 v[30:33], v[158:161], v[216:219], v[30:33]
	v_mfma_f32_16x16x32_bf16 v[26:29], v[166:169], v[216:219], v[26:29]
	v_mfma_f32_16x16x32_bf16 v[14:17], v[158:161], v[230:233], v[14:17]
	v_mfma_f32_16x16x32_bf16 v[10:13], v[166:169], v[230:233], v[10:13]
	v_mfma_f32_16x16x32_bf16 v[54:57], v[170:173], v[186:189], v[54:57]
	v_mfma_f32_16x16x32_bf16 v[50:53], v[178:181], v[186:189], v[50:53]
	v_mfma_f32_16x16x32_bf16 v[38:41], v[170:173], v[204:207], v[38:41]
	v_mfma_f32_16x16x32_bf16 v[34:37], v[178:181], v[204:207], v[34:37]
	v_mfma_f32_16x16x32_bf16 v[22:25], v[170:173], v[212:215], v[22:25]
	v_mfma_f32_16x16x32_bf16 v[18:21], v[178:181], v[212:215], v[18:21]
	v_mfma_f32_16x16x32_bf16 v[6:9], v[170:173], v[220:223], v[6:9]
	v_mfma_f32_16x16x32_bf16 v[2:5], v[178:181], v[220:223], v[2:5]
	v_mfma_f32_16x16x32_bf16 v[54:57], v[174:177], v[190:193], v[54:57]
	v_mfma_f32_16x16x32_bf16 v[50:53], v[182:185], v[190:193], v[50:53]
	v_mfma_f32_16x16x32_bf16 v[38:41], v[174:177], v[208:211], v[38:41]
	v_mfma_f32_16x16x32_bf16 v[34:37], v[182:185], v[208:211], v[34:37]
	v_mfma_f32_16x16x32_bf16 v[22:25], v[174:177], v[216:219], v[22:25]
	v_mfma_f32_16x16x32_bf16 v[18:21], v[182:185], v[216:219], v[18:21]
	v_mfma_f32_16x16x32_bf16 v[6:9], v[174:177], v[230:233], v[6:9]
	v_mfma_f32_16x16x32_bf16 v[2:5], v[182:185], v[230:233], v[2:5]
	s_setprio 0
	s_barrier
	s_add_i32 s4, 0, 0x18000
	v_add_u32_e32 v157, s4, v147
	s_add_i32 s80, 0, 0x1c000
	ds_read_b128 v[140:143], v157
	ds_read_b128 v[158:161], v157 offset:1024
	ds_read_b128 v[162:165], v157 offset:2048
	ds_read_b128 v[166:169], v157 offset:3072
	v_add_u32_e32 v157, s80, v147
	ds_read_b128 v[170:173], v157
	ds_read_b128 v[174:177], v157 offset:1024
	ds_read_b128 v[178:181], v157 offset:2048
	ds_read_b128 v[182:185], v157 offset:3072
	s_add_u32 s14, s78, 0x80000
	s_addc_u32 s15, s79, 0
	s_mov_b32 m0, s46
	v_lshl_add_u64 v[200:201], s[14:15], 0, v[130:131]
	ds_read_b128 v[186:189], v156 offset:32768
	ds_read_b128 v[190:193], v156 offset:33792
	ds_read_b128 v[204:207], v156 offset:34816
	ds_read_b128 v[208:211], v156 offset:35840
	ds_read_b128 v[212:215], v156 offset:36864
	ds_read_b128 v[216:219], v156 offset:37888
	ds_read_b128 v[220:223], v156 offset:38912
	ds_read_b128 v[230:233], v156 offset:39936
	global_load_lds_dwordx4 v[200:201], off
	v_lshl_add_u64 v[200:201], s[14:15], 0, v[132:133]
	s_mov_b32 m0, s47
	s_nop 0
	global_load_lds_dwordx4 v[200:201], off
	s_waitcnt vmcnt(8)
	s_waitcnt lgkmcnt(0)
	s_barrier
	s_setprio 1
	v_mfma_f32_16x16x32_bf16 v[126:129], v[140:143], v[186:189], v[126:129]
	v_mfma_f32_16x16x32_bf16 v[122:125], v[162:165], v[186:189], v[122:125]
	v_mfma_f32_16x16x32_bf16 v[110:113], v[140:143], v[204:207], v[110:113]
	v_mfma_f32_16x16x32_bf16 v[106:109], v[162:165], v[204:207], v[106:109]
	v_mfma_f32_16x16x32_bf16 v[94:97], v[140:143], v[212:215], v[94:97]
	v_mfma_f32_16x16x32_bf16 v[90:93], v[162:165], v[212:215], v[90:93]
	v_mfma_f32_16x16x32_bf16 v[78:81], v[140:143], v[220:223], v[78:81]
	v_mfma_f32_16x16x32_bf16 v[74:77], v[162:165], v[220:223], v[74:77]
	v_mfma_f32_16x16x32_bf16 v[126:129], v[158:161], v[190:193], v[126:129]
	v_mfma_f32_16x16x32_bf16 v[122:125], v[166:169], v[190:193], v[122:125]
	v_mfma_f32_16x16x32_bf16 v[110:113], v[158:161], v[208:211], v[110:113]
	v_mfma_f32_16x16x32_bf16 v[106:109], v[166:169], v[208:211], v[106:109]
	v_mfma_f32_16x16x32_bf16 v[94:97], v[158:161], v[216:219], v[94:97]
	v_mfma_f32_16x16x32_bf16 v[90:93], v[166:169], v[216:219], v[90:93]
	v_mfma_f32_16x16x32_bf16 v[78:81], v[158:161], v[230:233], v[78:81]
	v_mfma_f32_16x16x32_bf16 v[74:77], v[166:169], v[230:233], v[74:77]
	v_mfma_f32_16x16x32_bf16 v[118:121], v[170:173], v[186:189], v[118:121]
	v_mfma_f32_16x16x32_bf16 v[114:117], v[178:181], v[186:189], v[114:117]
	v_mfma_f32_16x16x32_bf16 v[102:105], v[170:173], v[204:207], v[102:105]
	v_mfma_f32_16x16x32_bf16 v[98:101], v[178:181], v[204:207], v[98:101]
	v_mfma_f32_16x16x32_bf16 v[86:89], v[170:173], v[212:215], v[86:89]
	v_mfma_f32_16x16x32_bf16 v[82:85], v[178:181], v[212:215], v[82:85]
	v_mfma_f32_16x16x32_bf16 v[70:73], v[170:173], v[220:223], v[70:73]
	v_mfma_f32_16x16x32_bf16 v[66:69], v[178:181], v[220:223], v[66:69]
	v_mfma_f32_16x16x32_bf16 v[118:121], v[174:177], v[190:193], v[118:121]
	v_mfma_f32_16x16x32_bf16 v[114:117], v[182:185], v[190:193], v[114:117]
	v_mfma_f32_16x16x32_bf16 v[102:105], v[174:177], v[208:211], v[102:105]
	v_mfma_f32_16x16x32_bf16 v[98:101], v[182:185], v[208:211], v[98:101]
	v_mfma_f32_16x16x32_bf16 v[86:89], v[174:177], v[216:219], v[86:89]
	v_mfma_f32_16x16x32_bf16 v[82:85], v[182:185], v[216:219], v[82:85]
	v_mfma_f32_16x16x32_bf16 v[70:73], v[174:177], v[230:233], v[70:73]
	v_mfma_f32_16x16x32_bf16 v[66:69], v[182:185], v[230:233], v[66:69]
	s_setprio 0
	s_barrier
; #define PG8_STAGE(bufoff, gbase, voff) do { _Pragma("unroll") for (int _i = 0; _i < 2; ++_i) \
;         __builtin_amdgcn_global_load_lds((const unsigned*)((const char*)(gbase) + (voff)[_i]), (LAS unsigned*)(lds + (bufoff) + ldsw + _i * 8192), 16, 0, 0); } while (0)
; #define PG8_LDA(dst, b, h) do { _Pragma("unroll") for (int m = 0; m < 4; ++m) _Pragma("unroll") for (int k = 0; k < 2; ++k) dst[m][k] = *(const LAS bf16x8*)(lds + PG8_SA(b, h) + aoff + m * 2048 + k * 1024); } while (0)
; #define PG8_LDB(dst, b, h) do { _Pragma("unroll") for (int n = 0; n < 2; ++n) _Pragma("unroll") for (int k = 0; k < 2; ++k) dst[n][k] = *(const LAS bf16x8*)(lds + PG8_SB(b, h) + boff + n * 2048 + k * 1024); } while (0)
; #define PG8_WAIT_V(n) asm volatile("s_waitcnt vmcnt(" #n ")" ::: "memory")
; template <class Epi, class Sched>
; __device__ __forceinline__ void gemm_phase(LAS unsigned char* lds, const Gemm g, const Sched& S, const Epi& E, const int tid) {
;     ...
;         for (int t = 0; t < nt; t += 2) {
;             const bool last = (t == nt - 2);
;             const char* a1 = cA + (size_t)(t + 1) * kstep;
;             const char* a2 = last ? nA : cA + (size_t)(t + 2) * kstep; const char* b2 = last ? nB : cB + (size_t)(t + 2) * kstep;
;             const char* a3 = a2 + kstep; const char* b3 = b2 + kstep;
;             PG8_LDB(B0, 0, 0); PG8_LDB(B1, 0, 1); PG8_SCHED; PG8_LDA(At, 0, 0); PG8_STAGE(PG8_SA(1, 1), a1 + hstepA, voffA);
;             PG8_WAIT_V(8); PG8_WAIT_L(0); PG8_BAR; PG8_MMA(0, 0, At, B0); PG8_MMA(0, 1, At, B1); PG8_BAR; PG8_SCHED;
;             PG8_LDA(At, 0, 1); PG8_STAGE(PG8_SB(0, 0), b2, voffB); PG8_STAGE(PG8_SB(0, 1), b2 + hstepB, voffB); PG8_STAGE(PG8_SA(0, 0), a2, voffA);
;             PG8_WAIT_V(8); PG8_WAIT_L(0); PG8_BAR; PG8_MMA(1, 0, At, B0); PG8_MMA(1, 1, At, B1); PG8_BAR; PG8_SCHED;
;             PG8_LDB(B0, 1, 0); PG8_LDB(B1, 1, 1); PG8_SCHED; PG8_LDA(At, 1, 0); PG8_STAGE(PG8_SA(0, 1), a2 + hstepA, voffA);
;             PG8_WAIT_V(8); PG8_WAIT_L(0); PG8_BAR; PG8_MMA(0, 0, At, B0); PG8_MMA(0, 1, At, B1); PG8_BAR; PG8_SCHED;
;             PG8_LDA(At, 1, 1); PG8_STAGE(PG8_SB(1, 0), b3, voffB); PG8_STAGE(PG8_SB(1, 1), b3 + hstepB, voffB); PG8_STAGE(PG8_SA(1, 0), a3, voffA);
;             PG8_WAIT_V(8); PG8_WAIT_L(0); PG8_BAR; PG8_MMA(1, 0, At, B0); PG8_MMA(1, 1, At, B1); PG8_BAR; PG8_SCHED;
;         }
;         if (wr == 0) PG8_BAR;
	s_add_i32 s4, s4, s83
	v_lshl_add_u64 v[144:145], v[144:145], 0, s[90:91]
	s_mov_b32 m0, s4
	ds_read_b128 v[186:189], v156 offset:49152
	ds_read_b128 v[190:193], v156 offset:50176
	ds_read_b128 v[204:207], v156 offset:51200
	ds_read_b128 v[208:211], v156 offset:52224
	ds_read_b128 v[212:215], v156 offset:53248
	ds_read_b128 v[216:219], v156 offset:54272
	ds_read_b128 v[220:223], v156 offset:55296
	ds_read_b128 v[230:233], v156 offset:56320
	global_load_lds_dwordx4 v[144:145], off
	s_add_i32 m0, s4, 0x2000
	s_add_u32 s14, s76, 0x80080
	v_lshl_add_u64 v[144:145], v[194:195], 0, s[90:91]
	s_addc_u32 s15, s77, 0
	s_add_i32 s4, s80, s83
	global_load_lds_dwordx4 v[144:145], off
	v_lshl_add_u64 v[144:145], s[14:15], 0, v[0:1]
	s_mov_b32 m0, s4
	s_nop 0
	global_load_lds_dwordx4 v[144:145], off
	v_lshl_add_u64 v[144:145], s[14:15], 0, v[134:135]
	s_add_i32 m0, s4, 0x2000
	s_nop 0
	global_load_lds_dwordx4 v[144:145], off
	v_lshl_add_u64 v[144:145], v[196:197], 0, s[90:91]
	s_mov_b32 m0, s5
	s_nop 0
	global_load_lds_dwordx4 v[144:145], off
	v_lshl_add_u64 v[144:145], v[198:199], 0, s[90:91]
	s_mov_b32 m0, s84
	s_nop 0
	global_load_lds_dwordx4 v[144:145], off
	s_waitcnt vmcnt(8)
	s_waitcnt lgkmcnt(0)
	s_barrier
	s_setprio 1
	v_mfma_f32_16x16x32_bf16 v[62:65], v[140:143], v[186:189], v[62:65]
	v_mfma_f32_16x16x32_bf16 v[58:61], v[162:165], v[186:189], v[58:61]
	v_mfma_f32_16x16x32_bf16 v[46:49], v[140:143], v[204:207], v[46:49]
	v_mfma_f32_16x16x32_bf16 v[42:45], v[162:165], v[204:207], v[42:45]
	v_mfma_f32_16x16x32_bf16 v[30:33], v[140:143], v[212:215], v[30:33]
	v_mfma_f32_16x16x32_bf16 v[26:29], v[162:165], v[212:215], v[26:29]
	v_mfma_f32_16x16x32_bf16 v[14:17], v[140:143], v[220:223], v[14:17]
	v_mfma_f32_16x16x32_bf16 v[10:13], v[162:165], v[220:223], v[10:13]
	v_mfma_f32_16x16x32_bf16 v[62:65], v[158:161], v[190:193], v[62:65]
	v_mfma_f32_16x16x32_bf16 v[58:61], v[166:169], v[190:193], v[58:61]
	v_mfma_f32_16x16x32_bf16 v[46:49], v[158:161], v[208:211], v[46:49]
	v_mfma_f32_16x16x32_bf16 v[42:45], v[166:169], v[208:211], v[42:45]
	v_mfma_f32_16x16x32_bf16 v[30:33], v[158:161], v[216:219], v[30:33]
	v_mfma_f32_16x16x32_bf16 v[26:29], v[166:169], v[216:219], v[26:29]
	v_mfma_f32_16x16x32_bf16 v[14:17], v[158:161], v[230:233], v[14:17]
	v_mfma_f32_16x16x32_bf16 v[10:13], v[166:169], v[230:233], v[10:13]
	v_mfma_f32_16x16x32_bf16 v[54:57], v[170:173], v[186:189], v[54:57]
	v_mfma_f32_16x16x32_bf16 v[50:53], v[178:181], v[186:189], v[50:53]
	v_mfma_f32_16x16x32_bf16 v[38:41], v[170:173], v[204:207], v[38:41]
	v_mfma_f32_16x16x32_bf16 v[34:37], v[178:181], v[204:207], v[34:37]
	v_mfma_f32_16x16x32_bf16 v[22:25], v[170:173], v[212:215], v[22:25]
	v_mfma_f32_16x16x32_bf16 v[18:21], v[178:181], v[212:215], v[18:21]
	v_mfma_f32_16x16x32_bf16 v[6:9], v[170:173], v[220:223], v[6:9]
	v_mfma_f32_16x16x32_bf16 v[2:5], v[178:181], v[220:223], v[2:5]
	v_mfma_f32_16x16x32_bf16 v[54:57], v[174:177], v[190:193], v[54:57]
	v_mfma_f32_16x16x32_bf16 v[50:53], v[182:185], v[190:193], v[50:53]
	v_mfma_f32_16x16x32_bf16 v[38:41], v[174:177], v[208:211], v[38:41]
	v_mfma_f32_16x16x32_bf16 v[34:37], v[182:185], v[208:211], v[34:37]
	v_mfma_f32_16x16x32_bf16 v[22:25], v[174:177], v[216:219], v[22:25]
	v_mfma_f32_16x16x32_bf16 v[18:21], v[182:185], v[216:219], v[18:21]
	v_mfma_f32_16x16x32_bf16 v[6:9], v[174:177], v[230:233], v[6:9]
	v_mfma_f32_16x16x32_bf16 v[2:5], v[182:185], v[230:233], v[2:5]
	s_setprio 0
	s_barrier
	s_add_i32 s45, s45, 2
	s_add_u32 vcc_hi, vcc_hi, 0x100
	s_addc_u32 s44, s44, 0
	s_add_u32 s38, s38, 0x100
	s_addc_u32 s39, s39, 0
	s_cmp_gt_u32 s45, 29
	s_cbranch_scc0 .LBB1_432
	s_and_b64 vcc, exec, s[26:27]
	s_cbranch_vccz .LBB1_435
	s_barrier

; #define PG8_STAGE(bufoff, gbase, voff) do { _Pragma("unroll") for (int _i = 0; _i < 2; ++_i) \
;         __builtin_amdgcn_global_load_lds((const unsigned*)((const char*)(gbase) + (voff)[_i]), (LAS unsigned*)(lds + (bufoff) + ldsw + _i * 8192), 16, 0, 0); } while (0)
; #define PG8_LDA(dst, b, h) do { _Pragma("unroll") for (int m = 0; m < 4; ++m) _Pragma("unroll") for (int k = 0; k < 2; ++k) dst[m][k] = *(const LAS bf16x8*)(lds + PG8_SA(b, h) + aoff + m * 2048 + k * 1024); } while (0)
; #define PG8_LDB(dst, b, h) do { _Pragma("unroll") for (int n = 0; n < 2; ++n) _Pragma("unroll") for (int k = 0; k < 2; ++k) dst[n][k] = *(const LAS bf16x8*)(lds + PG8_SB(b, h) + boff + n * 2048 + k * 1024); } while (0)
; #define PG8_WAIT_V(n) asm volatile("s_waitcnt vmcnt(" #n ")" ::: "memory")
; #define PG8_BAR __builtin_amdgcn_s_barrier()
; template <class Epi, class Sched>
; __device__ __forceinline__ void gemm_phase(LAS unsigned char* lds, const Gemm g, const Sched& S, const Epi& E, const int tid) {
;     ...
;         for (int t = 0; t < nt; t += 2) {
;             const bool last = (t == nt - 2);
;             const char* a1 = cA + (size_t)(t + 1) * kstep;
;             const char* a2 = last ? nA : cA + (size_t)(t + 2) * kstep; const char* b2 = last ? nB : cB + (size_t)(t + 2) * kstep;
;             const char* a3 = a2 + kstep; const char* b3 = b2 + kstep;
;             PG8_LDB(B0, 0, 0); PG8_LDB(B1, 0, 1); PG8_SCHED; PG8_LDA(At, 0, 0); PG8_STAGE(PG8_SA(1, 1), a1 + hstepA, voffA);
;             PG8_WAIT_V(8); PG8_WAIT_L(0); PG8_BAR; PG8_MMA(0, 0, At, B0); PG8_MMA(0, 1, At, B1); PG8_BAR; PG8_SCHED;
;             PG8_LDA(At, 0, 1); PG8_STAGE(PG8_SB(0, 0), b2, voffB); PG8_STAGE(PG8_SB(0, 1), b2 + hstepB, voffB); PG8_STAGE(PG8_SA(0, 0), a2, voffA);
;             PG8_WAIT_V(8); PG8_WAIT_L(0); PG8_BAR; PG8_MMA(1, 0, At, B0); PG8_MMA(1, 1, At, B1); PG8_BAR; PG8_SCHED;
;             PG8_LDB(B0, 1, 0); PG8_LDB(B1, 1, 1); PG8_SCHED; PG8_LDA(At, 1, 0); PG8_STAGE(PG8_SA(0, 1), a2 + hstepA, voffA);
;             PG8_WAIT_V(8); PG8_WAIT_L(0); PG8_BAR; PG8_MMA(0, 0, At, B0); PG8_MMA(0, 1, At, B1); PG8_BAR; PG8_SCHED;
;             PG8_LDA(At, 1, 1); PG8_STAGE(PG8_SB(1, 0), b3, voffB); PG8_STAGE(PG8_SB(1, 1), b3 + hstepB, voffB); PG8_STAGE(PG8_SA(1, 0), a3, voffA);
;             PG8_WAIT_V(8); PG8_WAIT_L(0); PG8_BAR; PG8_MMA(1, 0, At, B0); PG8_MMA(1, 1, At, B1); PG8_BAR; PG8_SCHED;
.LBB1_448:
	s_add_u32 s14, s78, 0xfff80080
	s_addc_u32 s15, s79, -1
	s_add_i32 s45, 0, 0x10000
	s_cmp_eq_u32 s44, 28
	s_cselect_b32 s83, s5, s15
	s_cselect_b32 s82, s59, s14
	v_add_u32_e32 v159, s45, v153
	s_cselect_b32 s81, s67, vcc_lo
	s_cselect_b32 s80, s69, s77
	s_add_i32 vcc_hi, 0, 0x14000
	ds_read_b128 v[140:143], v159
	ds_read_b128 v[144:147], v159 offset:1024
	ds_read_b128 v[148:151], v159 offset:2048
	ds_read_b128 v[160:163], v159 offset:3072
	v_add_u32_e32 v159, vcc_hi, v153
	ds_read_b128 v[164:167], v159
	ds_read_b128 v[168:171], v159 offset:1024
	ds_read_b128 v[172:175], v159 offset:2048
	ds_read_b128 v[176:179], v159 offset:3072
	v_lshl_add_u64 v[192:193], s[78:79], 0, v[138:139]
	s_add_i32 m0, s47, 0xc000
	ds_read_b128 v[180:183], v158
	ds_read_b128 v[184:187], v158 offset:1024
	ds_read_b128 v[188:191], v158 offset:2048
	ds_read_b128 v[204:207], v158 offset:3072
	ds_read_b128 v[208:211], v158 offset:4096
	ds_read_b128 v[212:215], v158 offset:5120
	ds_read_b128 v[216:219], v158 offset:6144
	ds_read_b128 v[220:223], v158 offset:7168
	global_load_lds_dwordx4 v[192:193], off
	v_lshl_add_u64 v[192:193], s[78:79], 0, v[136:137]
	s_add_i32 m0, s47, 0xe000
	s_nop 0
	global_load_lds_dwordx4 v[192:193], off
	s_waitcnt vmcnt(8)
	s_waitcnt lgkmcnt(0)
	s_barrier
	s_setprio 1
	v_mfma_f32_16x16x32_bf16 v[126:129], v[140:143], v[180:183], v[126:129]
	v_mfma_f32_16x16x32_bf16 v[122:125], v[148:151], v[180:183], v[122:125]
	v_mfma_f32_16x16x32_bf16 v[110:113], v[140:143], v[188:191], v[110:113]
	v_mfma_f32_16x16x32_bf16 v[106:109], v[148:151], v[188:191], v[106:109]
	v_mfma_f32_16x16x32_bf16 v[94:97], v[140:143], v[208:211], v[94:97]
	v_mfma_f32_16x16x32_bf16 v[90:93], v[148:151], v[208:211], v[90:93]
	v_mfma_f32_16x16x32_bf16 v[78:81], v[140:143], v[216:219], v[78:81]
	v_mfma_f32_16x16x32_bf16 v[74:77], v[148:151], v[216:219], v[74:77]
	v_mfma_f32_16x16x32_bf16 v[126:129], v[144:147], v[184:187], v[126:129]
	v_mfma_f32_16x16x32_bf16 v[122:125], v[160:163], v[184:187], v[122:125]
	v_mfma_f32_16x16x32_bf16 v[110:113], v[144:147], v[204:207], v[110:113]
	v_mfma_f32_16x16x32_bf16 v[106:109], v[160:163], v[204:207], v[106:109]
	v_mfma_f32_16x16x32_bf16 v[94:97], v[144:147], v[212:215], v[94:97]
	v_mfma_f32_16x16x32_bf16 v[90:93], v[160:163], v[212:215], v[90:93]
	v_mfma_f32_16x16x32_bf16 v[78:81], v[144:147], v[220:223], v[78:81]
	v_mfma_f32_16x16x32_bf16 v[74:77], v[160:163], v[220:223], v[74:77]
	v_mfma_f32_16x16x32_bf16 v[118:121], v[164:167], v[180:183], v[118:121]
	v_mfma_f32_16x16x32_bf16 v[114:117], v[172:175], v[180:183], v[114:117]
	v_mfma_f32_16x16x32_bf16 v[102:105], v[164:167], v[188:191], v[102:105]
	v_mfma_f32_16x16x32_bf16 v[98:101], v[172:175], v[188:191], v[98:101]
	v_mfma_f32_16x16x32_bf16 v[86:89], v[164:167], v[208:211], v[86:89]
	v_mfma_f32_16x16x32_bf16 v[82:85], v[172:175], v[208:211], v[82:85]
	v_mfma_f32_16x16x32_bf16 v[70:73], v[164:167], v[216:219], v[70:73]
	v_mfma_f32_16x16x32_bf16 v[66:69], v[172:175], v[216:219], v[66:69]
	v_mfma_f32_16x16x32_bf16 v[118:121], v[168:171], v[184:187], v[118:121]
	v_mfma_f32_16x16x32_bf16 v[114:117], v[176:179], v[184:187], v[114:117]
	v_mfma_f32_16x16x32_bf16 v[102:105], v[168:171], v[204:207], v[102:105]
	v_mfma_f32_16x16x32_bf16 v[98:101], v[176:179], v[204:207], v[98:101]
	v_mfma_f32_16x16x32_bf16 v[86:89], v[168:171], v[212:215], v[86:89]
	v_mfma_f32_16x16x32_bf16 v[82:85], v[176:179], v[212:215], v[82:85]
	v_mfma_f32_16x16x32_bf16 v[70:73], v[168:171], v[220:223], v[70:73]
	v_mfma_f32_16x16x32_bf16 v[66:69], v[176:179], v[220:223], v[66:69]
	s_setprio 0
	s_barrier
	s_add_i32 s14, s45, s46
	v_lshl_add_u64 v[192:193], s[80:81], 0, v[0:1]
	s_mov_b32 m0, s14
	ds_read_b128 v[180:183], v158 offset:16384
	ds_read_b128 v[184:187], v158 offset:17408
	ds_read_b128 v[188:191], v158 offset:18432
	ds_read_b128 v[204:207], v158 offset:19456
	ds_read_b128 v[208:211], v158 offset:20480
	ds_read_b128 v[212:215], v158 offset:21504
	ds_read_b128 v[216:219], v158 offset:22528
	ds_read_b128 v[220:223], v158 offset:23552
	global_load_lds_dwordx4 v[192:193], off
	s_add_i32 m0, s14, 0x2000
	s_add_u32 s14, s80, 0x80000
	v_lshl_add_u64 v[194:195], s[80:81], 0, v[134:135]
	s_addc_u32 s15, s81, 0
	s_add_i32 s45, vcc_hi, s46
	global_load_lds_dwordx4 v[194:195], off
	v_lshl_add_u64 v[196:197], s[14:15], 0, v[0:1]
	s_mov_b32 m0, s45
	v_lshl_add_u64 v[198:199], s[82:83], 0, v[132:133]
	global_load_lds_dwordx4 v[196:197], off
	v_lshl_add_u64 v[196:197], s[14:15], 0, v[134:135]
	s_add_i32 m0, s45, 0x2000
	s_nop 0
	global_load_lds_dwordx4 v[196:197], off
	v_lshl_add_u64 v[196:197], s[82:83], 0, v[130:131]
	s_mov_b32 m0, s47
	s_nop 0
	global_load_lds_dwordx4 v[196:197], off
	s_mov_b32 m0, s56
	s_nop 0
	global_load_lds_dwordx4 v[198:199], off
	s_waitcnt vmcnt(8)
	s_waitcnt lgkmcnt(0)
	s_barrier
; #define PG8_STAGE(bufoff, gbase, voff) do { _Pragma("unroll") for (int _i = 0; _i < 2; ++_i) \
;         __builtin_amdgcn_global_load_lds((const unsigned*)((const char*)(gbase) + (voff)[_i]), (LAS unsigned*)(lds + (bufoff) + ldsw + _i * 8192), 16, 0, 0); } while (0)
; #define PG8_LDA(dst, b, h) do { _Pragma("unroll") for (int m = 0; m < 4; ++m) _Pragma("unroll") for (int k = 0; k < 2; ++k) dst[m][k] = *(const LAS bf16x8*)(lds + PG8_SA(b, h) + aoff + m * 2048 + k * 1024); } while (0)
; #define PG8_LDB(dst, b, h) do { _Pragma("unroll") for (int n = 0; n < 2; ++n) _Pragma("unroll") for (int k = 0; k < 2; ++k) dst[n][k] = *(const LAS bf16x8*)(lds + PG8_SB(b, h) + boff + n * 2048 + k * 1024); } while (0)
; #define PG8_WAIT_V(n) asm volatile("s_waitcnt vmcnt(" #n ")" ::: "memory")
; #define PG8_BAR __builtin_amdgcn_s_barrier()
; template <class Epi, class Sched>
; __device__ __forceinline__ void gemm_phase(LAS unsigned char* lds, const Gemm g, const Sched& S, const Epi& E, const int tid) {
;     ...
;         for (int t = 0; t < nt; t += 2) {
;             const bool last = (t == nt - 2);
;             const char* a1 = cA + (size_t)(t + 1) * kstep;
;             const char* a2 = last ? nA : cA + (size_t)(t + 2) * kstep; const char* b2 = last ? nB : cB + (size_t)(t + 2) * kstep;
;             const char* a3 = a2 + kstep; const char* b3 = b2 + kstep;
;             PG8_LDB(B0, 0, 0); PG8_LDB(B1, 0, 1); PG8_SCHED; PG8_LDA(At, 0, 0); PG8_STAGE(PG8_SA(1, 1), a1 + hstepA, voffA);
;             PG8_WAIT_V(8); PG8_WAIT_L(0); PG8_BAR; PG8_MMA(0, 0, At, B0); PG8_MMA(0, 1, At, B1); PG8_BAR; PG8_SCHED;
;             PG8_LDA(At, 0, 1); PG8_STAGE(PG8_SB(0, 0), b2, voffB); PG8_STAGE(PG8_SB(0, 1), b2 + hstepB, voffB); PG8_STAGE(PG8_SA(0, 0), a2, voffA);
;             PG8_WAIT_V(8); PG8_WAIT_L(0); PG8_BAR; PG8_MMA(1, 0, At, B0); PG8_MMA(1, 1, At, B1); PG8_BAR; PG8_SCHED;
;             PG8_LDB(B0, 1, 0); PG8_LDB(B1, 1, 1); PG8_SCHED; PG8_LDA(At, 1, 0); PG8_STAGE(PG8_SA(0, 1), a2 + hstepA, voffA);
;             PG8_WAIT_V(8); PG8_WAIT_L(0); PG8_BAR; PG8_MMA(0, 0, At, B0); PG8_MMA(0, 1, At, B1); PG8_BAR; PG8_SCHED;
;             PG8_LDA(At, 1, 1); PG8_STAGE(PG8_SB(1, 0), b3, voffB); PG8_STAGE(PG8_SB(1, 1), b3 + hstepB, voffB); PG8_STAGE(PG8_SA(1, 0), a3, voffA);
;             PG8_WAIT_V(8); PG8_WAIT_L(0); PG8_BAR; PG8_MMA(1, 0, At, B0); PG8_MMA(1, 1, At, B1); PG8_BAR; PG8_SCHED;
	s_setprio 1
	v_mfma_f32_16x16x32_bf16 v[62:65], v[140:143], v[180:183], v[62:65]
	v_mfma_f32_16x16x32_bf16 v[58:61], v[148:151], v[180:183], v[58:61]
	v_mfma_f32_16x16x32_bf16 v[46:49], v[140:143], v[188:191], v[46:49]
	v_mfma_f32_16x16x32_bf16 v[42:45], v[148:151], v[188:191], v[42:45]
	v_mfma_f32_16x16x32_bf16 v[30:33], v[140:143], v[208:211], v[30:33]
	v_mfma_f32_16x16x32_bf16 v[26:29], v[148:151], v[208:211], v[26:29]
	v_mfma_f32_16x16x32_bf16 v[14:17], v[140:143], v[216:219], v[14:17]
	v_mfma_f32_16x16x32_bf16 v[10:13], v[148:151], v[216:219], v[10:13]
	v_mfma_f32_16x16x32_bf16 v[62:65], v[144:147], v[184:187], v[62:65]
	v_mfma_f32_16x16x32_bf16 v[58:61], v[160:163], v[184:187], v[58:61]
	v_mfma_f32_16x16x32_bf16 v[46:49], v[144:147], v[204:207], v[46:49]
	v_mfma_f32_16x16x32_bf16 v[42:45], v[160:163], v[204:207], v[42:45]
	v_mfma_f32_16x16x32_bf16 v[30:33], v[144:147], v[212:215], v[30:33]
	v_mfma_f32_16x16x32_bf16 v[26:29], v[160:163], v[212:215], v[26:29]
	v_mfma_f32_16x16x32_bf16 v[14:17], v[144:147], v[220:223], v[14:17]
	v_mfma_f32_16x16x32_bf16 v[10:13], v[160:163], v[220:223], v[10:13]
	v_mfma_f32_16x16x32_bf16 v[54:57], v[164:167], v[180:183], v[54:57]
	v_mfma_f32_16x16x32_bf16 v[50:53], v[172:175], v[180:183], v[50:53]
	v_mfma_f32_16x16x32_bf16 v[38:41], v[164:167], v[188:191], v[38:41]
	v_mfma_f32_16x16x32_bf16 v[34:37], v[172:175], v[188:191], v[34:37]
	v_mfma_f32_16x16x32_bf16 v[22:25], v[164:167], v[208:211], v[22:25]
	v_mfma_f32_16x16x32_bf16 v[18:21], v[172:175], v[208:211], v[18:21]
	v_mfma_f32_16x16x32_bf16 v[6:9], v[164:167], v[216:219], v[6:9]
	v_mfma_f32_16x16x32_bf16 v[2:5], v[172:175], v[216:219], v[2:5]
	v_mfma_f32_16x16x32_bf16 v[54:57], v[168:171], v[184:187], v[54:57]
	v_mfma_f32_16x16x32_bf16 v[50:53], v[176:179], v[184:187], v[50:53]
	v_mfma_f32_16x16x32_bf16 v[38:41], v[168:171], v[204:207], v[38:41]
	v_mfma_f32_16x16x32_bf16 v[34:37], v[176:179], v[204:207], v[34:37]
	v_mfma_f32_16x16x32_bf16 v[22:25], v[168:171], v[212:215], v[22:25]
	v_mfma_f32_16x16x32_bf16 v[18:21], v[176:179], v[212:215], v[18:21]
	v_mfma_f32_16x16x32_bf16 v[6:9], v[168:171], v[220:223], v[6:9]
	v_mfma_f32_16x16x32_bf16 v[2:5], v[176:179], v[220:223], v[2:5]
	s_setprio 0
	s_barrier
	s_add_i32 s45, 0, 0x18000
	v_add_u32_e32 v159, s45, v153
	s_add_i32 vcc_hi, 0, 0x1c000
	ds_read_b128 v[140:143], v159
	ds_read_b128 v[144:147], v159 offset:1024
	ds_read_b128 v[148:151], v159 offset:2048
	ds_read_b128 v[160:163], v159 offset:3072
	v_add_u32_e32 v159, vcc_hi, v153
	ds_read_b128 v[164:167], v159
	ds_read_b128 v[168:171], v159 offset:1024
	ds_read_b128 v[172:175], v159 offset:2048
	ds_read_b128 v[176:179], v159 offset:3072
	s_add_u32 s14, s82, 0x80000
	s_addc_u32 s15, s83, 0
	s_mov_b32 m0, s57
	v_lshl_add_u64 v[200:201], s[14:15], 0, v[130:131]
	ds_read_b128 v[180:183], v158 offset:32768
	ds_read_b128 v[184:187], v158 offset:33792
	ds_read_b128 v[188:191], v158 offset:34816
	ds_read_b128 v[204:207], v158 offset:35840
	ds_read_b128 v[208:211], v158 offset:36864
	ds_read_b128 v[212:215], v158 offset:37888
	ds_read_b128 v[216:219], v158 offset:38912
	ds_read_b128 v[220:223], v158 offset:39936
	global_load_lds_dwordx4 v[200:201], off
	v_lshl_add_u64 v[200:201], s[14:15], 0, v[132:133]
	s_mov_b32 m0, s84
	s_nop 0
	global_load_lds_dwordx4 v[200:201], off
	s_waitcnt vmcnt(8)
	s_waitcnt lgkmcnt(0)
	s_barrier
	s_setprio 1
	v_mfma_f32_16x16x32_bf16 v[126:129], v[140:143], v[180:183], v[126:129]
	v_mfma_f32_16x16x32_bf16 v[122:125], v[148:151], v[180:183], v[122:125]
	v_mfma_f32_16x16x32_bf16 v[110:113], v[140:143], v[188:191], v[110:113]
	v_mfma_f32_16x16x32_bf16 v[106:109], v[148:151], v[188:191], v[106:109]
	v_mfma_f32_16x16x32_bf16 v[94:97], v[140:143], v[208:211], v[94:97]
	v_mfma_f32_16x16x32_bf16 v[90:93], v[148:151], v[208:211], v[90:93]
	v_mfma_f32_16x16x32_bf16 v[78:81], v[140:143], v[216:219], v[78:81]
	v_mfma_f32_16x16x32_bf16 v[74:77], v[148:151], v[216:219], v[74:77]
	v_mfma_f32_16x16x32_bf16 v[126:129], v[144:147], v[184:187], v[126:129]
	v_mfma_f32_16x16x32_bf16 v[122:125], v[160:163], v[184:187], v[122:125]
	v_mfma_f32_16x16x32_bf16 v[110:113], v[144:147], v[204:207], v[110:113]
	v_mfma_f32_16x16x32_bf16 v[106:109], v[160:163], v[204:207], v[106:109]
	v_mfma_f32_16x16x32_bf16 v[94:97], v[144:147], v[212:215], v[94:97]
	v_mfma_f32_16x16x32_bf16 v[90:93], v[160:163], v[212:215], v[90:93]
	v_mfma_f32_16x16x32_bf16 v[78:81], v[144:147], v[220:223], v[78:81]
	v_mfma_f32_16x16x32_bf16 v[74:77], v[160:163], v[220:223], v[74:77]
	v_mfma_f32_16x16x32_bf16 v[118:121], v[164:167], v[180:183], v[118:121]
	v_mfma_f32_16x16x32_bf16 v[114:117], v[172:175], v[180:183], v[114:117]
	v_mfma_f32_16x16x32_bf16 v[102:105], v[164:167], v[188:191], v[102:105]
	v_mfma_f32_16x16x32_bf16 v[98:101], v[172:175], v[188:191], v[98:101]
	v_mfma_f32_16x16x32_bf16 v[86:89], v[164:167], v[208:211], v[86:89]
	v_mfma_f32_16x16x32_bf16 v[82:85], v[172:175], v[208:211], v[82:85]
	v_mfma_f32_16x16x32_bf16 v[70:73], v[164:167], v[216:219], v[70:73]
	v_mfma_f32_16x16x32_bf16 v[66:69], v[172:175], v[216:219], v[66:69]
	v_mfma_f32_16x16x32_bf16 v[118:121], v[168:171], v[184:187], v[118:121]
	v_mfma_f32_16x16x32_bf16 v[114:117], v[176:179], v[184:187], v[114:117]
	v_mfma_f32_16x16x32_bf16 v[102:105], v[168:171], v[204:207], v[102:105]
	v_mfma_f32_16x16x32_bf16 v[98:101], v[176:179], v[204:207], v[98:101]
	v_mfma_f32_16x16x32_bf16 v[86:89], v[168:171], v[212:215], v[86:89]
	v_mfma_f32_16x16x32_bf16 v[82:85], v[176:179], v[212:215], v[82:85]
	v_mfma_f32_16x16x32_bf16 v[70:73], v[168:171], v[220:223], v[70:73]
	v_mfma_f32_16x16x32_bf16 v[66:69], v[176:179], v[220:223], v[66:69]
	s_setprio 0
	s_barrier
; #define PG8_STAGE(bufoff, gbase, voff) do { _Pragma("unroll") for (int _i = 0; _i < 2; ++_i) \
;         __builtin_amdgcn_global_load_lds((const unsigned*)((const char*)(gbase) + (voff)[_i]), (LAS unsigned*)(lds + (bufoff) + ldsw + _i * 8192), 16, 0, 0); } while (0)
; #define PG8_LDA(dst, b, h) do { _Pragma("unroll") for (int m = 0; m < 4; ++m) _Pragma("unroll") for (int k = 0; k < 2; ++k) dst[m][k] = *(const LAS bf16x8*)(lds + PG8_SA(b, h) + aoff + m * 2048 + k * 1024); } while (0)
; #define PG8_LDB(dst, b, h) do { _Pragma("unroll") for (int n = 0; n < 2; ++n) _Pragma("unroll") for (int k = 0; k < 2; ++k) dst[n][k] = *(const LAS bf16x8*)(lds + PG8_SB(b, h) + boff + n * 2048 + k * 1024); } while (0)
; #define PG8_WAIT_V(n) asm volatile("s_waitcnt vmcnt(" #n ")" ::: "memory")
; template <class Epi, class Sched>
; __device__ __forceinline__ void gemm_phase(LAS unsigned char* lds, const Gemm g, const Sched& S, const Epi& E, const int tid) {
;     ...
;         for (int t = 0; t < nt; t += 2) {
;             const bool last = (t == nt - 2);
;             const char* a1 = cA + (size_t)(t + 1) * kstep;
;             const char* a2 = last ? nA : cA + (size_t)(t + 2) * kstep; const char* b2 = last ? nB : cB + (size_t)(t + 2) * kstep;
;             const char* a3 = a2 + kstep; const char* b3 = b2 + kstep;
;             PG8_LDB(B0, 0, 0); PG8_LDB(B1, 0, 1); PG8_SCHED; PG8_LDA(At, 0, 0); PG8_STAGE(PG8_SA(1, 1), a1 + hstepA, voffA);
;             PG8_WAIT_V(8); PG8_WAIT_L(0); PG8_BAR; PG8_MMA(0, 0, At, B0); PG8_MMA(0, 1, At, B1); PG8_BAR; PG8_SCHED;
;             PG8_LDA(At, 0, 1); PG8_STAGE(PG8_SB(0, 0), b2, voffB); PG8_STAGE(PG8_SB(0, 1), b2 + hstepB, voffB); PG8_STAGE(PG8_SA(0, 0), a2, voffA);
;             PG8_WAIT_V(8); PG8_WAIT_L(0); PG8_BAR; PG8_MMA(1, 0, At, B0); PG8_MMA(1, 1, At, B1); PG8_BAR; PG8_SCHED;
;             PG8_LDB(B0, 1, 0); PG8_LDB(B1, 1, 1); PG8_SCHED; PG8_LDA(At, 1, 0); PG8_STAGE(PG8_SA(0, 1), a2 + hstepA, voffA);
;             PG8_WAIT_V(8); PG8_WAIT_L(0); PG8_BAR; PG8_MMA(0, 0, At, B0); PG8_MMA(0, 1, At, B1); PG8_BAR; PG8_SCHED;
;             PG8_LDA(At, 1, 1); PG8_STAGE(PG8_SB(1, 0), b3, voffB); PG8_STAGE(PG8_SB(1, 1), b3 + hstepB, voffB); PG8_STAGE(PG8_SA(1, 0), a3, voffA);
;             PG8_WAIT_V(8); PG8_WAIT_L(0); PG8_BAR; PG8_MMA(1, 0, At, B0); PG8_MMA(1, 1, At, B1); PG8_BAR; PG8_SCHED;
;         }
;         if (wr == 0) PG8_BAR;
	s_add_i32 s14, s45, s46
	v_lshl_add_u64 v[192:193], v[192:193], 0, s[90:91]
	s_mov_b32 m0, s14
	ds_read_b128 v[180:183], v158 offset:49152
	ds_read_b128 v[184:187], v158 offset:50176
	ds_read_b128 v[188:191], v158 offset:51200
	ds_read_b128 v[204:207], v158 offset:52224
	ds_read_b128 v[208:211], v158 offset:53248
	ds_read_b128 v[212:215], v158 offset:54272
	ds_read_b128 v[216:219], v158 offset:55296
	ds_read_b128 v[220:223], v158 offset:56320
	global_load_lds_dwordx4 v[192:193], off
	s_add_i32 m0, s14, 0x2000
	s_add_u32 s14, s80, 0x80080
	v_lshl_add_u64 v[192:193], v[194:195], 0, s[90:91]
	s_addc_u32 s15, s81, 0
	s_add_i32 s45, vcc_hi, s46
	global_load_lds_dwordx4 v[192:193], off
	v_lshl_add_u64 v[192:193], s[14:15], 0, v[0:1]
	s_mov_b32 m0, s45
	s_nop 0
	global_load_lds_dwordx4 v[192:193], off
	v_lshl_add_u64 v[192:193], s[14:15], 0, v[134:135]
	s_add_i32 m0, s45, 0x2000
	s_nop 0
	global_load_lds_dwordx4 v[192:193], off
	v_lshl_add_u64 v[192:193], v[196:197], 0, s[90:91]
	s_mov_b32 m0, s85
	s_nop 0
	global_load_lds_dwordx4 v[192:193], off
	v_lshl_add_u64 v[192:193], v[198:199], 0, s[90:91]
	s_mov_b32 m0, s58
	s_nop 0
	global_load_lds_dwordx4 v[192:193], off
	s_waitcnt vmcnt(8)
	s_waitcnt lgkmcnt(0)
	s_barrier
	s_setprio 1
	v_mfma_f32_16x16x32_bf16 v[62:65], v[140:143], v[180:183], v[62:65]
	v_mfma_f32_16x16x32_bf16 v[58:61], v[148:151], v[180:183], v[58:61]
	v_mfma_f32_16x16x32_bf16 v[46:49], v[140:143], v[188:191], v[46:49]
	v_mfma_f32_16x16x32_bf16 v[42:45], v[148:151], v[188:191], v[42:45]
	v_mfma_f32_16x16x32_bf16 v[30:33], v[140:143], v[208:211], v[30:33]
	v_mfma_f32_16x16x32_bf16 v[26:29], v[148:151], v[208:211], v[26:29]
	v_mfma_f32_16x16x32_bf16 v[14:17], v[140:143], v[216:219], v[14:17]
	v_mfma_f32_16x16x32_bf16 v[10:13], v[148:151], v[216:219], v[10:13]
	v_mfma_f32_16x16x32_bf16 v[62:65], v[144:147], v[184:187], v[62:65]
	v_mfma_f32_16x16x32_bf16 v[58:61], v[160:163], v[184:187], v[58:61]
	v_mfma_f32_16x16x32_bf16 v[46:49], v[144:147], v[204:207], v[46:49]
	v_mfma_f32_16x16x32_bf16 v[42:45], v[160:163], v[204:207], v[42:45]
	v_mfma_f32_16x16x32_bf16 v[30:33], v[144:147], v[212:215], v[30:33]
	v_mfma_f32_16x16x32_bf16 v[26:29], v[160:163], v[212:215], v[26:29]
	v_mfma_f32_16x16x32_bf16 v[14:17], v[144:147], v[220:223], v[14:17]
	v_mfma_f32_16x16x32_bf16 v[10:13], v[160:163], v[220:223], v[10:13]
	v_mfma_f32_16x16x32_bf16 v[54:57], v[164:167], v[180:183], v[54:57]
	v_mfma_f32_16x16x32_bf16 v[50:53], v[172:175], v[180:183], v[50:53]
	v_mfma_f32_16x16x32_bf16 v[38:41], v[164:167], v[188:191], v[38:41]
	v_mfma_f32_16x16x32_bf16 v[34:37], v[172:175], v[188:191], v[34:37]
	v_mfma_f32_16x16x32_bf16 v[22:25], v[164:167], v[208:211], v[22:25]
	v_mfma_f32_16x16x32_bf16 v[18:21], v[172:175], v[208:211], v[18:21]
	v_mfma_f32_16x16x32_bf16 v[6:9], v[164:167], v[216:219], v[6:9]
	v_mfma_f32_16x16x32_bf16 v[2:5], v[172:175], v[216:219], v[2:5]
	v_mfma_f32_16x16x32_bf16 v[54:57], v[168:171], v[184:187], v[54:57]
	v_mfma_f32_16x16x32_bf16 v[50:53], v[176:179], v[184:187], v[50:53]
	v_mfma_f32_16x16x32_bf16 v[38:41], v[168:171], v[204:207], v[38:41]
	v_mfma_f32_16x16x32_bf16 v[34:37], v[176:179], v[204:207], v[34:37]
	v_mfma_f32_16x16x32_bf16 v[22:25], v[168:171], v[212:215], v[22:25]
	v_mfma_f32_16x16x32_bf16 v[18:21], v[176:179], v[212:215], v[18:21]
	v_mfma_f32_16x16x32_bf16 v[6:9], v[168:171], v[220:223], v[6:9]
	v_mfma_f32_16x16x32_bf16 v[2:5], v[176:179], v[220:223], v[2:5]
	s_setprio 0
	s_barrier
	s_add_i32 s44, s44, 2
	s_add_u32 s77, s77, 0x100
	s_addc_u32 vcc_lo, vcc_lo, 0
	s_add_u32 s78, s78, 0x100
	s_addc_u32 s79, s79, 0
	s_cmp_gt_u32 s44, 29
	s_cbranch_scc0 .LBB1_448
	s_and_b64 vcc, exec, s[36:37]
	s_cbranch_vccz .LBB1_451
	s_barrier

; #define PG8_STAGE(bufoff, gbase, voff) do { _Pragma("unroll") for (int _i = 0; _i < 2; ++_i) \
;         __builtin_amdgcn_global_load_lds((const unsigned*)((const char*)(gbase) + (voff)[_i]), (LAS unsigned*)(lds + (bufoff) + ldsw + _i * 8192), 16, 0, 0); } while (0)
; #define PG8_LDA(dst, b, h) do { _Pragma("unroll") for (int m = 0; m < 4; ++m) _Pragma("unroll") for (int k = 0; k < 2; ++k) dst[m][k] = *(const LAS bf16x8*)(lds + PG8_SA(b, h) + aoff + m * 2048 + k * 1024); } while (0)
; #define PG8_LDB(dst, b, h) do { _Pragma("unroll") for (int n = 0; n < 2; ++n) _Pragma("unroll") for (int k = 0; k < 2; ++k) dst[n][k] = *(const LAS bf16x8*)(lds + PG8_SB(b, h) + boff + n * 2048 + k * 1024); } while (0)
; #define PG8_WAIT_V(n) asm volatile("s_waitcnt vmcnt(" #n ")" ::: "memory")
; #define PG8_BAR __builtin_amdgcn_s_barrier()
; template <class Epi, class Sched>
; __device__ __forceinline__ void gemm_phase(LAS unsigned char* lds, const Gemm g, const Sched& S, const Epi& E, const int tid) {
;     ...
;         for (int t = 0; t < nt; t += 2) {
;             const bool last = (t == nt - 2);
;             const char* a1 = cA + (size_t)(t + 1) * kstep;
;             const char* a2 = last ? nA : cA + (size_t)(t + 2) * kstep; const char* b2 = last ? nB : cB + (size_t)(t + 2) * kstep;
;             const char* a3 = a2 + kstep; const char* b3 = b2 + kstep;
;             PG8_LDB(B0, 0, 0); PG8_LDB(B1, 0, 1); PG8_SCHED; PG8_LDA(At, 0, 0); PG8_STAGE(PG8_SA(1, 1), a1 + hstepA, voffA);
;             PG8_WAIT_V(8); PG8_WAIT_L(0); PG8_BAR; PG8_MMA(0, 0, At, B0); PG8_MMA(0, 1, At, B1); PG8_BAR; PG8_SCHED;
;             PG8_LDA(At, 0, 1); PG8_STAGE(PG8_SB(0, 0), b2, voffB); PG8_STAGE(PG8_SB(0, 1), b2 + hstepB, voffB); PG8_STAGE(PG8_SA(0, 0), a2, voffA);
;             PG8_WAIT_V(8); PG8_WAIT_L(0); PG8_BAR; PG8_MMA(1, 0, At, B0); PG8_MMA(1, 1, At, B1); PG8_BAR; PG8_SCHED;
;             PG8_LDB(B0, 1, 0); PG8_LDB(B1, 1, 1); PG8_SCHED; PG8_LDA(At, 1, 0); PG8_STAGE(PG8_SA(0, 1), a2 + hstepA, voffA);
;             PG8_WAIT_V(8); PG8_WAIT_L(0); PG8_BAR; PG8_MMA(0, 0, At, B0); PG8_MMA(0, 1, At, B1); PG8_BAR; PG8_SCHED;
;             PG8_LDA(At, 1, 1); PG8_STAGE(PG8_SB(1, 0), b3, voffB); PG8_STAGE(PG8_SB(1, 1), b3 + hstepB, voffB); PG8_STAGE(PG8_SA(1, 0), a3, voffA);
;             PG8_WAIT_V(8); PG8_WAIT_L(0); PG8_BAR; PG8_MMA(1, 0, At, B0); PG8_MMA(1, 1, At, B1); PG8_BAR; PG8_SCHED;
.LBB1_574:
	s_add_u32 s14, s44, 0xfff80080
	s_addc_u32 s15, s45, -1
	s_add_i32 s82, 0, 0x10000
	s_cmp_eq_u32 s81, 28
	s_cselect_b32 s73, s43, s15
	s_cselect_b32 s72, s47, s14
	v_add_u32_e32 v148, s82, v151
	s_cselect_b32 s71, s61, s80
	s_cselect_b32 s70, s65, s79
	s_add_i32 s83, 0, 0x14000
	ds_read_b128 v[144:147], v148
	ds_read_b128 v[158:161], v148 offset:1024
	ds_read_b128 v[162:165], v148 offset:2048
	ds_read_b128 v[166:169], v148 offset:3072
	v_add_u32_e32 v148, s83, v151
	ds_read_b128 v[170:173], v148
	ds_read_b128 v[174:177], v148 offset:1024
	ds_read_b128 v[178:181], v148 offset:2048
	ds_read_b128 v[182:185], v148 offset:3072
	v_lshl_add_u64 v[148:149], s[44:45], 0, v[142:143]
	s_add_i32 m0, s57, 0xc000
	ds_read_b128 v[186:189], v156
	ds_read_b128 v[190:193], v156 offset:1024
	ds_read_b128 v[204:207], v156 offset:2048
	ds_read_b128 v[208:211], v156 offset:3072
	ds_read_b128 v[212:215], v156 offset:4096
	ds_read_b128 v[216:219], v156 offset:5120
	ds_read_b128 v[220:223], v156 offset:6144
	ds_read_b128 v[230:233], v156 offset:7168
	global_load_lds_dwordx4 v[148:149], off
	v_lshl_add_u64 v[148:149], s[44:45], 0, v[140:141]
	s_add_i32 m0, s57, 0xe000
	s_nop 0
	global_load_lds_dwordx4 v[148:149], off
	s_waitcnt vmcnt(8)
	s_waitcnt lgkmcnt(0)
	s_barrier
	s_setprio 1
	v_mfma_f32_16x16x32_bf16 v[126:129], v[144:147], v[186:189], v[126:129]
	v_mfma_f32_16x16x32_bf16 v[122:125], v[162:165], v[186:189], v[122:125]
	v_mfma_f32_16x16x32_bf16 v[110:113], v[144:147], v[204:207], v[110:113]
	v_mfma_f32_16x16x32_bf16 v[106:109], v[162:165], v[204:207], v[106:109]
	v_mfma_f32_16x16x32_bf16 v[94:97], v[144:147], v[212:215], v[94:97]
	v_mfma_f32_16x16x32_bf16 v[90:93], v[162:165], v[212:215], v[90:93]
	v_mfma_f32_16x16x32_bf16 v[78:81], v[144:147], v[220:223], v[78:81]
	v_mfma_f32_16x16x32_bf16 v[74:77], v[162:165], v[220:223], v[74:77]
	v_mfma_f32_16x16x32_bf16 v[126:129], v[158:161], v[190:193], v[126:129]
	v_mfma_f32_16x16x32_bf16 v[122:125], v[166:169], v[190:193], v[122:125]
	v_mfma_f32_16x16x32_bf16 v[110:113], v[158:161], v[208:211], v[110:113]
	v_mfma_f32_16x16x32_bf16 v[106:109], v[166:169], v[208:211], v[106:109]
	v_mfma_f32_16x16x32_bf16 v[94:97], v[158:161], v[216:219], v[94:97]
	v_mfma_f32_16x16x32_bf16 v[90:93], v[166:169], v[216:219], v[90:93]
	v_mfma_f32_16x16x32_bf16 v[78:81], v[158:161], v[230:233], v[78:81]
	v_mfma_f32_16x16x32_bf16 v[74:77], v[166:169], v[230:233], v[74:77]
	v_mfma_f32_16x16x32_bf16 v[118:121], v[170:173], v[186:189], v[118:121]
	v_mfma_f32_16x16x32_bf16 v[114:117], v[178:181], v[186:189], v[114:117]
	v_mfma_f32_16x16x32_bf16 v[102:105], v[170:173], v[204:207], v[102:105]
	v_mfma_f32_16x16x32_bf16 v[98:101], v[178:181], v[204:207], v[98:101]
	v_mfma_f32_16x16x32_bf16 v[86:89], v[170:173], v[212:215], v[86:89]
	v_mfma_f32_16x16x32_bf16 v[82:85], v[178:181], v[212:215], v[82:85]
	v_mfma_f32_16x16x32_bf16 v[70:73], v[170:173], v[220:223], v[70:73]
	v_mfma_f32_16x16x32_bf16 v[66:69], v[178:181], v[220:223], v[66:69]
	v_mfma_f32_16x16x32_bf16 v[118:121], v[174:177], v[190:193], v[118:121]
	v_mfma_f32_16x16x32_bf16 v[114:117], v[182:185], v[190:193], v[114:117]
	v_mfma_f32_16x16x32_bf16 v[102:105], v[174:177], v[208:211], v[102:105]
	v_mfma_f32_16x16x32_bf16 v[98:101], v[182:185], v[208:211], v[98:101]
	v_mfma_f32_16x16x32_bf16 v[86:89], v[174:177], v[216:219], v[86:89]
	v_mfma_f32_16x16x32_bf16 v[82:85], v[182:185], v[216:219], v[82:85]
	v_mfma_f32_16x16x32_bf16 v[70:73], v[174:177], v[230:233], v[70:73]
	v_mfma_f32_16x16x32_bf16 v[66:69], v[182:185], v[230:233], v[66:69]
	s_setprio 0
	s_barrier
	s_add_i32 s14, s82, s56
	v_lshl_add_u64 v[148:149], s[70:71], 0, v[0:1]
	s_mov_b32 m0, s14
	ds_read_b128 v[186:189], v156 offset:16384
	ds_read_b128 v[190:193], v156 offset:17408
	ds_read_b128 v[204:207], v156 offset:18432
	ds_read_b128 v[208:211], v156 offset:19456
	ds_read_b128 v[212:215], v156 offset:20480
	ds_read_b128 v[216:219], v156 offset:21504
	ds_read_b128 v[220:223], v156 offset:22528
	ds_read_b128 v[230:233], v156 offset:23552
	global_load_lds_dwordx4 v[148:149], off
	s_add_i32 m0, s14, 0x2000
	s_add_u32 s14, s70, 0x80000
	v_lshl_add_u64 v[194:195], s[70:71], 0, v[134:135]
	s_addc_u32 s15, s71, 0
	s_add_i32 s82, s83, s56
	global_load_lds_dwordx4 v[194:195], off
	v_lshl_add_u64 v[196:197], s[14:15], 0, v[0:1]
	s_mov_b32 m0, s82
	v_lshl_add_u64 v[198:199], s[72:73], 0, v[132:133]
	global_load_lds_dwordx4 v[196:197], off
	v_lshl_add_u64 v[196:197], s[14:15], 0, v[134:135]
	s_add_i32 m0, s82, 0x2000
	s_nop 0
	global_load_lds_dwordx4 v[196:197], off
	v_lshl_add_u64 v[196:197], s[72:73], 0, v[130:131]
	s_mov_b32 m0, s57
	s_nop 0
	global_load_lds_dwordx4 v[196:197], off
	s_mov_b32 m0, s74
	s_nop 0
	global_load_lds_dwordx4 v[198:199], off
	s_waitcnt vmcnt(8)
	s_waitcnt lgkmcnt(0)
	s_barrier
; #define PG8_STAGE(bufoff, gbase, voff) do { _Pragma("unroll") for (int _i = 0; _i < 2; ++_i) \
;         __builtin_amdgcn_global_load_lds((const unsigned*)((const char*)(gbase) + (voff)[_i]), (LAS unsigned*)(lds + (bufoff) + ldsw + _i * 8192), 16, 0, 0); } while (0)
; #define PG8_LDA(dst, b, h) do { _Pragma("unroll") for (int m = 0; m < 4; ++m) _Pragma("unroll") for (int k = 0; k < 2; ++k) dst[m][k] = *(const LAS bf16x8*)(lds + PG8_SA(b, h) + aoff + m * 2048 + k * 1024); } while (0)
; #define PG8_LDB(dst, b, h) do { _Pragma("unroll") for (int n = 0; n < 2; ++n) _Pragma("unroll") for (int k = 0; k < 2; ++k) dst[n][k] = *(const LAS bf16x8*)(lds + PG8_SB(b, h) + boff + n * 2048 + k * 1024); } while (0)
; #define PG8_WAIT_V(n) asm volatile("s_waitcnt vmcnt(" #n ")" ::: "memory")
; #define PG8_BAR __builtin_amdgcn_s_barrier()
; template <class Epi, class Sched>
; __device__ __forceinline__ void gemm_phase(LAS unsigned char* lds, const Gemm g, const Sched& S, const Epi& E, const int tid) {
;     ...
;         for (int t = 0; t < nt; t += 2) {
;             const bool last = (t == nt - 2);
;             const char* a1 = cA + (size_t)(t + 1) * kstep;
;             const char* a2 = last ? nA : cA + (size_t)(t + 2) * kstep; const char* b2 = last ? nB : cB + (size_t)(t + 2) * kstep;
;             const char* a3 = a2 + kstep; const char* b3 = b2 + kstep;
;             PG8_LDB(B0, 0, 0); PG8_LDB(B1, 0, 1); PG8_SCHED; PG8_LDA(At, 0, 0); PG8_STAGE(PG8_SA(1, 1), a1 + hstepA, voffA);
;             PG8_WAIT_V(8); PG8_WAIT_L(0); PG8_BAR; PG8_MMA(0, 0, At, B0); PG8_MMA(0, 1, At, B1); PG8_BAR; PG8_SCHED;
;             PG8_LDA(At, 0, 1); PG8_STAGE(PG8_SB(0, 0), b2, voffB); PG8_STAGE(PG8_SB(0, 1), b2 + hstepB, voffB); PG8_STAGE(PG8_SA(0, 0), a2, voffA);
;             PG8_WAIT_V(8); PG8_WAIT_L(0); PG8_BAR; PG8_MMA(1, 0, At, B0); PG8_MMA(1, 1, At, B1); PG8_BAR; PG8_SCHED;
;             PG8_LDB(B0, 1, 0); PG8_LDB(B1, 1, 1); PG8_SCHED; PG8_LDA(At, 1, 0); PG8_STAGE(PG8_SA(0, 1), a2 + hstepA, voffA);
;             PG8_WAIT_V(8); PG8_WAIT_L(0); PG8_BAR; PG8_MMA(0, 0, At, B0); PG8_MMA(0, 1, At, B1); PG8_BAR; PG8_SCHED;
;             PG8_LDA(At, 1, 1); PG8_STAGE(PG8_SB(1, 0), b3, voffB); PG8_STAGE(PG8_SB(1, 1), b3 + hstepB, voffB); PG8_STAGE(PG8_SA(1, 0), a3, voffA);
;             PG8_WAIT_V(8); PG8_WAIT_L(0); PG8_BAR; PG8_MMA(1, 0, At, B0); PG8_MMA(1, 1, At, B1); PG8_BAR; PG8_SCHED;
	s_setprio 1
	v_mfma_f32_16x16x32_bf16 v[62:65], v[144:147], v[186:189], v[62:65]
	v_mfma_f32_16x16x32_bf16 v[58:61], v[162:165], v[186:189], v[58:61]
	v_mfma_f32_16x16x32_bf16 v[46:49], v[144:147], v[204:207], v[46:49]
	v_mfma_f32_16x16x32_bf16 v[42:45], v[162:165], v[204:207], v[42:45]
	v_mfma_f32_16x16x32_bf16 v[30:33], v[144:147], v[212:215], v[30:33]
	v_mfma_f32_16x16x32_bf16 v[26:29], v[162:165], v[212:215], v[26:29]
	v_mfma_f32_16x16x32_bf16 v[14:17], v[144:147], v[220:223], v[14:17]
	v_mfma_f32_16x16x32_bf16 v[10:13], v[162:165], v[220:223], v[10:13]
	v_mfma_f32_16x16x32_bf16 v[62:65], v[158:161], v[190:193], v[62:65]
	v_mfma_f32_16x16x32_bf16 v[58:61], v[166:169], v[190:193], v[58:61]
	v_mfma_f32_16x16x32_bf16 v[46:49], v[158:161], v[208:211], v[46:49]
	v_mfma_f32_16x16x32_bf16 v[42:45], v[166:169], v[208:211], v[42:45]
	v_mfma_f32_16x16x32_bf16 v[30:33], v[158:161], v[216:219], v[30:33]
	v_mfma_f32_16x16x32_bf16 v[26:29], v[166:169], v[216:219], v[26:29]
	v_mfma_f32_16x16x32_bf16 v[14:17], v[158:161], v[230:233], v[14:17]
	v_mfma_f32_16x16x32_bf16 v[10:13], v[166:169], v[230:233], v[10:13]
	v_mfma_f32_16x16x32_bf16 v[54:57], v[170:173], v[186:189], v[54:57]
	v_mfma_f32_16x16x32_bf16 v[50:53], v[178:181], v[186:189], v[50:53]
	v_mfma_f32_16x16x32_bf16 v[38:41], v[170:173], v[204:207], v[38:41]
	v_mfma_f32_16x16x32_bf16 v[34:37], v[178:181], v[204:207], v[34:37]
	v_mfma_f32_16x16x32_bf16 v[22:25], v[170:173], v[212:215], v[22:25]
	v_mfma_f32_16x16x32_bf16 v[18:21], v[178:181], v[212:215], v[18:21]
	v_mfma_f32_16x16x32_bf16 v[6:9], v[170:173], v[220:223], v[6:9]
	v_mfma_f32_16x16x32_bf16 v[2:5], v[178:181], v[220:223], v[2:5]
	v_mfma_f32_16x16x32_bf16 v[54:57], v[174:177], v[190:193], v[54:57]
	v_mfma_f32_16x16x32_bf16 v[50:53], v[182:185], v[190:193], v[50:53]
	v_mfma_f32_16x16x32_bf16 v[38:41], v[174:177], v[208:211], v[38:41]
	v_mfma_f32_16x16x32_bf16 v[34:37], v[182:185], v[208:211], v[34:37]
	v_mfma_f32_16x16x32_bf16 v[22:25], v[174:177], v[216:219], v[22:25]
	v_mfma_f32_16x16x32_bf16 v[18:21], v[182:185], v[216:219], v[18:21]
	v_mfma_f32_16x16x32_bf16 v[6:9], v[174:177], v[230:233], v[6:9]
	v_mfma_f32_16x16x32_bf16 v[2:5], v[182:185], v[230:233], v[2:5]
	s_setprio 0
	s_barrier
	s_add_i32 s82, 0, 0x18000
	v_add_u32_e32 v157, s82, v151
	s_add_i32 s83, 0, 0x1c000
	ds_read_b128 v[144:147], v157
	ds_read_b128 v[158:161], v157 offset:1024
	ds_read_b128 v[162:165], v157 offset:2048
	ds_read_b128 v[166:169], v157 offset:3072
	v_add_u32_e32 v157, s83, v151
	ds_read_b128 v[170:173], v157
	ds_read_b128 v[174:177], v157 offset:1024
	ds_read_b128 v[178:181], v157 offset:2048
	ds_read_b128 v[182:185], v157 offset:3072
	s_add_u32 s14, s72, 0x80000
	s_addc_u32 s15, s73, 0
	s_mov_b32 m0, s75
	v_lshl_add_u64 v[200:201], s[14:15], 0, v[130:131]
	ds_read_b128 v[186:189], v156 offset:32768
	ds_read_b128 v[190:193], v156 offset:33792
	ds_read_b128 v[204:207], v156 offset:34816
	ds_read_b128 v[208:211], v156 offset:35840
	ds_read_b128 v[212:215], v156 offset:36864
	ds_read_b128 v[216:219], v156 offset:37888
	ds_read_b128 v[220:223], v156 offset:38912
	ds_read_b128 v[230:233], v156 offset:39936
	global_load_lds_dwordx4 v[200:201], off
	v_lshl_add_u64 v[200:201], s[14:15], 0, v[132:133]
	s_mov_b32 m0, s76
	s_nop 0
	global_load_lds_dwordx4 v[200:201], off
	s_waitcnt vmcnt(8)
	s_waitcnt lgkmcnt(0)
	s_barrier
	s_setprio 1
	v_mfma_f32_16x16x32_bf16 v[126:129], v[144:147], v[186:189], v[126:129]
	v_mfma_f32_16x16x32_bf16 v[122:125], v[162:165], v[186:189], v[122:125]
	v_mfma_f32_16x16x32_bf16 v[110:113], v[144:147], v[204:207], v[110:113]
	v_mfma_f32_16x16x32_bf16 v[106:109], v[162:165], v[204:207], v[106:109]
	v_mfma_f32_16x16x32_bf16 v[94:97], v[144:147], v[212:215], v[94:97]
	v_mfma_f32_16x16x32_bf16 v[90:93], v[162:165], v[212:215], v[90:93]
	v_mfma_f32_16x16x32_bf16 v[78:81], v[144:147], v[220:223], v[78:81]
	v_mfma_f32_16x16x32_bf16 v[74:77], v[162:165], v[220:223], v[74:77]
	v_mfma_f32_16x16x32_bf16 v[126:129], v[158:161], v[190:193], v[126:129]
	v_mfma_f32_16x16x32_bf16 v[122:125], v[166:169], v[190:193], v[122:125]
	v_mfma_f32_16x16x32_bf16 v[110:113], v[158:161], v[208:211], v[110:113]
	v_mfma_f32_16x16x32_bf16 v[106:109], v[166:169], v[208:211], v[106:109]
	v_mfma_f32_16x16x32_bf16 v[94:97], v[158:161], v[216:219], v[94:97]
	v_mfma_f32_16x16x32_bf16 v[90:93], v[166:169], v[216:219], v[90:93]
	v_mfma_f32_16x16x32_bf16 v[78:81], v[158:161], v[230:233], v[78:81]
	v_mfma_f32_16x16x32_bf16 v[74:77], v[166:169], v[230:233], v[74:77]
	v_mfma_f32_16x16x32_bf16 v[118:121], v[170:173], v[186:189], v[118:121]
	v_mfma_f32_16x16x32_bf16 v[114:117], v[178:181], v[186:189], v[114:117]
	v_mfma_f32_16x16x32_bf16 v[102:105], v[170:173], v[204:207], v[102:105]
	v_mfma_f32_16x16x32_bf16 v[98:101], v[178:181], v[204:207], v[98:101]
	v_mfma_f32_16x16x32_bf16 v[86:89], v[170:173], v[212:215], v[86:89]
	v_mfma_f32_16x16x32_bf16 v[82:85], v[178:181], v[212:215], v[82:85]
	v_mfma_f32_16x16x32_bf16 v[70:73], v[170:173], v[220:223], v[70:73]
	v_mfma_f32_16x16x32_bf16 v[66:69], v[178:181], v[220:223], v[66:69]
	v_mfma_f32_16x16x32_bf16 v[118:121], v[174:177], v[190:193], v[118:121]
	v_mfma_f32_16x16x32_bf16 v[114:117], v[182:185], v[190:193], v[114:117]
	v_mfma_f32_16x16x32_bf16 v[102:105], v[174:177], v[208:211], v[102:105]
	v_mfma_f32_16x16x32_bf16 v[98:101], v[182:185], v[208:211], v[98:101]
	v_mfma_f32_16x16x32_bf16 v[86:89], v[174:177], v[216:219], v[86:89]
	v_mfma_f32_16x16x32_bf16 v[82:85], v[182:185], v[216:219], v[82:85]
	v_mfma_f32_16x16x32_bf16 v[70:73], v[174:177], v[230:233], v[70:73]
	v_mfma_f32_16x16x32_bf16 v[66:69], v[182:185], v[230:233], v[66:69]
	s_setprio 0
	s_barrier
; #define PG8_STAGE(bufoff, gbase, voff) do { _Pragma("unroll") for (int _i = 0; _i < 2; ++_i) \
;         __builtin_amdgcn_global_load_lds((const unsigned*)((const char*)(gbase) + (voff)[_i]), (LAS unsigned*)(lds + (bufoff) + ldsw + _i * 8192), 16, 0, 0); } while (0)
; #define PG8_LDA(dst, b, h) do { _Pragma("unroll") for (int m = 0; m < 4; ++m) _Pragma("unroll") for (int k = 0; k < 2; ++k) dst[m][k] = *(const LAS bf16x8*)(lds + PG8_SA(b, h) + aoff + m * 2048 + k * 1024); } while (0)
; #define PG8_LDB(dst, b, h) do { _Pragma("unroll") for (int n = 0; n < 2; ++n) _Pragma("unroll") for (int k = 0; k < 2; ++k) dst[n][k] = *(const LAS bf16x8*)(lds + PG8_SB(b, h) + boff + n * 2048 + k * 1024); } while (0)
; #define PG8_WAIT_V(n) asm volatile("s_waitcnt vmcnt(" #n ")" ::: "memory")
; template <class Epi, class Sched>
; __device__ __forceinline__ void gemm_phase(LAS unsigned char* lds, const Gemm g, const Sched& S, const Epi& E, const int tid) {
;     ...
;         for (int t = 0; t < nt; t += 2) {
;             const bool last = (t == nt - 2);
;             const char* a1 = cA + (size_t)(t + 1) * kstep;
;             const char* a2 = last ? nA : cA + (size_t)(t + 2) * kstep; const char* b2 = last ? nB : cB + (size_t)(t + 2) * kstep;
;             const char* a3 = a2 + kstep; const char* b3 = b2 + kstep;
;             PG8_LDB(B0, 0, 0); PG8_LDB(B1, 0, 1); PG8_SCHED; PG8_LDA(At, 0, 0); PG8_STAGE(PG8_SA(1, 1), a1 + hstepA, voffA);
;             PG8_WAIT_V(8); PG8_WAIT_L(0); PG8_BAR; PG8_MMA(0, 0, At, B0); PG8_MMA(0, 1, At, B1); PG8_BAR; PG8_SCHED;
;             PG8_LDA(At, 0, 1); PG8_STAGE(PG8_SB(0, 0), b2, voffB); PG8_STAGE(PG8_SB(0, 1), b2 + hstepB, voffB); PG8_STAGE(PG8_SA(0, 0), a2, voffA);
;             PG8_WAIT_V(8); PG8_WAIT_L(0); PG8_BAR; PG8_MMA(1, 0, At, B0); PG8_MMA(1, 1, At, B1); PG8_BAR; PG8_SCHED;
;             PG8_LDB(B0, 1, 0); PG8_LDB(B1, 1, 1); PG8_SCHED; PG8_LDA(At, 1, 0); PG8_STAGE(PG8_SA(0, 1), a2 + hstepA, voffA);
;             PG8_WAIT_V(8); PG8_WAIT_L(0); PG8_BAR; PG8_MMA(0, 0, At, B0); PG8_MMA(0, 1, At, B1); PG8_BAR; PG8_SCHED;
;             PG8_LDA(At, 1, 1); PG8_STAGE(PG8_SB(1, 0), b3, voffB); PG8_STAGE(PG8_SB(1, 1), b3 + hstepB, voffB); PG8_STAGE(PG8_SA(1, 0), a3, voffA);
;             PG8_WAIT_V(8); PG8_WAIT_L(0); PG8_BAR; PG8_MMA(1, 0, At, B0); PG8_MMA(1, 1, At, B1); PG8_BAR; PG8_SCHED;
;         }
;         if (wr == 0) PG8_BAR;
	s_add_i32 s14, s82, s56
	v_lshl_add_u64 v[148:149], v[148:149], 0, s[90:91]
	s_mov_b32 m0, s14
	ds_read_b128 v[186:189], v156 offset:49152
	ds_read_b128 v[190:193], v156 offset:50176
	ds_read_b128 v[204:207], v156 offset:51200
	ds_read_b128 v[208:211], v156 offset:52224
	ds_read_b128 v[212:215], v156 offset:53248
	ds_read_b128 v[216:219], v156 offset:54272
	ds_read_b128 v[220:223], v156 offset:55296
	ds_read_b128 v[230:233], v156 offset:56320
	global_load_lds_dwordx4 v[148:149], off
	s_add_i32 m0, s14, 0x2000
	s_add_u32 s14, s70, 0x80080
	v_lshl_add_u64 v[148:149], v[194:195], 0, s[90:91]
	s_addc_u32 s15, s71, 0
	s_add_i32 s70, s83, s56
	global_load_lds_dwordx4 v[148:149], off
	v_lshl_add_u64 v[148:149], s[14:15], 0, v[0:1]
	s_mov_b32 m0, s70
	s_nop 0
	global_load_lds_dwordx4 v[148:149], off
	v_lshl_add_u64 v[148:149], s[14:15], 0, v[134:135]
	s_add_i32 m0, s70, 0x2000
	s_nop 0
	global_load_lds_dwordx4 v[148:149], off
	v_lshl_add_u64 v[148:149], v[196:197], 0, s[90:91]
	s_mov_b32 m0, s77
	s_nop 0
	global_load_lds_dwordx4 v[148:149], off
	v_lshl_add_u64 v[148:149], v[198:199], 0, s[90:91]
	s_mov_b32 m0, s78
	s_nop 0
	global_load_lds_dwordx4 v[148:149], off
	s_waitcnt vmcnt(8)
	s_waitcnt lgkmcnt(0)
	s_barrier
	s_setprio 1
	v_mfma_f32_16x16x32_bf16 v[62:65], v[144:147], v[186:189], v[62:65]
	v_mfma_f32_16x16x32_bf16 v[58:61], v[162:165], v[186:189], v[58:61]
	v_mfma_f32_16x16x32_bf16 v[46:49], v[144:147], v[204:207], v[46:49]
	v_mfma_f32_16x16x32_bf16 v[42:45], v[162:165], v[204:207], v[42:45]
	v_mfma_f32_16x16x32_bf16 v[30:33], v[144:147], v[212:215], v[30:33]
	v_mfma_f32_16x16x32_bf16 v[26:29], v[162:165], v[212:215], v[26:29]
	v_mfma_f32_16x16x32_bf16 v[14:17], v[144:147], v[220:223], v[14:17]
	v_mfma_f32_16x16x32_bf16 v[10:13], v[162:165], v[220:223], v[10:13]
	v_mfma_f32_16x16x32_bf16 v[62:65], v[158:161], v[190:193], v[62:65]
	v_mfma_f32_16x16x32_bf16 v[58:61], v[166:169], v[190:193], v[58:61]
	v_mfma_f32_16x16x32_bf16 v[46:49], v[158:161], v[208:211], v[46:49]
	v_mfma_f32_16x16x32_bf16 v[42:45], v[166:169], v[208:211], v[42:45]
	v_mfma_f32_16x16x32_bf16 v[30:33], v[158:161], v[216:219], v[30:33]
	v_mfma_f32_16x16x32_bf16 v[26:29], v[166:169], v[216:219], v[26:29]
	v_mfma_f32_16x16x32_bf16 v[14:17], v[158:161], v[230:233], v[14:17]
	v_mfma_f32_16x16x32_bf16 v[10:13], v[166:169], v[230:233], v[10:13]
	v_mfma_f32_16x16x32_bf16 v[54:57], v[170:173], v[186:189], v[54:57]
	v_mfma_f32_16x16x32_bf16 v[50:53], v[178:181], v[186:189], v[50:53]
	v_mfma_f32_16x16x32_bf16 v[38:41], v[170:173], v[204:207], v[38:41]
	v_mfma_f32_16x16x32_bf16 v[34:37], v[178:181], v[204:207], v[34:37]
	v_mfma_f32_16x16x32_bf16 v[22:25], v[170:173], v[212:215], v[22:25]
	v_mfma_f32_16x16x32_bf16 v[18:21], v[178:181], v[212:215], v[18:21]
	v_mfma_f32_16x16x32_bf16 v[6:9], v[170:173], v[220:223], v[6:9]
	v_mfma_f32_16x16x32_bf16 v[2:5], v[178:181], v[220:223], v[2:5]
	v_mfma_f32_16x16x32_bf16 v[54:57], v[174:177], v[190:193], v[54:57]
	v_mfma_f32_16x16x32_bf16 v[50:53], v[182:185], v[190:193], v[50:53]
	v_mfma_f32_16x16x32_bf16 v[38:41], v[174:177], v[208:211], v[38:41]
	v_mfma_f32_16x16x32_bf16 v[34:37], v[182:185], v[208:211], v[34:37]
	v_mfma_f32_16x16x32_bf16 v[22:25], v[174:177], v[216:219], v[22:25]
	v_mfma_f32_16x16x32_bf16 v[18:21], v[182:185], v[216:219], v[18:21]
	v_mfma_f32_16x16x32_bf16 v[6:9], v[174:177], v[230:233], v[6:9]
	v_mfma_f32_16x16x32_bf16 v[2:5], v[182:185], v[230:233], v[2:5]
	s_setprio 0
	s_barrier
	s_add_i32 s81, s81, 2
	s_add_u32 s79, s79, 0x100
	s_addc_u32 s80, s80, 0
	s_add_u32 s44, s44, 0x100
	s_addc_u32 s45, s45, 0
	s_cmp_gt_u32 s81, 29
	s_cbranch_scc0 .LBB1_574
	s_and_b64 vcc, exec, s[36:37]
	s_cbranch_vccz .LBB1_577
	s_barrier

; #define PG8_STAGE(bufoff, gbase, voff) do { _Pragma("unroll") for (int _i = 0; _i < 2; ++_i) \
;         __builtin_amdgcn_global_load_lds((const unsigned*)((const char*)(gbase) + (voff)[_i]), (LAS unsigned*)(lds + (bufoff) + ldsw + _i * 8192), 16, 0, 0); } while (0)
; #define PG8_LDA(dst, b, h) do { _Pragma("unroll") for (int m = 0; m < 4; ++m) _Pragma("unroll") for (int k = 0; k < 2; ++k) dst[m][k] = *(const LAS bf16x8*)(lds + PG8_SA(b, h) + aoff + m * 2048 + k * 1024); } while (0)
; #define PG8_LDB(dst, b, h) do { _Pragma("unroll") for (int n = 0; n < 2; ++n) _Pragma("unroll") for (int k = 0; k < 2; ++k) dst[n][k] = *(const LAS bf16x8*)(lds + PG8_SB(b, h) + boff + n * 2048 + k * 1024); } while (0)
; #define PG8_WAIT_V(n) asm volatile("s_waitcnt vmcnt(" #n ")" ::: "memory")
; #define PG8_BAR __builtin_amdgcn_s_barrier()
; template <class Epi, class Sched>
; __device__ __forceinline__ void gemm_phase(LAS unsigned char* lds, const Gemm g, const Sched& S, const Epi& E, const int tid) {
;     ...
;         for (int t = 0; t < nt; t += 2) {
;             const bool last = (t == nt - 2);
;             const char* a1 = cA + (size_t)(t + 1) * kstep;
;             const char* a2 = last ? nA : cA + (size_t)(t + 2) * kstep; const char* b2 = last ? nB : cB + (size_t)(t + 2) * kstep;
;             const char* a3 = a2 + kstep; const char* b3 = b2 + kstep;
;             PG8_LDB(B0, 0, 0); PG8_LDB(B1, 0, 1); PG8_SCHED; PG8_LDA(At, 0, 0); PG8_STAGE(PG8_SA(1, 1), a1 + hstepA, voffA);
;             PG8_WAIT_V(8); PG8_WAIT_L(0); PG8_BAR; PG8_MMA(0, 0, At, B0); PG8_MMA(0, 1, At, B1); PG8_BAR; PG8_SCHED;
;             PG8_LDA(At, 0, 1); PG8_STAGE(PG8_SB(0, 0), b2, voffB); PG8_STAGE(PG8_SB(0, 1), b2 + hstepB, voffB); PG8_STAGE(PG8_SA(0, 0), a2, voffA);
;             PG8_WAIT_V(8); PG8_WAIT_L(0); PG8_BAR; PG8_MMA(1, 0, At, B0); PG8_MMA(1, 1, At, B1); PG8_BAR; PG8_SCHED;
;             PG8_LDB(B0, 1, 0); PG8_LDB(B1, 1, 1); PG8_SCHED; PG8_LDA(At, 1, 0); PG8_STAGE(PG8_SA(0, 1), a2 + hstepA, voffA);
;             PG8_WAIT_V(8); PG8_WAIT_L(0); PG8_BAR; PG8_MMA(0, 0, At, B0); PG8_MMA(0, 1, At, B1); PG8_BAR; PG8_SCHED;
;             PG8_LDA(At, 1, 1); PG8_STAGE(PG8_SB(1, 0), b3, voffB); PG8_STAGE(PG8_SB(1, 1), b3 + hstepB, voffB); PG8_STAGE(PG8_SA(1, 0), a3, voffA);
;             PG8_WAIT_V(8); PG8_WAIT_L(0); PG8_BAR; PG8_MMA(1, 0, At, B0); PG8_MMA(1, 1, At, B1); PG8_BAR; PG8_SCHED;
.LBB1_724:
	s_add_u32 s14, s48, 0xfff80080
	s_addc_u32 s15, s49, -1
	s_add_i32 s72, 0, 0x10000
	s_cmp_eq_u32 s71, 28
	s_cselect_b32 s57, s37, s15
	s_cselect_b32 s56, s41, s14
	v_add_u32_e32 v144, s72, v147
	s_cselect_b32 s53, s27, s70
	s_cselect_b32 s52, s68, s69
	s_add_i32 s73, 0, 0x14000
	ds_read_b128 v[140:143], v144
	ds_read_b128 v[158:161], v144 offset:1024
	ds_read_b128 v[162:165], v144 offset:2048
	ds_read_b128 v[166:169], v144 offset:3072
	v_add_u32_e32 v144, s73, v147
	ds_read_b128 v[170:173], v144
	ds_read_b128 v[174:177], v144 offset:1024
	ds_read_b128 v[178:181], v144 offset:2048
	ds_read_b128 v[182:185], v144 offset:3072
	v_lshl_add_u64 v[144:145], s[48:49], 0, v[138:139]
	s_add_i32 m0, s47, 0xc000
	ds_read_b128 v[186:189], v156
	ds_read_b128 v[190:193], v156 offset:1024
	ds_read_b128 v[204:207], v156 offset:2048
	ds_read_b128 v[208:211], v156 offset:3072
	ds_read_b128 v[212:215], v156 offset:4096
	ds_read_b128 v[216:219], v156 offset:5120
	ds_read_b128 v[220:223], v156 offset:6144
	ds_read_b128 v[230:233], v156 offset:7168
	global_load_lds_dwordx4 v[144:145], off
	v_lshl_add_u64 v[144:145], s[48:49], 0, v[136:137]
	s_add_i32 m0, s47, 0xe000
	s_nop 0
	global_load_lds_dwordx4 v[144:145], off
	s_waitcnt vmcnt(8)
	s_waitcnt lgkmcnt(0)
	s_barrier
	s_setprio 1
	v_mfma_f32_16x16x32_bf16 v[126:129], v[140:143], v[186:189], v[126:129]
	v_mfma_f32_16x16x32_bf16 v[122:125], v[162:165], v[186:189], v[122:125]
	v_mfma_f32_16x16x32_bf16 v[110:113], v[140:143], v[204:207], v[110:113]
	v_mfma_f32_16x16x32_bf16 v[106:109], v[162:165], v[204:207], v[106:109]
	v_mfma_f32_16x16x32_bf16 v[94:97], v[140:143], v[212:215], v[94:97]
	v_mfma_f32_16x16x32_bf16 v[90:93], v[162:165], v[212:215], v[90:93]
	v_mfma_f32_16x16x32_bf16 v[78:81], v[140:143], v[220:223], v[78:81]
	v_mfma_f32_16x16x32_bf16 v[74:77], v[162:165], v[220:223], v[74:77]
	v_mfma_f32_16x16x32_bf16 v[126:129], v[158:161], v[190:193], v[126:129]
	v_mfma_f32_16x16x32_bf16 v[122:125], v[166:169], v[190:193], v[122:125]
	v_mfma_f32_16x16x32_bf16 v[110:113], v[158:161], v[208:211], v[110:113]
	v_mfma_f32_16x16x32_bf16 v[106:109], v[166:169], v[208:211], v[106:109]
	v_mfma_f32_16x16x32_bf16 v[94:97], v[158:161], v[216:219], v[94:97]
	v_mfma_f32_16x16x32_bf16 v[90:93], v[166:169], v[216:219], v[90:93]
	v_mfma_f32_16x16x32_bf16 v[78:81], v[158:161], v[230:233], v[78:81]
	v_mfma_f32_16x16x32_bf16 v[74:77], v[166:169], v[230:233], v[74:77]
	v_mfma_f32_16x16x32_bf16 v[118:121], v[170:173], v[186:189], v[118:121]
	v_mfma_f32_16x16x32_bf16 v[114:117], v[178:181], v[186:189], v[114:117]
	v_mfma_f32_16x16x32_bf16 v[102:105], v[170:173], v[204:207], v[102:105]
	v_mfma_f32_16x16x32_bf16 v[98:101], v[178:181], v[204:207], v[98:101]
	v_mfma_f32_16x16x32_bf16 v[86:89], v[170:173], v[212:215], v[86:89]
	v_mfma_f32_16x16x32_bf16 v[82:85], v[178:181], v[212:215], v[82:85]
	v_mfma_f32_16x16x32_bf16 v[70:73], v[170:173], v[220:223], v[70:73]
	v_mfma_f32_16x16x32_bf16 v[66:69], v[178:181], v[220:223], v[66:69]
	v_mfma_f32_16x16x32_bf16 v[118:121], v[174:177], v[190:193], v[118:121]
	v_mfma_f32_16x16x32_bf16 v[114:117], v[182:185], v[190:193], v[114:117]
	v_mfma_f32_16x16x32_bf16 v[102:105], v[174:177], v[208:211], v[102:105]
	v_mfma_f32_16x16x32_bf16 v[98:101], v[182:185], v[208:211], v[98:101]
	v_mfma_f32_16x16x32_bf16 v[86:89], v[174:177], v[216:219], v[86:89]
	v_mfma_f32_16x16x32_bf16 v[82:85], v[182:185], v[216:219], v[82:85]
	v_mfma_f32_16x16x32_bf16 v[70:73], v[174:177], v[230:233], v[70:73]
	v_mfma_f32_16x16x32_bf16 v[66:69], v[182:185], v[230:233], v[66:69]
	s_setprio 0
	s_barrier
	s_add_i32 s14, s72, s62
	v_lshl_add_u64 v[144:145], s[52:53], 0, v[0:1]
	s_mov_b32 m0, s14
	ds_read_b128 v[186:189], v156 offset:16384
	ds_read_b128 v[190:193], v156 offset:17408
	ds_read_b128 v[204:207], v156 offset:18432
	ds_read_b128 v[208:211], v156 offset:19456
	ds_read_b128 v[212:215], v156 offset:20480
	ds_read_b128 v[216:219], v156 offset:21504
	ds_read_b128 v[220:223], v156 offset:22528
	ds_read_b128 v[230:233], v156 offset:23552
	global_load_lds_dwordx4 v[144:145], off
	s_add_i32 m0, s14, 0x2000
	s_add_u32 s14, s52, 0x80000
	v_lshl_add_u64 v[194:195], s[52:53], 0, v[134:135]
	s_addc_u32 s15, s53, 0
	s_add_i32 s72, s73, s62
	global_load_lds_dwordx4 v[194:195], off
	v_lshl_add_u64 v[196:197], s[14:15], 0, v[0:1]
	s_mov_b32 m0, s72
	v_lshl_add_u64 v[198:199], s[56:57], 0, v[132:133]
	global_load_lds_dwordx4 v[196:197], off
	v_lshl_add_u64 v[196:197], s[14:15], 0, v[134:135]
	s_add_i32 m0, s72, 0x2000
	s_nop 0
	global_load_lds_dwordx4 v[196:197], off
	v_lshl_add_u64 v[196:197], s[56:57], 0, v[130:131]
	s_mov_b32 m0, s47
	s_nop 0
	global_load_lds_dwordx4 v[196:197], off
	s_mov_b32 m0, s63
	s_nop 0
	global_load_lds_dwordx4 v[198:199], off
	s_waitcnt vmcnt(8)
	s_waitcnt lgkmcnt(0)
	s_barrier
; #define PG8_STAGE(bufoff, gbase, voff) do { _Pragma("unroll") for (int _i = 0; _i < 2; ++_i) \
;         __builtin_amdgcn_global_load_lds((const unsigned*)((const char*)(gbase) + (voff)[_i]), (LAS unsigned*)(lds + (bufoff) + ldsw + _i * 8192), 16, 0, 0); } while (0)
; #define PG8_LDA(dst, b, h) do { _Pragma("unroll") for (int m = 0; m < 4; ++m) _Pragma("unroll") for (int k = 0; k < 2; ++k) dst[m][k] = *(const LAS bf16x8*)(lds + PG8_SA(b, h) + aoff + m * 2048 + k * 1024); } while (0)
; #define PG8_LDB(dst, b, h) do { _Pragma("unroll") for (int n = 0; n < 2; ++n) _Pragma("unroll") for (int k = 0; k < 2; ++k) dst[n][k] = *(const LAS bf16x8*)(lds + PG8_SB(b, h) + boff + n * 2048 + k * 1024); } while (0)
; #define PG8_WAIT_V(n) asm volatile("s_waitcnt vmcnt(" #n ")" ::: "memory")
; #define PG8_BAR __builtin_amdgcn_s_barrier()
; template <class Epi, class Sched>
; __device__ __forceinline__ void gemm_phase(LAS unsigned char* lds, const Gemm g, const Sched& S, const Epi& E, const int tid) {
;     ...
;         for (int t = 0; t < nt; t += 2) {
;             const bool last = (t == nt - 2);
;             const char* a1 = cA + (size_t)(t + 1) * kstep;
;             const char* a2 = last ? nA : cA + (size_t)(t + 2) * kstep; const char* b2 = last ? nB : cB + (size_t)(t + 2) * kstep;
;             const char* a3 = a2 + kstep; const char* b3 = b2 + kstep;
;             PG8_LDB(B0, 0, 0); PG8_LDB(B1, 0, 1); PG8_SCHED; PG8_LDA(At, 0, 0); PG8_STAGE(PG8_SA(1, 1), a1 + hstepA, voffA);
;             PG8_WAIT_V(8); PG8_WAIT_L(0); PG8_BAR; PG8_MMA(0, 0, At, B0); PG8_MMA(0, 1, At, B1); PG8_BAR; PG8_SCHED;
;             PG8_LDA(At, 0, 1); PG8_STAGE(PG8_SB(0, 0), b2, voffB); PG8_STAGE(PG8_SB(0, 1), b2 + hstepB, voffB); PG8_STAGE(PG8_SA(0, 0), a2, voffA);
;             PG8_WAIT_V(8); PG8_WAIT_L(0); PG8_BAR; PG8_MMA(1, 0, At, B0); PG8_MMA(1, 1, At, B1); PG8_BAR; PG8_SCHED;
;             PG8_LDB(B0, 1, 0); PG8_LDB(B1, 1, 1); PG8_SCHED; PG8_LDA(At, 1, 0); PG8_STAGE(PG8_SA(0, 1), a2 + hstepA, voffA);
;             PG8_WAIT_V(8); PG8_WAIT_L(0); PG8_BAR; PG8_MMA(0, 0, At, B0); PG8_MMA(0, 1, At, B1); PG8_BAR; PG8_SCHED;
;             PG8_LDA(At, 1, 1); PG8_STAGE(PG8_SB(1, 0), b3, voffB); PG8_STAGE(PG8_SB(1, 1), b3 + hstepB, voffB); PG8_STAGE(PG8_SA(1, 0), a3, voffA);
;             PG8_WAIT_V(8); PG8_WAIT_L(0); PG8_BAR; PG8_MMA(1, 0, At, B0); PG8_MMA(1, 1, At, B1); PG8_BAR; PG8_SCHED;
	s_setprio 1
	v_mfma_f32_16x16x32_bf16 v[62:65], v[140:143], v[186:189], v[62:65]
	v_mfma_f32_16x16x32_bf16 v[58:61], v[162:165], v[186:189], v[58:61]
	v_mfma_f32_16x16x32_bf16 v[46:49], v[140:143], v[204:207], v[46:49]
	v_mfma_f32_16x16x32_bf16 v[42:45], v[162:165], v[204:207], v[42:45]
	v_mfma_f32_16x16x32_bf16 v[30:33], v[140:143], v[212:215], v[30:33]
	v_mfma_f32_16x16x32_bf16 v[26:29], v[162:165], v[212:215], v[26:29]
	v_mfma_f32_16x16x32_bf16 v[14:17], v[140:143], v[220:223], v[14:17]
	v_mfma_f32_16x16x32_bf16 v[10:13], v[162:165], v[220:223], v[10:13]
	v_mfma_f32_16x16x32_bf16 v[62:65], v[158:161], v[190:193], v[62:65]
	v_mfma_f32_16x16x32_bf16 v[58:61], v[166:169], v[190:193], v[58:61]
	v_mfma_f32_16x16x32_bf16 v[46:49], v[158:161], v[208:211], v[46:49]
	v_mfma_f32_16x16x32_bf16 v[42:45], v[166:169], v[208:211], v[42:45]
	v_mfma_f32_16x16x32_bf16 v[30:33], v[158:161], v[216:219], v[30:33]
	v_mfma_f32_16x16x32_bf16 v[26:29], v[166:169], v[216:219], v[26:29]
	v_mfma_f32_16x16x32_bf16 v[14:17], v[158:161], v[230:233], v[14:17]
	v_mfma_f32_16x16x32_bf16 v[10:13], v[166:169], v[230:233], v[10:13]
	v_mfma_f32_16x16x32_bf16 v[54:57], v[170:173], v[186:189], v[54:57]
	v_mfma_f32_16x16x32_bf16 v[50:53], v[178:181], v[186:189], v[50:53]
	v_mfma_f32_16x16x32_bf16 v[38:41], v[170:173], v[204:207], v[38:41]
	v_mfma_f32_16x16x32_bf16 v[34:37], v[178:181], v[204:207], v[34:37]
	v_mfma_f32_16x16x32_bf16 v[22:25], v[170:173], v[212:215], v[22:25]
	v_mfma_f32_16x16x32_bf16 v[18:21], v[178:181], v[212:215], v[18:21]
	v_mfma_f32_16x16x32_bf16 v[6:9], v[170:173], v[220:223], v[6:9]
	v_mfma_f32_16x16x32_bf16 v[2:5], v[178:181], v[220:223], v[2:5]
	v_mfma_f32_16x16x32_bf16 v[54:57], v[174:177], v[190:193], v[54:57]
	v_mfma_f32_16x16x32_bf16 v[50:53], v[182:185], v[190:193], v[50:53]
	v_mfma_f32_16x16x32_bf16 v[38:41], v[174:177], v[208:211], v[38:41]
	v_mfma_f32_16x16x32_bf16 v[34:37], v[182:185], v[208:211], v[34:37]
	v_mfma_f32_16x16x32_bf16 v[22:25], v[174:177], v[216:219], v[22:25]
	v_mfma_f32_16x16x32_bf16 v[18:21], v[182:185], v[216:219], v[18:21]
	v_mfma_f32_16x16x32_bf16 v[6:9], v[174:177], v[230:233], v[6:9]
	v_mfma_f32_16x16x32_bf16 v[2:5], v[182:185], v[230:233], v[2:5]
	s_setprio 0
	s_barrier
	s_add_i32 s72, 0, 0x18000
	v_add_u32_e32 v157, s72, v147
	s_add_i32 s73, 0, 0x1c000
	ds_read_b128 v[140:143], v157
	ds_read_b128 v[158:161], v157 offset:1024
	ds_read_b128 v[162:165], v157 offset:2048
	ds_read_b128 v[166:169], v157 offset:3072
	v_add_u32_e32 v157, s73, v147
	ds_read_b128 v[170:173], v157
	ds_read_b128 v[174:177], v157 offset:1024
	ds_read_b128 v[178:181], v157 offset:2048
	ds_read_b128 v[182:185], v157 offset:3072
	s_add_u32 s14, s56, 0x80000
	s_addc_u32 s15, s57, 0
	s_mov_b32 m0, s64
	v_lshl_add_u64 v[200:201], s[14:15], 0, v[130:131]
	ds_read_b128 v[186:189], v156 offset:32768
	ds_read_b128 v[190:193], v156 offset:33792
	ds_read_b128 v[204:207], v156 offset:34816
	ds_read_b128 v[208:211], v156 offset:35840
	ds_read_b128 v[212:215], v156 offset:36864
	ds_read_b128 v[216:219], v156 offset:37888
	ds_read_b128 v[220:223], v156 offset:38912
	ds_read_b128 v[230:233], v156 offset:39936
	global_load_lds_dwordx4 v[200:201], off
	v_lshl_add_u64 v[200:201], s[14:15], 0, v[132:133]
	s_mov_b32 m0, s65
	s_nop 0
	global_load_lds_dwordx4 v[200:201], off
	s_waitcnt vmcnt(8)
	s_waitcnt lgkmcnt(0)
	s_barrier
	s_setprio 1
	v_mfma_f32_16x16x32_bf16 v[126:129], v[140:143], v[186:189], v[126:129]
	v_mfma_f32_16x16x32_bf16 v[122:125], v[162:165], v[186:189], v[122:125]
	v_mfma_f32_16x16x32_bf16 v[110:113], v[140:143], v[204:207], v[110:113]
	v_mfma_f32_16x16x32_bf16 v[106:109], v[162:165], v[204:207], v[106:109]
	v_mfma_f32_16x16x32_bf16 v[94:97], v[140:143], v[212:215], v[94:97]
	v_mfma_f32_16x16x32_bf16 v[90:93], v[162:165], v[212:215], v[90:93]
	v_mfma_f32_16x16x32_bf16 v[78:81], v[140:143], v[220:223], v[78:81]
	v_mfma_f32_16x16x32_bf16 v[74:77], v[162:165], v[220:223], v[74:77]
	v_mfma_f32_16x16x32_bf16 v[126:129], v[158:161], v[190:193], v[126:129]
	v_mfma_f32_16x16x32_bf16 v[122:125], v[166:169], v[190:193], v[122:125]
	v_mfma_f32_16x16x32_bf16 v[110:113], v[158:161], v[208:211], v[110:113]
	v_mfma_f32_16x16x32_bf16 v[106:109], v[166:169], v[208:211], v[106:109]
	v_mfma_f32_16x16x32_bf16 v[94:97], v[158:161], v[216:219], v[94:97]
	v_mfma_f32_16x16x32_bf16 v[90:93], v[166:169], v[216:219], v[90:93]
	v_mfma_f32_16x16x32_bf16 v[78:81], v[158:161], v[230:233], v[78:81]
	v_mfma_f32_16x16x32_bf16 v[74:77], v[166:169], v[230:233], v[74:77]
	v_mfma_f32_16x16x32_bf16 v[118:121], v[170:173], v[186:189], v[118:121]
	v_mfma_f32_16x16x32_bf16 v[114:117], v[178:181], v[186:189], v[114:117]
	v_mfma_f32_16x16x32_bf16 v[102:105], v[170:173], v[204:207], v[102:105]
	v_mfma_f32_16x16x32_bf16 v[98:101], v[178:181], v[204:207], v[98:101]
	v_mfma_f32_16x16x32_bf16 v[86:89], v[170:173], v[212:215], v[86:89]
	v_mfma_f32_16x16x32_bf16 v[82:85], v[178:181], v[212:215], v[82:85]
	v_mfma_f32_16x16x32_bf16 v[70:73], v[170:173], v[220:223], v[70:73]
	v_mfma_f32_16x16x32_bf16 v[66:69], v[178:181], v[220:223], v[66:69]
	v_mfma_f32_16x16x32_bf16 v[118:121], v[174:177], v[190:193], v[118:121]
	v_mfma_f32_16x16x32_bf16 v[114:117], v[182:185], v[190:193], v[114:117]
	v_mfma_f32_16x16x32_bf16 v[102:105], v[174:177], v[208:211], v[102:105]
	v_mfma_f32_16x16x32_bf16 v[98:101], v[182:185], v[208:211], v[98:101]
	v_mfma_f32_16x16x32_bf16 v[86:89], v[174:177], v[216:219], v[86:89]
	v_mfma_f32_16x16x32_bf16 v[82:85], v[182:185], v[216:219], v[82:85]
	v_mfma_f32_16x16x32_bf16 v[70:73], v[174:177], v[230:233], v[70:73]
	v_mfma_f32_16x16x32_bf16 v[66:69], v[182:185], v[230:233], v[66:69]
	s_setprio 0
	s_barrier
; #define PG8_STAGE(bufoff, gbase, voff) do { _Pragma("unroll") for (int _i = 0; _i < 2; ++_i) \
;         __builtin_amdgcn_global_load_lds((const unsigned*)((const char*)(gbase) + (voff)[_i]), (LAS unsigned*)(lds + (bufoff) + ldsw + _i * 8192), 16, 0, 0); } while (0)
; #define PG8_LDA(dst, b, h) do { _Pragma("unroll") for (int m = 0; m < 4; ++m) _Pragma("unroll") for (int k = 0; k < 2; ++k) dst[m][k] = *(const LAS bf16x8*)(lds + PG8_SA(b, h) + aoff + m * 2048 + k * 1024); } while (0)
; #define PG8_LDB(dst, b, h) do { _Pragma("unroll") for (int n = 0; n < 2; ++n) _Pragma("unroll") for (int k = 0; k < 2; ++k) dst[n][k] = *(const LAS bf16x8*)(lds + PG8_SB(b, h) + boff + n * 2048 + k * 1024); } while (0)
; #define PG8_WAIT_V(n) asm volatile("s_waitcnt vmcnt(" #n ")" ::: "memory")
; template <class Epi, class Sched>
; __device__ __forceinline__ void gemm_phase(LAS unsigned char* lds, const Gemm g, const Sched& S, const Epi& E, const int tid) {
;     ...
;         for (int t = 0; t < nt; t += 2) {
;             const bool last = (t == nt - 2);
;             const char* a1 = cA + (size_t)(t + 1) * kstep;
;             const char* a2 = last ? nA : cA + (size_t)(t + 2) * kstep; const char* b2 = last ? nB : cB + (size_t)(t + 2) * kstep;
;             const char* a3 = a2 + kstep; const char* b3 = b2 + kstep;
;             PG8_LDB(B0, 0, 0); PG8_LDB(B1, 0, 1); PG8_SCHED; PG8_LDA(At, 0, 0); PG8_STAGE(PG8_SA(1, 1), a1 + hstepA, voffA);
;             PG8_WAIT_V(8); PG8_WAIT_L(0); PG8_BAR; PG8_MMA(0, 0, At, B0); PG8_MMA(0, 1, At, B1); PG8_BAR; PG8_SCHED;
;             PG8_LDA(At, 0, 1); PG8_STAGE(PG8_SB(0, 0), b2, voffB); PG8_STAGE(PG8_SB(0, 1), b2 + hstepB, voffB); PG8_STAGE(PG8_SA(0, 0), a2, voffA);
;             PG8_WAIT_V(8); PG8_WAIT_L(0); PG8_BAR; PG8_MMA(1, 0, At, B0); PG8_MMA(1, 1, At, B1); PG8_BAR; PG8_SCHED;
;             PG8_LDB(B0, 1, 0); PG8_LDB(B1, 1, 1); PG8_SCHED; PG8_LDA(At, 1, 0); PG8_STAGE(PG8_SA(0, 1), a2 + hstepA, voffA);
;             PG8_WAIT_V(8); PG8_WAIT_L(0); PG8_BAR; PG8_MMA(0, 0, At, B0); PG8_MMA(0, 1, At, B1); PG8_BAR; PG8_SCHED;
;             PG8_LDA(At, 1, 1); PG8_STAGE(PG8_SB(1, 0), b3, voffB); PG8_STAGE(PG8_SB(1, 1), b3 + hstepB, voffB); PG8_STAGE(PG8_SA(1, 0), a3, voffA);
;             PG8_WAIT_V(8); PG8_WAIT_L(0); PG8_BAR; PG8_MMA(1, 0, At, B0); PG8_MMA(1, 1, At, B1); PG8_BAR; PG8_SCHED;
;         }
;         if (wr == 0) PG8_BAR;
	s_add_i32 s14, s72, s62
	v_lshl_add_u64 v[144:145], v[144:145], 0, s[90:91]
	s_mov_b32 m0, s14
	ds_read_b128 v[186:189], v156 offset:49152
	ds_read_b128 v[190:193], v156 offset:50176
	ds_read_b128 v[204:207], v156 offset:51200
	ds_read_b128 v[208:211], v156 offset:52224
	ds_read_b128 v[212:215], v156 offset:53248
	ds_read_b128 v[216:219], v156 offset:54272
	ds_read_b128 v[220:223], v156 offset:55296
	ds_read_b128 v[230:233], v156 offset:56320
	global_load_lds_dwordx4 v[144:145], off
	s_add_i32 m0, s14, 0x2000
	s_add_u32 s14, s52, 0x80080
	v_lshl_add_u64 v[144:145], v[194:195], 0, s[90:91]
	s_addc_u32 s15, s53, 0
	s_add_i32 s52, s73, s62
	global_load_lds_dwordx4 v[144:145], off
	v_lshl_add_u64 v[144:145], s[14:15], 0, v[0:1]
	s_mov_b32 m0, s52
	s_nop 0
	global_load_lds_dwordx4 v[144:145], off
	v_lshl_add_u64 v[144:145], s[14:15], 0, v[134:135]
	s_add_i32 m0, s52, 0x2000
	s_nop 0
	global_load_lds_dwordx4 v[144:145], off
	v_lshl_add_u64 v[144:145], v[196:197], 0, s[90:91]
	s_mov_b32 m0, s66
	s_nop 0
	global_load_lds_dwordx4 v[144:145], off
	v_lshl_add_u64 v[144:145], v[198:199], 0, s[90:91]
	s_mov_b32 m0, s67
	s_nop 0
	global_load_lds_dwordx4 v[144:145], off
	s_waitcnt vmcnt(8)
	s_waitcnt lgkmcnt(0)
	s_barrier
	s_setprio 1
	v_mfma_f32_16x16x32_bf16 v[62:65], v[140:143], v[186:189], v[62:65]
	v_mfma_f32_16x16x32_bf16 v[58:61], v[162:165], v[186:189], v[58:61]
	v_mfma_f32_16x16x32_bf16 v[46:49], v[140:143], v[204:207], v[46:49]
	v_mfma_f32_16x16x32_bf16 v[42:45], v[162:165], v[204:207], v[42:45]
	v_mfma_f32_16x16x32_bf16 v[30:33], v[140:143], v[212:215], v[30:33]
	v_mfma_f32_16x16x32_bf16 v[26:29], v[162:165], v[212:215], v[26:29]
	v_mfma_f32_16x16x32_bf16 v[14:17], v[140:143], v[220:223], v[14:17]
	v_mfma_f32_16x16x32_bf16 v[10:13], v[162:165], v[220:223], v[10:13]
	v_mfma_f32_16x16x32_bf16 v[62:65], v[158:161], v[190:193], v[62:65]
	v_mfma_f32_16x16x32_bf16 v[58:61], v[166:169], v[190:193], v[58:61]
	v_mfma_f32_16x16x32_bf16 v[46:49], v[158:161], v[208:211], v[46:49]
	v_mfma_f32_16x16x32_bf16 v[42:45], v[166:169], v[208:211], v[42:45]
	v_mfma_f32_16x16x32_bf16 v[30:33], v[158:161], v[216:219], v[30:33]
	v_mfma_f32_16x16x32_bf16 v[26:29], v[166:169], v[216:219], v[26:29]
	v_mfma_f32_16x16x32_bf16 v[14:17], v[158:161], v[230:233], v[14:17]
	v_mfma_f32_16x16x32_bf16 v[10:13], v[166:169], v[230:233], v[10:13]
	v_mfma_f32_16x16x32_bf16 v[54:57], v[170:173], v[186:189], v[54:57]
	v_mfma_f32_16x16x32_bf16 v[50:53], v[178:181], v[186:189], v[50:53]
	v_mfma_f32_16x16x32_bf16 v[38:41], v[170:173], v[204:207], v[38:41]
	v_mfma_f32_16x16x32_bf16 v[34:37], v[178:181], v[204:207], v[34:37]
	v_mfma_f32_16x16x32_bf16 v[22:25], v[170:173], v[212:215], v[22:25]
	v_mfma_f32_16x16x32_bf16 v[18:21], v[178:181], v[212:215], v[18:21]
	v_mfma_f32_16x16x32_bf16 v[6:9], v[170:173], v[220:223], v[6:9]
	v_mfma_f32_16x16x32_bf16 v[2:5], v[178:181], v[220:223], v[2:5]
	v_mfma_f32_16x16x32_bf16 v[54:57], v[174:177], v[190:193], v[54:57]
	v_mfma_f32_16x16x32_bf16 v[50:53], v[182:185], v[190:193], v[50:53]
	v_mfma_f32_16x16x32_bf16 v[38:41], v[174:177], v[208:211], v[38:41]
	v_mfma_f32_16x16x32_bf16 v[34:37], v[182:185], v[208:211], v[34:37]
	v_mfma_f32_16x16x32_bf16 v[22:25], v[174:177], v[216:219], v[22:25]
	v_mfma_f32_16x16x32_bf16 v[18:21], v[182:185], v[216:219], v[18:21]
	v_mfma_f32_16x16x32_bf16 v[6:9], v[174:177], v[230:233], v[6:9]
	v_mfma_f32_16x16x32_bf16 v[2:5], v[182:185], v[230:233], v[2:5]
	s_setprio 0
	s_barrier
	s_add_i32 s71, s71, 2
	s_add_u32 s69, s69, 0x100
	s_addc_u32 s70, s70, 0
	s_add_u32 s48, s48, 0x100
	s_addc_u32 s49, s49, 0
	s_cmp_gt_u32 s71, 29
	s_cbranch_scc0 .LBB1_724
	s_and_b64 vcc, exec, s[6:7]
	s_cbranch_vccz .LBB1_727
	s_barrier

; __global__ void __launch_bounds__(512, 2) mega(Args args) {
;     ...
;         if (ph + 1 < args.hi) { if (!(args.flags & FL_XCDBAR) || ph == args.lo) grid.sync(); else xcd_barrier(xbar); }
;     }
.Lpost_getpc0:
	s_add_u32 s98, s98, (.LBB1_9-.Lpost_getpc0)&4294967295
	s_addc_u32 s99, s99, (.LBB1_9-.Lpost_getpc0)>>32
	s_setpc_b64 s[98:99]
	s_nop 0
	s_nop 0
	s_nop 0
	s_nop 0
	s_nop 0
	s_nop 0
	s_nop 0
	s_nop 0
	s_nop 0
	s_nop 0
	s_nop 0
	s_nop 0
	s_nop 0
	s_nop 0
	s_nop 0
	s_nop 0
	s_nop 0
	s_nop 0
	s_nop 0
	s_nop 0
	s_nop 0
	s_nop 0
	s_nop 0
	s_nop 0
	s_nop 0
	s_nop 0
	s_nop 0
	s_nop 0
	s_nop 0
	s_nop 0
	s_nop 0
	s_nop 0
	s_nop 0
	s_nop 0
	s_nop 0
	s_nop 0
	s_nop 0
	s_nop 0
	s_nop 0
	s_nop 0
	s_nop 0
	s_nop 0
	s_nop 0
	s_nop 0
	s_nop 0
	s_nop 0
	s_nop 0
	s_nop 0
